# fused RMS-norm+residual epilogue: hoist the 8 second-half residual loads (4 before the exchange, 4 after first row block), counted waits
# baseline (speedup 1.0000x reference)
.LBB0_166:
	s_or_b64 exec, exec, s[8:9]
	s_lshl_b32 s8, s12, 8
	s_lshl_b32 s9, s11, 5
	s_add_i32 s9, s9, s8
	s_lshl_b32 s76, s10, 8
	s_lshl_b32 s77, s13, 6
	v_lshl_add_u32 v144, v206, 3, s9
	s_add_i32 s8, s77, s76
	v_ashrrev_i32_e32 v145, 31, v144
	v_add_u32_e32 v146, s8, v231
	s_waitcnt vmcnt(0)
	v_lshl_add_u64 v[108:109], v[144:145], 2, v[104:105]
	v_lshl_add_u64 v[144:145], v[144:145], 1, v[202:203]
	v_ashrrev_i32_e32 v147, 31, v146
	v_lshl_add_u64 v[204:205], v[144:145], 0, s[30:31]
	v_lshlrev_b64 v[144:145], 11, v[146:147]
	s_waitcnt lgkmcnt(0)
	s_barrier
	v_lshl_add_u64 v[144:145], v[204:205], 0, v[144:145]
	global_load_dwordx4 v[120:123], v[108:109], off offset:16
	global_load_dwordx4 v[124:127], v[108:109], off
	s_waitcnt lgkmcnt(0)
	global_load_dwordx4 v[104:107], v[108:109], off offset:528
	s_nop 0
	global_load_dwordx4 v[108:111], v[108:109], off offset:512
	s_nop 0
	global_load_dwordx4 v[172:175], v[144:145], off
	global_load_dwordx4 v[168:171], v[144:145], off offset:256
	v_add_u32_e32 v144, 16, v146
	v_ashrrev_i32_e32 v145, 31, v144
	v_lshlrev_b64 v[144:145], 11, v[144:145]
	v_lshl_add_u64 v[144:145], v[204:205], 0, v[144:145]
	global_load_dwordx4 v[164:167], v[144:145], off
	global_load_dwordx4 v[160:163], v[144:145], off offset:256
	v_add_u32_e32 v144, 32, v146
	v_ashrrev_i32_e32 v145, 31, v144
	v_lshlrev_b64 v[144:145], 11, v[144:145]
	v_lshl_add_u64 v[144:145], v[204:205], 0, v[144:145]
	global_load_dwordx4 v[156:159], v[144:145], off
	global_load_dwordx4 v[152:155], v[144:145], off offset:256
	v_add_u32_e32 v144, 0x80, v146
	v_ashrrev_i32_e32 v145, 31, v144
	v_lshlrev_b64 v[144:145], 11, v[144:145]
	v_lshl_add_u64 v[144:145], v[204:205], 0, v[144:145]
	global_load_dwordx4 v[236:239], v[144:145], off
	global_load_dwordx4 v[240:243], v[144:145], off offset:256
	v_add_u32_e32 v144, 0x90, v146
	v_ashrrev_i32_e32 v145, 31, v144
	v_lshlrev_b64 v[144:145], 11, v[144:145]
	v_lshl_add_u64 v[144:145], v[204:205], 0, v[144:145]
	global_load_dwordx4 v[244:247], v[144:145], off
	global_load_dwordx4 v[248:251], v[144:145], off offset:256
	v_add_u32_e32 v144, 48, v146
	v_ashrrev_i32_e32 v145, 31, v144
	v_lshlrev_b64 v[144:145], 11, v[144:145]
	v_lshl_add_u64 v[144:145], v[204:205], 0, v[144:145]
	global_load_dwordx4 v[148:151], v[144:145], off
	s_nop 0
	global_load_dwordx4 v[144:147], v[144:145], off offset:256
	s_lshl_b32 s8, s13, 2
	v_lshl_add_u32 v206, v206, 4, v231
	s_add_i32 s10, s8, s11
	v_cmp_gt_i32_e64 s[8:9], 32, v206
	v_lshl_add_u32 v230, s10, 5, v206
	s_and_saveexec_b64 s[36:37], s[8:9]
	s_cbranch_execz .LBB0_181
	v_lshl_add_u32 v206, v230, 4, v226
	ds_read_b128 v[208:211], v206
	v_add_u32_e32 v206, s76, v230
	v_ashrrev_i32_e32 v207, 31, v206
	v_lshlrev_b64 v[206:207], 5, v[206:207]
	v_lshl_add_u64 v[206:207], v[202:203], 0, v[206:207]
	s_waitcnt lgkmcnt(0)
	v_mov_b32_e32 v214, v209
	v_mov_b32_e32 v215, v210
	v_mov_b32_e32 v209, v211
	v_pk_add_f32 v[208:209], v[214:215], v[208:209]
	v_lshl_add_u64 v[206:207], v[206:207], 0, s[34:35]
	s_ashr_i32 s13, s12, 31
	v_pk_add_f32 v[208:209], v[208:209], v[208:209] op_sel:[0,1] op_sel_hi:[1,0]
	v_lshl_add_u64 v[212:213], s[12:13], 3, v[206:207]
	v_mov_b32_e32 v209, v216
	s_mov_b32 s13, 0x100000
	s_mov_b64 s[38:39], 0
	global_store_dwordx2 v[212:213], v[208:209], off sc1
	s_branch .LBB0_173

.LBB0_181:
	s_or_b64 exec, exec, s[36:37]
	v_add_u32_e32 v207, s77, v231
	s_waitcnt vmcnt(0) lgkmcnt(0)
	s_barrier
	v_lshl_add_u32 v206, v207, 2, v227
	ds_read_b32 v210, v206
	v_lshlrev_b32_e32 v212, 16, v172
	v_and_b32_e32 v213, 0xffff0000, v172
	v_lshlrev_b32_e32 v172, 16, v173
	v_and_b32_e32 v173, 0xffff0000, v173
	s_waitcnt lgkmcnt(0)
	v_pk_mul_f32 v[142:143], v[142:143], v[210:211] op_sel_hi:[1,0]
	v_pk_mul_f32 v[140:141], v[140:141], v[210:211] op_sel_hi:[1,0]
	v_lshlrev_b32_e32 v214, 16, v174
	v_and_b32_e32 v215, 0xffff0000, v174
	v_lshlrev_b32_e32 v174, 16, v175
	v_and_b32_e32 v175, 0xffff0000, v175
	v_pk_fma_f32 v[142:143], v[126:127], v[142:143], v[172:173]
	v_pk_fma_f32 v[140:141], v[124:125], v[140:141], v[212:213]
	v_pk_mul_f32 v[138:139], v[138:139], v[210:211] op_sel_hi:[1,0]
	v_pk_mul_f32 v[136:137], v[136:137], v[210:211] op_sel_hi:[1,0]
	v_pk_fma_f32 v[172:173], v[122:123], v[138:139], v[174:175]
	v_pk_fma_f32 v[138:139], v[120:121], v[136:137], v[214:215]
	v_mul_f32_e32 v136, v141, v141
	v_mul_f32_e32 v137, v143, v143
	v_fmac_f32_e32 v136, v140, v140
	v_fmac_f32_e32 v137, v142, v142
	v_add_f32_e32 v136, v136, v137
	v_mul_f32_e32 v137, v139, v139
	v_mul_f32_e32 v174, v173, v173
	v_fmac_f32_e32 v137, v138, v138
	v_fmac_f32_e32 v174, v172, v172
	v_add_f32_e32 v137, v137, v174
	v_add_f32_e32 v174, v136, v137
	v_cvt_pk_bf16_f32 v136, v140, v141
	v_cvt_pk_bf16_f32 v137, v142, v143
	v_lshlrev_b32_e32 v140, 16, v168
	v_and_b32_e32 v141, 0xffff0000, v168
	v_lshlrev_b32_e32 v142, 16, v169
	v_and_b32_e32 v143, 0xffff0000, v169
	v_pk_mul_f32 v[134:135], v[134:135], v[210:211] op_sel_hi:[1,0]
	v_pk_mul_f32 v[132:133], v[132:133], v[210:211] op_sel_hi:[1,0]
	v_lshlrev_b32_e32 v168, 16, v170
	v_and_b32_e32 v169, 0xffff0000, v170
	v_pk_fma_f32 v[134:135], v[110:111], v[134:135], v[142:143]
	v_pk_fma_f32 v[132:133], v[108:109], v[132:133], v[140:141]
	v_pk_mul_f32 v[128:129], v[128:129], v[210:211] op_sel_hi:[1,0]
	v_lshlrev_b32_e32 v170, 16, v171
	v_and_b32_e32 v171, 0xffff0000, v171
	v_pk_mul_f32 v[130:131], v[130:131], v[210:211] op_sel_hi:[1,0]
	v_pk_fma_f32 v[142:143], v[104:105], v[128:129], v[168:169]
	v_mul_f32_e32 v128, v133, v133
	v_mul_f32_e32 v129, v135, v135
	v_pk_fma_f32 v[140:141], v[106:107], v[130:131], v[170:171]
	v_fmac_f32_e32 v128, v132, v132
	v_fmac_f32_e32 v129, v134, v134
	v_add_f32_e32 v128, v128, v129
	v_mul_f32_e32 v129, v143, v143
	v_mul_f32_e32 v130, v141, v141
	v_fmac_f32_e32 v129, v142, v142
	v_fmac_f32_e32 v130, v140, v140
	v_add_f32_e32 v129, v129, v130
	v_add_f32_e32 v128, v128, v129
	v_add_f32_e32 v128, v174, v128
	ds_bpermute_b32 v129, v228, v128
	v_add_u32_e32 v208, s76, v207
	v_ashrrev_i32_e32 v209, 31, v208
	v_lshlrev_b64 v[208:209], 11, v[208:209]
	v_lshl_add_u64 v[208:209], v[204:205], 0, v[208:209]
	s_waitcnt lgkmcnt(0)
	v_add_f32_e32 v128, v128, v129
	ds_bpermute_b32 v129, v229, v128
	v_cvt_pk_bf16_f32 v138, v138, v139
	v_cvt_pk_bf16_f32 v139, v172, v173
	global_store_dwordx4 v[208:209], v[136:139], off
	v_cvt_pk_bf16_f32 v130, v132, v133
	v_cvt_pk_bf16_f32 v131, v134, v135
	v_cvt_pk_bf16_f32 v132, v142, v143
	v_cvt_pk_bf16_f32 v133, v140, v141
	global_store_dwordx4 v[208:209], v[130:133], off offset:256
	s_and_saveexec_b64 s[10:11], vcc
	s_cbranch_execz .LBB0_183
	s_waitcnt lgkmcnt(0)
	v_add_f32_e32 v128, v128, v129
	v_lshl_add_u32 v129, v207, 4, s75
	ds_write_b32 v129, v128
.LBB0_183:
	s_or_b64 exec, exec, s[10:11]
	v_add_u32_e32 v252, 0xa0, v207
	v_add_u32_e32 v252, s76, v252
	v_ashrrev_i32_e32 v253, 31, v252
	v_lshlrev_b64 v[252:253], 11, v[252:253]
	v_lshl_add_u64 v[252:253], v[204:205], 0, v[252:253]
	global_load_dwordx4 v[168:171], v[252:253], off
	global_load_dwordx4 v[172:175], v[252:253], off offset:256
	v_add_u32_e32 v252, 0xb0, v207
	v_add_u32_e32 v252, s76, v252
	v_ashrrev_i32_e32 v253, 31, v252
	v_lshlrev_b64 v[252:253], 11, v[252:253]
	v_lshl_add_u64 v[252:253], v[204:205], 0, v[252:253]
	global_load_dwordx4 v[208:211], v[252:253], off
	global_load_dwordx4 v[212:215], v[252:253], off offset:256
	ds_read_b32 v132, v206 offset:64
	v_lshlrev_b32_e32 v134, 16, v164
	v_and_b32_e32 v135, 0xffff0000, v164
	v_lshlrev_b32_e32 v136, 16, v165
	v_and_b32_e32 v137, 0xffff0000, v165
	s_waitcnt lgkmcnt(0)
	v_pk_mul_f32 v[118:119], v[118:119], v[132:133] op_sel_hi:[1,0]
	v_pk_mul_f32 v[116:117], v[116:117], v[132:133] op_sel_hi:[1,0]
	v_lshlrev_b32_e32 v138, 16, v166
	v_and_b32_e32 v139, 0xffff0000, v166
	v_lshlrev_b32_e32 v140, 16, v167
	v_and_b32_e32 v141, 0xffff0000, v167
	v_pk_fma_f32 v[118:119], v[126:127], v[118:119], v[136:137]
	v_pk_fma_f32 v[116:117], v[124:125], v[116:117], v[134:135]
	v_pk_mul_f32 v[114:115], v[114:115], v[132:133] op_sel_hi:[1,0]
	v_pk_mul_f32 v[112:113], v[112:113], v[132:133] op_sel_hi:[1,0]
	v_pk_fma_f32 v[134:135], v[122:123], v[114:115], v[140:141]
	v_pk_fma_f32 v[114:115], v[120:121], v[112:113], v[138:139]
	v_mul_f32_e32 v112, v117, v117
	v_mul_f32_e32 v113, v119, v119
	v_fmac_f32_e32 v112, v116, v116
	v_fmac_f32_e32 v113, v118, v118
	v_add_f32_e32 v112, v112, v113
	v_mul_f32_e32 v113, v115, v115
	v_mul_f32_e32 v129, v135, v135
	v_fmac_f32_e32 v113, v114, v114
	v_fmac_f32_e32 v129, v134, v134
	v_add_f32_e32 v113, v113, v129
	v_add_f32_e32 v129, v112, v113
	v_cvt_pk_bf16_f32 v112, v116, v117
	v_cvt_pk_bf16_f32 v113, v118, v119
	v_lshlrev_b32_e32 v116, 16, v160
	v_and_b32_e32 v117, 0xffff0000, v160
	v_lshlrev_b32_e32 v118, 16, v161
	v_and_b32_e32 v119, 0xffff0000, v161
	v_pk_mul_f32 v[102:103], v[102:103], v[132:133] op_sel_hi:[1,0]
	v_pk_mul_f32 v[100:101], v[100:101], v[132:133] op_sel_hi:[1,0]
	v_lshlrev_b32_e32 v136, 16, v162
	v_and_b32_e32 v137, 0xffff0000, v162
	v_pk_fma_f32 v[102:103], v[110:111], v[102:103], v[118:119]
	v_pk_fma_f32 v[100:101], v[108:109], v[100:101], v[116:117]
	v_pk_mul_f32 v[96:97], v[96:97], v[132:133] op_sel_hi:[1,0]
	v_lshlrev_b32_e32 v138, 16, v163
	v_and_b32_e32 v139, 0xffff0000, v163
	v_pk_mul_f32 v[98:99], v[98:99], v[132:133] op_sel_hi:[1,0]
	v_pk_fma_f32 v[118:119], v[104:105], v[96:97], v[136:137]
	v_mul_f32_e32 v96, v101, v101
	v_mul_f32_e32 v97, v103, v103
	v_pk_fma_f32 v[116:117], v[106:107], v[98:99], v[138:139]
	v_fmac_f32_e32 v96, v100, v100
	v_fmac_f32_e32 v97, v102, v102
	v_add_f32_e32 v96, v96, v97
	v_mul_f32_e32 v97, v119, v119
	v_mul_f32_e32 v98, v117, v117
	v_fmac_f32_e32 v97, v118, v118
	v_fmac_f32_e32 v98, v116, v116
	v_add_f32_e32 v97, v97, v98
	v_add_f32_e32 v96, v96, v97
	v_add_f32_e32 v96, v129, v96
	ds_bpermute_b32 v97, v228, v96
	v_add_u32_e32 v128, 16, v207
	v_add_u32_e32 v130, s76, v128
	v_ashrrev_i32_e32 v131, 31, v130
	v_lshlrev_b64 v[130:131], 11, v[130:131]
	s_waitcnt lgkmcnt(0)
	v_add_f32_e32 v96, v96, v97
	ds_bpermute_b32 v97, v229, v96
	v_lshl_add_u64 v[130:131], v[204:205], 0, v[130:131]
	v_cvt_pk_bf16_f32 v114, v114, v115
	v_cvt_pk_bf16_f32 v115, v134, v135
	global_store_dwordx4 v[130:131], v[112:115], off
	v_cvt_pk_bf16_f32 v98, v100, v101
	v_cvt_pk_bf16_f32 v99, v102, v103
	v_cvt_pk_bf16_f32 v100, v118, v119
	v_cvt_pk_bf16_f32 v101, v116, v117
	global_store_dwordx4 v[130:131], v[98:101], off offset:256
	s_and_saveexec_b64 s[10:11], vcc
	s_cbranch_execz .LBB0_185
	s_waitcnt lgkmcnt(0)
	v_add_f32_e32 v96, v96, v97
	v_lshl_add_u32 v97, v128, 4, s75
	ds_write_b32 v97, v96
.LBB0_185:
	s_or_b64 exec, exec, s[10:11]
	ds_read_b32 v100, v206 offset:128
	v_lshlrev_b32_e32 v102, 16, v156
	v_and_b32_e32 v103, 0xffff0000, v156
	v_lshlrev_b32_e32 v112, 16, v157
	v_and_b32_e32 v113, 0xffff0000, v157
	s_waitcnt lgkmcnt(0)
	v_pk_mul_f32 v[94:95], v[94:95], v[100:101] op_sel_hi:[1,0]
	v_pk_mul_f32 v[92:93], v[92:93], v[100:101] op_sel_hi:[1,0]
	v_lshlrev_b32_e32 v114, 16, v158
	v_and_b32_e32 v115, 0xffff0000, v158
	v_lshlrev_b32_e32 v116, 16, v159
	v_and_b32_e32 v117, 0xffff0000, v159
	v_pk_fma_f32 v[94:95], v[126:127], v[94:95], v[112:113]
	v_pk_fma_f32 v[92:93], v[124:125], v[92:93], v[102:103]
	v_pk_mul_f32 v[90:91], v[90:91], v[100:101] op_sel_hi:[1,0]
	v_pk_mul_f32 v[88:89], v[88:89], v[100:101] op_sel_hi:[1,0]
	v_pk_fma_f32 v[102:103], v[122:123], v[90:91], v[116:117]
	v_pk_fma_f32 v[90:91], v[120:121], v[88:89], v[114:115]
	v_mul_f32_e32 v88, v93, v93
	v_mul_f32_e32 v89, v95, v95
	v_fmac_f32_e32 v88, v92, v92
	v_fmac_f32_e32 v89, v94, v94
	v_add_f32_e32 v88, v88, v89
	v_mul_f32_e32 v89, v91, v91
	v_mul_f32_e32 v97, v103, v103
	v_fmac_f32_e32 v89, v90, v90
	v_fmac_f32_e32 v97, v102, v102
	v_add_f32_e32 v89, v89, v97
	v_add_f32_e32 v97, v88, v89
	v_cvt_pk_bf16_f32 v88, v92, v93
	v_cvt_pk_bf16_f32 v89, v94, v95
	v_lshlrev_b32_e32 v92, 16, v152
	v_and_b32_e32 v93, 0xffff0000, v152
	v_lshlrev_b32_e32 v94, 16, v153
	v_and_b32_e32 v95, 0xffff0000, v153
	v_pk_mul_f32 v[86:87], v[86:87], v[100:101] op_sel_hi:[1,0]
	v_pk_mul_f32 v[84:85], v[84:85], v[100:101] op_sel_hi:[1,0]
	v_lshlrev_b32_e32 v112, 16, v154
	v_and_b32_e32 v113, 0xffff0000, v154
	v_pk_fma_f32 v[86:87], v[110:111], v[86:87], v[94:95]
	v_pk_fma_f32 v[84:85], v[108:109], v[84:85], v[92:93]
	v_pk_mul_f32 v[80:81], v[80:81], v[100:101] op_sel_hi:[1,0]
	v_lshlrev_b32_e32 v114, 16, v155
	v_and_b32_e32 v115, 0xffff0000, v155
	v_pk_mul_f32 v[82:83], v[82:83], v[100:101] op_sel_hi:[1,0]
	v_pk_fma_f32 v[94:95], v[104:105], v[80:81], v[112:113]
	v_mul_f32_e32 v80, v85, v85
	v_mul_f32_e32 v81, v87, v87
	v_pk_fma_f32 v[92:93], v[106:107], v[82:83], v[114:115]
	v_fmac_f32_e32 v80, v84, v84
	v_fmac_f32_e32 v81, v86, v86
	v_add_f32_e32 v80, v80, v81
	v_mul_f32_e32 v81, v95, v95
	v_mul_f32_e32 v82, v93, v93
	v_fmac_f32_e32 v81, v94, v94
	v_fmac_f32_e32 v82, v92, v92
	v_add_f32_e32 v81, v81, v82
	v_add_f32_e32 v80, v80, v81
	v_add_f32_e32 v80, v97, v80
	ds_bpermute_b32 v81, v228, v80
	v_add_u32_e32 v96, 32, v207
	v_add_u32_e32 v98, s76, v96
	v_ashrrev_i32_e32 v99, 31, v98
	v_lshlrev_b64 v[98:99], 11, v[98:99]
	s_waitcnt lgkmcnt(0)
	v_add_f32_e32 v80, v80, v81
	ds_bpermute_b32 v81, v229, v80
	v_lshl_add_u64 v[98:99], v[204:205], 0, v[98:99]
	v_cvt_pk_bf16_f32 v90, v90, v91
	v_cvt_pk_bf16_f32 v91, v102, v103
	global_store_dwordx4 v[98:99], v[88:91], off
	v_cvt_pk_bf16_f32 v82, v84, v85
	v_cvt_pk_bf16_f32 v83, v86, v87
	v_cvt_pk_bf16_f32 v84, v94, v95
	v_cvt_pk_bf16_f32 v85, v92, v93
	global_store_dwordx4 v[98:99], v[82:85], off offset:256
	s_and_saveexec_b64 s[10:11], vcc
	s_cbranch_execz .LBB0_187
	s_waitcnt lgkmcnt(0)
	v_add_f32_e32 v80, v80, v81
	v_lshl_add_u32 v81, v96, 4, s75
	ds_write_b32 v81, v80
.LBB0_187:
	s_or_b64 exec, exec, s[10:11]
	ds_read_b32 v84, v206 offset:192
	v_lshlrev_b32_e32 v86, 16, v148
	v_and_b32_e32 v87, 0xffff0000, v148
	v_lshlrev_b32_e32 v88, 16, v149
	v_and_b32_e32 v89, 0xffff0000, v149
	s_waitcnt lgkmcnt(0)
	v_pk_mul_f32 v[78:79], v[78:79], v[84:85] op_sel_hi:[1,0]
	v_pk_mul_f32 v[76:77], v[76:77], v[84:85] op_sel_hi:[1,0]
	v_lshlrev_b32_e32 v90, 16, v150
	v_and_b32_e32 v91, 0xffff0000, v150
	v_lshlrev_b32_e32 v92, 16, v151
	v_and_b32_e32 v93, 0xffff0000, v151
	v_pk_fma_f32 v[78:79], v[126:127], v[78:79], v[88:89]
	v_pk_fma_f32 v[76:77], v[124:125], v[76:77], v[86:87]
	v_pk_mul_f32 v[74:75], v[74:75], v[84:85] op_sel_hi:[1,0]
	v_pk_mul_f32 v[72:73], v[72:73], v[84:85] op_sel_hi:[1,0]
	v_pk_fma_f32 v[86:87], v[122:123], v[74:75], v[92:93]
	v_pk_fma_f32 v[74:75], v[120:121], v[72:73], v[90:91]
	v_mul_f32_e32 v72, v77, v77
	v_mul_f32_e32 v73, v79, v79
	v_fmac_f32_e32 v72, v76, v76
	v_fmac_f32_e32 v73, v78, v78
	v_add_f32_e32 v72, v72, v73
	v_mul_f32_e32 v73, v75, v75
	v_mul_f32_e32 v81, v87, v87
	v_fmac_f32_e32 v73, v74, v74
	v_fmac_f32_e32 v81, v86, v86
	v_add_f32_e32 v73, v73, v81
	v_add_f32_e32 v81, v72, v73
	v_cvt_pk_bf16_f32 v72, v76, v77
	v_cvt_pk_bf16_f32 v73, v78, v79
	v_lshlrev_b32_e32 v76, 16, v144
	v_and_b32_e32 v77, 0xffff0000, v144
	v_lshlrev_b32_e32 v78, 16, v145
	v_and_b32_e32 v79, 0xffff0000, v145
	v_pk_mul_f32 v[70:71], v[70:71], v[84:85] op_sel_hi:[1,0]
	v_pk_mul_f32 v[68:69], v[68:69], v[84:85] op_sel_hi:[1,0]
	v_lshlrev_b32_e32 v88, 16, v146
	v_and_b32_e32 v89, 0xffff0000, v146
	v_pk_fma_f32 v[70:71], v[110:111], v[70:71], v[78:79]
	v_pk_fma_f32 v[68:69], v[108:109], v[68:69], v[76:77]
	v_pk_mul_f32 v[64:65], v[64:65], v[84:85] op_sel_hi:[1,0]
	v_lshlrev_b32_e32 v90, 16, v147
	v_and_b32_e32 v91, 0xffff0000, v147
	v_pk_mul_f32 v[66:67], v[66:67], v[84:85] op_sel_hi:[1,0]
	v_pk_fma_f32 v[78:79], v[104:105], v[64:65], v[88:89]
	v_mul_f32_e32 v64, v69, v69
	v_mul_f32_e32 v65, v71, v71
	v_pk_fma_f32 v[76:77], v[106:107], v[66:67], v[90:91]
	v_fmac_f32_e32 v64, v68, v68
	v_fmac_f32_e32 v65, v70, v70
	v_add_f32_e32 v64, v64, v65
	v_mul_f32_e32 v65, v79, v79
	v_mul_f32_e32 v66, v77, v77
	v_fmac_f32_e32 v65, v78, v78
	v_fmac_f32_e32 v66, v76, v76
	v_add_f32_e32 v65, v65, v66
	v_add_f32_e32 v64, v64, v65
	v_add_f32_e32 v64, v81, v64
	ds_bpermute_b32 v65, v228, v64
	v_add_u32_e32 v80, 48, v207
	v_add_u32_e32 v82, s76, v80
	v_ashrrev_i32_e32 v83, 31, v82
	v_lshlrev_b64 v[82:83], 11, v[82:83]
	s_waitcnt lgkmcnt(0)
	v_add_f32_e32 v64, v64, v65
	ds_bpermute_b32 v65, v229, v64
	v_lshl_add_u64 v[82:83], v[204:205], 0, v[82:83]
	v_cvt_pk_bf16_f32 v74, v74, v75
	v_cvt_pk_bf16_f32 v75, v86, v87
	global_store_dwordx4 v[82:83], v[72:75], off
	v_cvt_pk_bf16_f32 v66, v68, v69
	v_cvt_pk_bf16_f32 v67, v70, v71
	v_cvt_pk_bf16_f32 v68, v78, v79
	v_cvt_pk_bf16_f32 v69, v76, v77
	global_store_dwordx4 v[82:83], v[66:69], off offset:256
	s_and_saveexec_b64 s[10:11], vcc
	s_cbranch_execz .LBB0_189
	s_waitcnt lgkmcnt(0)
	v_add_f32_e32 v64, v64, v65
	v_lshl_add_u32 v65, v80, 4, s75
	ds_write_b32 v65, v64
.LBB0_189:
	s_or_b64 exec, exec, s[10:11]
	v_add_u32_e32 v64, 0x80, v207
	v_add_u32_e32 v66, s76, v64
	v_ashrrev_i32_e32 v67, 31, v66
	v_lshlrev_b64 v[66:67], 11, v[66:67]
	v_lshl_add_u64 v[70:71], v[204:205], 0, v[66:67]
	ds_read_b32 v72, v206 offset:512
	s_waitcnt lgkmcnt(0)
	v_pk_mul_f32 v[62:63], v[62:63], v[72:73] op_sel_hi:[1,0]
	v_pk_mul_f32 v[60:61], v[60:61], v[72:73] op_sel_hi:[1,0]
	v_pk_mul_f32 v[58:59], v[58:59], v[72:73] op_sel_hi:[1,0]
	v_pk_mul_f32 v[56:57], v[56:57], v[72:73] op_sel_hi:[1,0]
	v_pk_mul_f32 v[54:55], v[54:55], v[72:73] op_sel_hi:[1,0]
	v_pk_mul_f32 v[52:53], v[52:53], v[72:73] op_sel_hi:[1,0]
	v_pk_mul_f32 v[50:51], v[50:51], v[72:73] op_sel_hi:[1,0]
	v_pk_mul_f32 v[48:49], v[48:49], v[72:73] op_sel_hi:[1,0]
	v_lshlrev_b32_e32 v74, 16, v236
	v_and_b32_e32 v75, 0xffff0000, v236
	v_lshlrev_b32_e32 v66, 16, v237
	v_and_b32_e32 v67, 0xffff0000, v237
	v_lshlrev_b32_e32 v76, 16, v238
	v_and_b32_e32 v77, 0xffff0000, v238
	v_lshlrev_b32_e32 v68, 16, v239
	v_and_b32_e32 v69, 0xffff0000, v239
	v_pk_fma_f32 v[66:67], v[126:127], v[62:63], v[66:67]
	v_pk_fma_f32 v[74:75], v[124:125], v[60:61], v[74:75]
	v_pk_fma_f32 v[68:69], v[122:123], v[58:59], v[68:69]
	v_pk_fma_f32 v[76:77], v[120:121], v[56:57], v[76:77]
	v_cvt_pk_bf16_f32 v56, v74, v75
	v_cvt_pk_bf16_f32 v57, v66, v67
	v_mul_f32_e32 v65, v75, v75
	v_cvt_pk_bf16_f32 v58, v76, v77
	v_cvt_pk_bf16_f32 v59, v68, v69
	v_mul_f32_e32 v67, v67, v67
	v_mul_f32_e32 v72, v77, v77
	v_mul_f32_e32 v69, v69, v69
	v_fmac_f32_e32 v65, v74, v74
	v_fmac_f32_e32 v67, v66, v66
	v_fmac_f32_e32 v72, v76, v76
	v_fmac_f32_e32 v69, v68, v68
	v_add_f32_e32 v65, v65, v67
	v_add_f32_e32 v66, v72, v69
	v_add_f32_e32 v65, v65, v66
	global_store_dwordx4 v[70:71], v[56:59], off
	v_lshlrev_b32_e32 v66, 16, v240
	v_and_b32_e32 v67, 0xffff0000, v240
	v_lshlrev_b32_e32 v60, 16, v241
	v_and_b32_e32 v61, 0xffff0000, v241
	v_lshlrev_b32_e32 v68, 16, v242
	v_and_b32_e32 v69, 0xffff0000, v242
	v_lshlrev_b32_e32 v62, 16, v243
	v_and_b32_e32 v63, 0xffff0000, v243
	v_pk_fma_f32 v[54:55], v[110:111], v[54:55], v[60:61]
	v_pk_fma_f32 v[52:53], v[108:109], v[52:53], v[66:67]
	v_pk_fma_f32 v[60:61], v[106:107], v[50:51], v[62:63]
	v_pk_fma_f32 v[62:63], v[104:105], v[48:49], v[68:69]
	v_mul_f32_e32 v48, v53, v53
	v_mul_f32_e32 v49, v55, v55
	v_mul_f32_e32 v50, v63, v63
	v_mul_f32_e32 v51, v61, v61
	v_fmac_f32_e32 v48, v52, v52
	v_fmac_f32_e32 v49, v54, v54
	v_fmac_f32_e32 v50, v62, v62
	v_fmac_f32_e32 v51, v60, v60
	v_add_f32_e32 v48, v48, v49
	v_add_f32_e32 v49, v50, v51
	v_add_f32_e32 v48, v48, v49
	v_add_f32_e32 v48, v65, v48
	ds_bpermute_b32 v49, v228, v48
	v_cvt_pk_bf16_f32 v50, v52, v53
	v_cvt_pk_bf16_f32 v51, v54, v55
	v_cvt_pk_bf16_f32 v52, v62, v63
	v_cvt_pk_bf16_f32 v53, v60, v61
	s_waitcnt lgkmcnt(0)
	v_add_f32_e32 v48, v48, v49
	ds_bpermute_b32 v49, v229, v48
	global_store_dwordx4 v[70:71], v[50:53], off offset:256
	s_and_saveexec_b64 s[10:11], vcc
	s_cbranch_execz .LBB0_191
	s_waitcnt lgkmcnt(0)
	v_add_f32_e32 v48, v48, v49
	v_lshl_add_u32 v49, v64, 4, s75
	ds_write_b32 v49, v48
.LBB0_191:
	s_or_b64 exec, exec, s[10:11]
	v_add_u32_e32 v48, 0x90, v207
	v_add_u32_e32 v50, s76, v48
	v_ashrrev_i32_e32 v51, 31, v50
	v_lshlrev_b64 v[50:51], 11, v[50:51]
	v_lshl_add_u64 v[54:55], v[204:205], 0, v[50:51]
	ds_read_b32 v56, v206 offset:576
	s_waitcnt lgkmcnt(0)
	v_pk_mul_f32 v[46:47], v[46:47], v[56:57] op_sel_hi:[1,0]
	v_pk_mul_f32 v[44:45], v[44:45], v[56:57] op_sel_hi:[1,0]
	v_pk_mul_f32 v[42:43], v[42:43], v[56:57] op_sel_hi:[1,0]
	v_pk_mul_f32 v[40:41], v[40:41], v[56:57] op_sel_hi:[1,0]
	v_pk_mul_f32 v[38:39], v[38:39], v[56:57] op_sel_hi:[1,0]
	v_pk_mul_f32 v[36:37], v[36:37], v[56:57] op_sel_hi:[1,0]
	v_pk_mul_f32 v[34:35], v[34:35], v[56:57] op_sel_hi:[1,0]
	v_pk_mul_f32 v[32:33], v[32:33], v[56:57] op_sel_hi:[1,0]
	v_lshlrev_b32_e32 v58, 16, v244
	v_and_b32_e32 v59, 0xffff0000, v244
	v_lshlrev_b32_e32 v50, 16, v245
	v_and_b32_e32 v51, 0xffff0000, v245
	v_lshlrev_b32_e32 v60, 16, v246
	v_and_b32_e32 v61, 0xffff0000, v246
	v_lshlrev_b32_e32 v52, 16, v247
	v_and_b32_e32 v53, 0xffff0000, v247
	v_pk_fma_f32 v[50:51], v[126:127], v[46:47], v[50:51]
	v_pk_fma_f32 v[58:59], v[124:125], v[44:45], v[58:59]
	v_pk_fma_f32 v[52:53], v[122:123], v[42:43], v[52:53]
	v_pk_fma_f32 v[60:61], v[120:121], v[40:41], v[60:61]
	v_cvt_pk_bf16_f32 v40, v58, v59
	v_cvt_pk_bf16_f32 v41, v50, v51
	v_mul_f32_e32 v49, v59, v59
	v_cvt_pk_bf16_f32 v42, v60, v61
	v_cvt_pk_bf16_f32 v43, v52, v53
	v_mul_f32_e32 v51, v51, v51
	v_mul_f32_e32 v56, v61, v61
	v_mul_f32_e32 v53, v53, v53
	v_fmac_f32_e32 v49, v58, v58
	v_fmac_f32_e32 v51, v50, v50
	v_fmac_f32_e32 v56, v60, v60
	v_fmac_f32_e32 v53, v52, v52
	v_add_f32_e32 v49, v49, v51
	v_add_f32_e32 v50, v56, v53
	v_add_f32_e32 v49, v49, v50
	global_store_dwordx4 v[54:55], v[40:43], off
	v_lshlrev_b32_e32 v50, 16, v248
	v_and_b32_e32 v51, 0xffff0000, v248
	v_lshlrev_b32_e32 v44, 16, v249
	v_and_b32_e32 v45, 0xffff0000, v249
	v_lshlrev_b32_e32 v52, 16, v250
	v_and_b32_e32 v53, 0xffff0000, v250
	v_lshlrev_b32_e32 v46, 16, v251
	v_and_b32_e32 v47, 0xffff0000, v251
	v_pk_fma_f32 v[38:39], v[110:111], v[38:39], v[44:45]
	v_pk_fma_f32 v[36:37], v[108:109], v[36:37], v[50:51]
	v_pk_fma_f32 v[44:45], v[106:107], v[34:35], v[46:47]
	v_pk_fma_f32 v[46:47], v[104:105], v[32:33], v[52:53]
	v_mul_f32_e32 v32, v37, v37
	v_mul_f32_e32 v33, v39, v39
	v_mul_f32_e32 v34, v47, v47
	v_mul_f32_e32 v35, v45, v45
	v_fmac_f32_e32 v32, v36, v36
	v_fmac_f32_e32 v33, v38, v38
	v_fmac_f32_e32 v34, v46, v46
	v_fmac_f32_e32 v35, v44, v44
	v_add_f32_e32 v32, v32, v33
	v_add_f32_e32 v33, v34, v35
	v_add_f32_e32 v32, v32, v33
	v_add_f32_e32 v32, v49, v32
	ds_bpermute_b32 v33, v228, v32
	v_cvt_pk_bf16_f32 v34, v36, v37
	v_cvt_pk_bf16_f32 v35, v38, v39
	v_cvt_pk_bf16_f32 v36, v46, v47
	v_cvt_pk_bf16_f32 v37, v44, v45
	s_waitcnt lgkmcnt(0)
	v_add_f32_e32 v32, v32, v33
	ds_bpermute_b32 v33, v229, v32
	global_store_dwordx4 v[54:55], v[34:37], off offset:256
	s_and_saveexec_b64 s[10:11], vcc
	s_cbranch_execz .LBB0_193
	s_waitcnt lgkmcnt(0)
	v_add_f32_e32 v32, v32, v33
	v_lshl_add_u32 v33, v48, 4, s75
	ds_write_b32 v33, v32
.LBB0_193:
	s_or_b64 exec, exec, s[10:11]
	v_add_u32_e32 v32, 0xa0, v207
	v_add_u32_e32 v34, s76, v32
	v_ashrrev_i32_e32 v35, 31, v34
	v_lshlrev_b64 v[34:35], 11, v[34:35]
	v_lshl_add_u64 v[38:39], v[204:205], 0, v[34:35]
	ds_read_b32 v40, v206 offset:640
	s_waitcnt lgkmcnt(0)
	v_pk_mul_f32 v[30:31], v[30:31], v[40:41] op_sel_hi:[1,0]
	v_pk_mul_f32 v[28:29], v[28:29], v[40:41] op_sel_hi:[1,0]
	v_pk_mul_f32 v[26:27], v[26:27], v[40:41] op_sel_hi:[1,0]
	v_pk_mul_f32 v[24:25], v[24:25], v[40:41] op_sel_hi:[1,0]
	v_pk_mul_f32 v[22:23], v[22:23], v[40:41] op_sel_hi:[1,0]
	v_pk_mul_f32 v[20:21], v[20:21], v[40:41] op_sel_hi:[1,0]
	v_pk_mul_f32 v[18:19], v[18:19], v[40:41] op_sel_hi:[1,0]
	v_pk_mul_f32 v[16:17], v[16:17], v[40:41] op_sel_hi:[1,0]
	s_waitcnt vmcnt(13)
	v_lshlrev_b32_e32 v42, 16, v168
	v_and_b32_e32 v43, 0xffff0000, v168
	v_lshlrev_b32_e32 v34, 16, v169
	v_and_b32_e32 v35, 0xffff0000, v169
	v_lshlrev_b32_e32 v44, 16, v170
	v_and_b32_e32 v45, 0xffff0000, v170
	v_lshlrev_b32_e32 v36, 16, v171
	v_and_b32_e32 v37, 0xffff0000, v171
	v_pk_fma_f32 v[34:35], v[126:127], v[30:31], v[34:35]
	v_pk_fma_f32 v[42:43], v[124:125], v[28:29], v[42:43]
	v_pk_fma_f32 v[36:37], v[122:123], v[26:27], v[36:37]
	v_pk_fma_f32 v[44:45], v[120:121], v[24:25], v[44:45]
	v_cvt_pk_bf16_f32 v24, v42, v43
	v_cvt_pk_bf16_f32 v25, v34, v35
	v_mul_f32_e32 v33, v43, v43
	v_cvt_pk_bf16_f32 v26, v44, v45
	v_cvt_pk_bf16_f32 v27, v36, v37
	v_mul_f32_e32 v35, v35, v35
	v_mul_f32_e32 v40, v45, v45
	v_mul_f32_e32 v37, v37, v37
	v_fmac_f32_e32 v33, v42, v42
	v_fmac_f32_e32 v35, v34, v34
	v_fmac_f32_e32 v40, v44, v44
	v_fmac_f32_e32 v37, v36, v36
	v_add_f32_e32 v33, v33, v35
	v_add_f32_e32 v34, v40, v37
	v_add_f32_e32 v33, v33, v34
	global_store_dwordx4 v[38:39], v[24:27], off
	s_waitcnt vmcnt(13)
	v_lshlrev_b32_e32 v34, 16, v172
	v_and_b32_e32 v35, 0xffff0000, v172
	v_lshlrev_b32_e32 v28, 16, v173
	v_and_b32_e32 v29, 0xffff0000, v173
	v_lshlrev_b32_e32 v36, 16, v174
	v_and_b32_e32 v37, 0xffff0000, v174
	v_lshlrev_b32_e32 v30, 16, v175
	v_and_b32_e32 v31, 0xffff0000, v175
	v_pk_fma_f32 v[22:23], v[110:111], v[22:23], v[28:29]
	v_pk_fma_f32 v[20:21], v[108:109], v[20:21], v[34:35]
	v_pk_fma_f32 v[28:29], v[106:107], v[18:19], v[30:31]
	v_pk_fma_f32 v[30:31], v[104:105], v[16:17], v[36:37]
	v_mul_f32_e32 v16, v21, v21
	v_mul_f32_e32 v17, v23, v23
	v_mul_f32_e32 v18, v31, v31
	v_mul_f32_e32 v19, v29, v29
	v_fmac_f32_e32 v16, v20, v20
	v_fmac_f32_e32 v17, v22, v22
	v_fmac_f32_e32 v18, v30, v30
	v_fmac_f32_e32 v19, v28, v28
	v_add_f32_e32 v16, v16, v17
	v_add_f32_e32 v17, v18, v19
	v_add_f32_e32 v16, v16, v17
	v_add_f32_e32 v16, v33, v16
	ds_bpermute_b32 v17, v228, v16
	v_cvt_pk_bf16_f32 v18, v20, v21
	v_cvt_pk_bf16_f32 v19, v22, v23
	v_cvt_pk_bf16_f32 v20, v30, v31
	v_cvt_pk_bf16_f32 v21, v28, v29
	s_waitcnt lgkmcnt(0)
	v_add_f32_e32 v16, v16, v17
	ds_bpermute_b32 v17, v229, v16
	global_store_dwordx4 v[38:39], v[18:21], off offset:256
	s_and_saveexec_b64 s[10:11], vcc
	s_cbranch_execz .LBB0_195
	s_waitcnt lgkmcnt(0)
	v_add_f32_e32 v16, v16, v17
	v_lshl_add_u32 v17, v32, 4, s75
	ds_write_b32 v17, v16
.LBB0_195:
	s_or_b64 exec, exec, s[10:11]
	v_add_u32_e32 v16, 0xb0, v207
	v_add_u32_e32 v18, s76, v16
	v_ashrrev_i32_e32 v19, 31, v18
	v_lshlrev_b64 v[18:19], 11, v[18:19]
	v_lshl_add_u64 v[22:23], v[204:205], 0, v[18:19]
	ds_read_b32 v24, v206 offset:704
	s_waitcnt lgkmcnt(0)
	v_pk_mul_f32 v[14:15], v[14:15], v[24:25] op_sel_hi:[1,0]
	v_pk_mul_f32 v[12:13], v[12:13], v[24:25] op_sel_hi:[1,0]
	v_pk_mul_f32 v[10:11], v[10:11], v[24:25] op_sel_hi:[1,0]
	v_pk_mul_f32 v[8:9], v[8:9], v[24:25] op_sel_hi:[1,0]
	v_pk_mul_f32 v[6:7], v[6:7], v[24:25] op_sel_hi:[1,0]
	v_pk_mul_f32 v[4:5], v[4:5], v[24:25] op_sel_hi:[1,0]
	v_pk_mul_f32 v[2:3], v[2:3], v[24:25] op_sel_hi:[1,0]
	v_pk_mul_f32 v[0:1], v[0:1], v[24:25] op_sel_hi:[1,0]
	s_waitcnt vmcnt(13)
	v_lshlrev_b32_e32 v26, 16, v208
	v_and_b32_e32 v27, 0xffff0000, v208
	v_lshlrev_b32_e32 v18, 16, v209
	v_and_b32_e32 v19, 0xffff0000, v209
	v_lshlrev_b32_e32 v28, 16, v210
	v_and_b32_e32 v29, 0xffff0000, v210
	v_lshlrev_b32_e32 v20, 16, v211
	v_and_b32_e32 v21, 0xffff0000, v211
	v_pk_fma_f32 v[18:19], v[126:127], v[14:15], v[18:19]
	v_pk_fma_f32 v[26:27], v[124:125], v[12:13], v[26:27]
	v_pk_fma_f32 v[20:21], v[122:123], v[10:11], v[20:21]
	v_pk_fma_f32 v[28:29], v[120:121], v[8:9], v[28:29]
	v_cvt_pk_bf16_f32 v8, v26, v27
	v_cvt_pk_bf16_f32 v9, v18, v19
	v_mul_f32_e32 v17, v27, v27
	v_cvt_pk_bf16_f32 v10, v28, v29
	v_cvt_pk_bf16_f32 v11, v20, v21
	v_mul_f32_e32 v19, v19, v19
	v_mul_f32_e32 v24, v29, v29
	v_mul_f32_e32 v21, v21, v21
	v_fmac_f32_e32 v17, v26, v26
	v_fmac_f32_e32 v19, v18, v18
	v_fmac_f32_e32 v24, v28, v28
	v_fmac_f32_e32 v21, v20, v20
	v_add_f32_e32 v17, v17, v19
	v_add_f32_e32 v18, v24, v21
	v_add_f32_e32 v17, v17, v18
	global_store_dwordx4 v[22:23], v[8:11], off
	s_waitcnt vmcnt(13)
	v_lshlrev_b32_e32 v18, 16, v212
	v_and_b32_e32 v19, 0xffff0000, v212
	v_lshlrev_b32_e32 v12, 16, v213
	v_and_b32_e32 v13, 0xffff0000, v213
	v_lshlrev_b32_e32 v20, 16, v214
	v_and_b32_e32 v21, 0xffff0000, v214
	v_lshlrev_b32_e32 v14, 16, v215
	v_and_b32_e32 v15, 0xffff0000, v215
	v_pk_fma_f32 v[6:7], v[110:111], v[6:7], v[12:13]
	v_pk_fma_f32 v[4:5], v[108:109], v[4:5], v[18:19]
	v_pk_fma_f32 v[12:13], v[106:107], v[2:3], v[14:15]
	v_pk_fma_f32 v[14:15], v[104:105], v[0:1], v[20:21]
	v_mul_f32_e32 v0, v5, v5
	v_mul_f32_e32 v1, v7, v7
	v_mul_f32_e32 v2, v15, v15
	v_mul_f32_e32 v3, v13, v13
	v_fmac_f32_e32 v0, v4, v4
	v_fmac_f32_e32 v1, v6, v6
	v_fmac_f32_e32 v2, v14, v14
	v_fmac_f32_e32 v3, v12, v12
	v_add_f32_e32 v0, v0, v1
	v_add_f32_e32 v1, v2, v3
	v_add_f32_e32 v0, v0, v1
	v_add_f32_e32 v0, v17, v0
	ds_bpermute_b32 v1, v228, v0
	v_cvt_pk_bf16_f32 v2, v4, v5
	v_cvt_pk_bf16_f32 v3, v6, v7
	v_cvt_pk_bf16_f32 v4, v14, v15
	v_cvt_pk_bf16_f32 v5, v12, v13
	s_waitcnt lgkmcnt(0)
	v_add_f32_e32 v0, v0, v1
	ds_bpermute_b32 v1, v229, v0
	global_store_dwordx4 v[22:23], v[2:5], off offset:256
	s_and_saveexec_b64 s[10:11], vcc
	s_cbranch_execz .LBB0_197
	s_waitcnt lgkmcnt(0)
	v_add_f32_e32 v0, v0, v1
	v_lshl_add_u32 v1, v16, 4, s75
	ds_write_b32 v1, v0

.LBB0_527:
	s_or_b64 exec, exec, s[10:11]
	s_lshl_b32 s10, s12, 8
	s_lshl_b32 s11, s9, 5
	s_add_i32 s11, s11, s10
	s_lshl_b32 s51, s8, 8
	s_lshl_b32 s85, s13, 6
	v_lshl_add_u32 v144, v206, 3, s11
	s_add_i32 s8, s85, s51
	v_ashrrev_i32_e32 v145, 31, v144
	v_add_u32_e32 v146, s8, v232
	s_waitcnt vmcnt(0)
	v_lshl_add_u64 v[108:109], v[144:145], 2, v[104:105]
	v_lshl_add_u64 v[144:145], v[144:145], 1, v[202:203]
	v_ashrrev_i32_e32 v147, 31, v146
	v_lshl_add_u64 v[204:205], v[144:145], 0, s[34:35]
	v_lshlrev_b64 v[144:145], 11, v[146:147]
	s_waitcnt lgkmcnt(0)
	s_barrier
	v_lshl_add_u64 v[144:145], v[204:205], 0, v[144:145]
	global_load_dwordx4 v[120:123], v[108:109], off offset:16
	global_load_dwordx4 v[124:127], v[108:109], off
	s_waitcnt lgkmcnt(0)
	global_load_dwordx4 v[104:107], v[108:109], off offset:528
	s_nop 0
	global_load_dwordx4 v[108:111], v[108:109], off offset:512
	s_nop 0
	global_load_dwordx4 v[172:175], v[144:145], off
	global_load_dwordx4 v[168:171], v[144:145], off offset:256
	v_add_u32_e32 v144, 16, v146
	v_ashrrev_i32_e32 v145, 31, v144
	v_lshlrev_b64 v[144:145], 11, v[144:145]
	v_lshl_add_u64 v[144:145], v[204:205], 0, v[144:145]
	global_load_dwordx4 v[164:167], v[144:145], off
	global_load_dwordx4 v[160:163], v[144:145], off offset:256
	v_add_u32_e32 v144, 32, v146
	v_ashrrev_i32_e32 v145, 31, v144
	v_lshlrev_b64 v[144:145], 11, v[144:145]
	v_lshl_add_u64 v[144:145], v[204:205], 0, v[144:145]
	global_load_dwordx4 v[156:159], v[144:145], off
	global_load_dwordx4 v[152:155], v[144:145], off offset:256
	v_add_u32_e32 v144, 0x80, v146
	v_ashrrev_i32_e32 v145, 31, v144
	v_lshlrev_b64 v[144:145], 11, v[144:145]
	v_lshl_add_u64 v[144:145], v[204:205], 0, v[144:145]
	global_load_dwordx4 v[236:239], v[144:145], off
	global_load_dwordx4 v[240:243], v[144:145], off offset:256
	v_add_u32_e32 v144, 0x90, v146
	v_ashrrev_i32_e32 v145, 31, v144
	v_lshlrev_b64 v[144:145], 11, v[144:145]
	v_lshl_add_u64 v[144:145], v[204:205], 0, v[144:145]
	global_load_dwordx4 v[244:247], v[144:145], off
	global_load_dwordx4 v[248:251], v[144:145], off offset:256
	v_add_u32_e32 v144, 48, v146
	v_ashrrev_i32_e32 v145, 31, v144
	v_lshlrev_b64 v[144:145], 11, v[144:145]
	v_lshl_add_u64 v[144:145], v[204:205], 0, v[144:145]
	global_load_dwordx4 v[148:151], v[144:145], off
	s_nop 0
	global_load_dwordx4 v[144:147], v[144:145], off offset:256
	s_lshl_b32 s8, s13, 2
	v_lshl_add_u32 v206, v206, 4, v232
	s_add_i32 s10, s8, s9
	v_cmp_gt_i32_e64 s[8:9], 32, v206
	v_lshl_add_u32 v231, s10, 5, v206
	s_and_saveexec_b64 s[52:53], s[8:9]
	s_cbranch_execz .LBB0_542
	v_lshl_add_u32 v206, v231, 4, v227
	ds_read_b128 v[208:211], v206
	v_add_u32_e32 v206, s51, v231
	v_ashrrev_i32_e32 v207, 31, v206
	v_lshlrev_b64 v[206:207], 5, v[206:207]
	v_lshl_add_u64 v[206:207], v[202:203], 0, v[206:207]
	s_waitcnt lgkmcnt(0)
	v_mov_b32_e32 v214, v209
	v_mov_b32_e32 v215, v210
	v_mov_b32_e32 v209, v211
	v_pk_add_f32 v[208:209], v[214:215], v[208:209]
	v_lshl_add_u64 v[206:207], v[206:207], 0, s[36:37]
	s_ashr_i32 s13, s12, 31
	v_pk_add_f32 v[208:209], v[208:209], v[208:209] op_sel:[0,1] op_sel_hi:[1,0]
	v_lshl_add_u64 v[212:213], s[12:13], 3, v[206:207]
	v_mov_b32_e32 v209, v217
	s_mov_b32 s13, 0x100000
	s_mov_b64 s[54:55], 0
	global_store_dwordx2 v[212:213], v[208:209], off sc1
	s_branch .LBB0_534

.LBB0_542:
	s_or_b64 exec, exec, s[52:53]
	v_add_u32_e32 v207, s85, v232
	s_waitcnt vmcnt(0) lgkmcnt(0)
	s_barrier
	v_lshl_add_u32 v206, v207, 2, v228
	ds_read_b32 v210, v206
	v_lshlrev_b32_e32 v212, 16, v172
	v_and_b32_e32 v213, 0xffff0000, v172
	v_lshlrev_b32_e32 v172, 16, v173
	v_and_b32_e32 v173, 0xffff0000, v173
	s_waitcnt lgkmcnt(0)
	v_pk_mul_f32 v[142:143], v[142:143], v[210:211] op_sel_hi:[1,0]
	v_pk_mul_f32 v[140:141], v[140:141], v[210:211] op_sel_hi:[1,0]
	v_lshlrev_b32_e32 v214, 16, v174
	v_and_b32_e32 v215, 0xffff0000, v174
	v_lshlrev_b32_e32 v174, 16, v175
	v_and_b32_e32 v175, 0xffff0000, v175
	v_pk_fma_f32 v[142:143], v[126:127], v[142:143], v[172:173]
	v_pk_fma_f32 v[140:141], v[124:125], v[140:141], v[212:213]
	v_pk_mul_f32 v[138:139], v[138:139], v[210:211] op_sel_hi:[1,0]
	v_pk_mul_f32 v[136:137], v[136:137], v[210:211] op_sel_hi:[1,0]
	v_pk_fma_f32 v[172:173], v[122:123], v[138:139], v[174:175]
	v_pk_fma_f32 v[138:139], v[120:121], v[136:137], v[214:215]
	v_mul_f32_e32 v136, v141, v141
	v_mul_f32_e32 v137, v143, v143
	v_fmac_f32_e32 v136, v140, v140
	v_fmac_f32_e32 v137, v142, v142
	v_add_f32_e32 v136, v136, v137
	v_mul_f32_e32 v137, v139, v139
	v_mul_f32_e32 v174, v173, v173
	v_fmac_f32_e32 v137, v138, v138
	v_fmac_f32_e32 v174, v172, v172
	v_add_f32_e32 v137, v137, v174
	v_add_f32_e32 v174, v136, v137
	v_cvt_pk_bf16_f32 v136, v140, v141
	v_cvt_pk_bf16_f32 v137, v142, v143
	v_lshlrev_b32_e32 v140, 16, v168
	v_and_b32_e32 v141, 0xffff0000, v168
	v_lshlrev_b32_e32 v142, 16, v169
	v_and_b32_e32 v143, 0xffff0000, v169
	v_pk_mul_f32 v[134:135], v[134:135], v[210:211] op_sel_hi:[1,0]
	v_pk_mul_f32 v[132:133], v[132:133], v[210:211] op_sel_hi:[1,0]
	v_lshlrev_b32_e32 v168, 16, v170
	v_and_b32_e32 v169, 0xffff0000, v170
	v_pk_fma_f32 v[134:135], v[110:111], v[134:135], v[142:143]
	v_pk_fma_f32 v[132:133], v[108:109], v[132:133], v[140:141]
	v_pk_mul_f32 v[128:129], v[128:129], v[210:211] op_sel_hi:[1,0]
	v_lshlrev_b32_e32 v170, 16, v171
	v_and_b32_e32 v171, 0xffff0000, v171
	v_pk_mul_f32 v[130:131], v[130:131], v[210:211] op_sel_hi:[1,0]
	v_pk_fma_f32 v[142:143], v[104:105], v[128:129], v[168:169]
	v_mul_f32_e32 v128, v133, v133
	v_mul_f32_e32 v129, v135, v135
	v_pk_fma_f32 v[140:141], v[106:107], v[130:131], v[170:171]
	v_fmac_f32_e32 v128, v132, v132
	v_fmac_f32_e32 v129, v134, v134
	v_add_f32_e32 v128, v128, v129
	v_mul_f32_e32 v129, v143, v143
	v_mul_f32_e32 v130, v141, v141
	v_fmac_f32_e32 v129, v142, v142
	v_fmac_f32_e32 v130, v140, v140
	v_add_f32_e32 v129, v129, v130
	v_add_f32_e32 v128, v128, v129
	v_add_f32_e32 v128, v174, v128
	ds_bpermute_b32 v129, v229, v128
	v_add_u32_e32 v208, s51, v207
	v_ashrrev_i32_e32 v209, 31, v208
	v_lshlrev_b64 v[208:209], 11, v[208:209]
	v_lshl_add_u64 v[208:209], v[204:205], 0, v[208:209]
	s_waitcnt lgkmcnt(0)
	v_add_f32_e32 v128, v128, v129
	ds_bpermute_b32 v129, v230, v128
	v_cvt_pk_bf16_f32 v138, v138, v139
	v_cvt_pk_bf16_f32 v139, v172, v173
	global_store_dwordx4 v[208:209], v[136:139], off
	v_cvt_pk_bf16_f32 v130, v132, v133
	v_cvt_pk_bf16_f32 v131, v134, v135
	v_cvt_pk_bf16_f32 v132, v142, v143
	v_cvt_pk_bf16_f32 v133, v140, v141
	global_store_dwordx4 v[208:209], v[130:133], off offset:256
	s_and_saveexec_b64 s[10:11], vcc
	s_cbranch_execz .LBB0_544
	s_waitcnt lgkmcnt(0)
	v_add_f32_e32 v128, v128, v129
	v_lshl_add_u32 v129, v207, 4, s39
	ds_write_b32 v129, v128
.LBB0_544:
	s_or_b64 exec, exec, s[10:11]
	v_add_u32_e32 v252, 0xa0, v207
	v_add_u32_e32 v252, s51, v252
	v_ashrrev_i32_e32 v253, 31, v252
	v_lshlrev_b64 v[252:253], 11, v[252:253]
	v_lshl_add_u64 v[252:253], v[204:205], 0, v[252:253]
	global_load_dwordx4 v[168:171], v[252:253], off
	global_load_dwordx4 v[172:175], v[252:253], off offset:256
	v_add_u32_e32 v252, 0xb0, v207
	v_add_u32_e32 v252, s51, v252
	v_ashrrev_i32_e32 v253, 31, v252
	v_lshlrev_b64 v[252:253], 11, v[252:253]
	v_lshl_add_u64 v[252:253], v[204:205], 0, v[252:253]
	global_load_dwordx4 v[208:211], v[252:253], off
	global_load_dwordx4 v[212:215], v[252:253], off offset:256
	ds_read_b32 v132, v206 offset:64
	v_lshlrev_b32_e32 v134, 16, v164
	v_and_b32_e32 v135, 0xffff0000, v164
	v_lshlrev_b32_e32 v136, 16, v165
	v_and_b32_e32 v137, 0xffff0000, v165
	s_waitcnt lgkmcnt(0)
	v_pk_mul_f32 v[118:119], v[118:119], v[132:133] op_sel_hi:[1,0]
	v_pk_mul_f32 v[116:117], v[116:117], v[132:133] op_sel_hi:[1,0]
	v_lshlrev_b32_e32 v138, 16, v166
	v_and_b32_e32 v139, 0xffff0000, v166
	v_lshlrev_b32_e32 v140, 16, v167
	v_and_b32_e32 v141, 0xffff0000, v167
	v_pk_fma_f32 v[118:119], v[126:127], v[118:119], v[136:137]
	v_pk_fma_f32 v[116:117], v[124:125], v[116:117], v[134:135]
	v_pk_mul_f32 v[114:115], v[114:115], v[132:133] op_sel_hi:[1,0]
	v_pk_mul_f32 v[112:113], v[112:113], v[132:133] op_sel_hi:[1,0]
	v_pk_fma_f32 v[134:135], v[122:123], v[114:115], v[140:141]
	v_pk_fma_f32 v[114:115], v[120:121], v[112:113], v[138:139]
	v_mul_f32_e32 v112, v117, v117
	v_mul_f32_e32 v113, v119, v119
	v_fmac_f32_e32 v112, v116, v116
	v_fmac_f32_e32 v113, v118, v118
	v_add_f32_e32 v112, v112, v113
	v_mul_f32_e32 v113, v115, v115
	v_mul_f32_e32 v129, v135, v135
	v_fmac_f32_e32 v113, v114, v114
	v_fmac_f32_e32 v129, v134, v134
	v_add_f32_e32 v113, v113, v129
	v_add_f32_e32 v129, v112, v113
	v_cvt_pk_bf16_f32 v112, v116, v117
	v_cvt_pk_bf16_f32 v113, v118, v119
	v_lshlrev_b32_e32 v116, 16, v160
	v_and_b32_e32 v117, 0xffff0000, v160
	v_lshlrev_b32_e32 v118, 16, v161
	v_and_b32_e32 v119, 0xffff0000, v161
	v_pk_mul_f32 v[102:103], v[102:103], v[132:133] op_sel_hi:[1,0]
	v_pk_mul_f32 v[100:101], v[100:101], v[132:133] op_sel_hi:[1,0]
	v_lshlrev_b32_e32 v136, 16, v162
	v_and_b32_e32 v137, 0xffff0000, v162
	v_pk_fma_f32 v[102:103], v[110:111], v[102:103], v[118:119]
	v_pk_fma_f32 v[100:101], v[108:109], v[100:101], v[116:117]
	v_pk_mul_f32 v[96:97], v[96:97], v[132:133] op_sel_hi:[1,0]
	v_lshlrev_b32_e32 v138, 16, v163
	v_and_b32_e32 v139, 0xffff0000, v163
	v_pk_mul_f32 v[98:99], v[98:99], v[132:133] op_sel_hi:[1,0]
	v_pk_fma_f32 v[118:119], v[104:105], v[96:97], v[136:137]
	v_mul_f32_e32 v96, v101, v101
	v_mul_f32_e32 v97, v103, v103
	v_pk_fma_f32 v[116:117], v[106:107], v[98:99], v[138:139]
	v_fmac_f32_e32 v96, v100, v100
	v_fmac_f32_e32 v97, v102, v102
	v_add_f32_e32 v96, v96, v97
	v_mul_f32_e32 v97, v119, v119
	v_mul_f32_e32 v98, v117, v117
	v_fmac_f32_e32 v97, v118, v118
	v_fmac_f32_e32 v98, v116, v116
	v_add_f32_e32 v97, v97, v98
	v_add_f32_e32 v96, v96, v97
	v_add_f32_e32 v96, v129, v96
	ds_bpermute_b32 v97, v229, v96
	v_add_u32_e32 v128, 16, v207
	v_add_u32_e32 v130, s51, v128
	v_ashrrev_i32_e32 v131, 31, v130
	v_lshlrev_b64 v[130:131], 11, v[130:131]
	s_waitcnt lgkmcnt(0)
	v_add_f32_e32 v96, v96, v97
	ds_bpermute_b32 v97, v230, v96
	v_lshl_add_u64 v[130:131], v[204:205], 0, v[130:131]
	v_cvt_pk_bf16_f32 v114, v114, v115
	v_cvt_pk_bf16_f32 v115, v134, v135
	global_store_dwordx4 v[130:131], v[112:115], off
	v_cvt_pk_bf16_f32 v98, v100, v101
	v_cvt_pk_bf16_f32 v99, v102, v103
	v_cvt_pk_bf16_f32 v100, v118, v119
	v_cvt_pk_bf16_f32 v101, v116, v117
	global_store_dwordx4 v[130:131], v[98:101], off offset:256
	s_and_saveexec_b64 s[10:11], vcc
	s_cbranch_execz .LBB0_546
	s_waitcnt lgkmcnt(0)
	v_add_f32_e32 v96, v96, v97
	v_lshl_add_u32 v97, v128, 4, s39
	ds_write_b32 v97, v96
.LBB0_546:
	s_or_b64 exec, exec, s[10:11]
	ds_read_b32 v100, v206 offset:128
	v_lshlrev_b32_e32 v102, 16, v156
	v_and_b32_e32 v103, 0xffff0000, v156
	v_lshlrev_b32_e32 v112, 16, v157
	v_and_b32_e32 v113, 0xffff0000, v157
	s_waitcnt lgkmcnt(0)
	v_pk_mul_f32 v[94:95], v[94:95], v[100:101] op_sel_hi:[1,0]
	v_pk_mul_f32 v[92:93], v[92:93], v[100:101] op_sel_hi:[1,0]
	v_lshlrev_b32_e32 v114, 16, v158
	v_and_b32_e32 v115, 0xffff0000, v158
	v_lshlrev_b32_e32 v116, 16, v159
	v_and_b32_e32 v117, 0xffff0000, v159
	v_pk_fma_f32 v[94:95], v[126:127], v[94:95], v[112:113]
	v_pk_fma_f32 v[92:93], v[124:125], v[92:93], v[102:103]
	v_pk_mul_f32 v[90:91], v[90:91], v[100:101] op_sel_hi:[1,0]
	v_pk_mul_f32 v[88:89], v[88:89], v[100:101] op_sel_hi:[1,0]
	v_pk_fma_f32 v[102:103], v[122:123], v[90:91], v[116:117]
	v_pk_fma_f32 v[90:91], v[120:121], v[88:89], v[114:115]
	v_mul_f32_e32 v88, v93, v93
	v_mul_f32_e32 v89, v95, v95
	v_fmac_f32_e32 v88, v92, v92
	v_fmac_f32_e32 v89, v94, v94
	v_add_f32_e32 v88, v88, v89
	v_mul_f32_e32 v89, v91, v91
	v_mul_f32_e32 v97, v103, v103
	v_fmac_f32_e32 v89, v90, v90
	v_fmac_f32_e32 v97, v102, v102
	v_add_f32_e32 v89, v89, v97
	v_add_f32_e32 v97, v88, v89
	v_cvt_pk_bf16_f32 v88, v92, v93
	v_cvt_pk_bf16_f32 v89, v94, v95
	v_lshlrev_b32_e32 v92, 16, v152
	v_and_b32_e32 v93, 0xffff0000, v152
	v_lshlrev_b32_e32 v94, 16, v153
	v_and_b32_e32 v95, 0xffff0000, v153
	v_pk_mul_f32 v[86:87], v[86:87], v[100:101] op_sel_hi:[1,0]
	v_pk_mul_f32 v[84:85], v[84:85], v[100:101] op_sel_hi:[1,0]
	v_lshlrev_b32_e32 v112, 16, v154
	v_and_b32_e32 v113, 0xffff0000, v154
	v_pk_fma_f32 v[86:87], v[110:111], v[86:87], v[94:95]
	v_pk_fma_f32 v[84:85], v[108:109], v[84:85], v[92:93]
	v_pk_mul_f32 v[80:81], v[80:81], v[100:101] op_sel_hi:[1,0]
	v_lshlrev_b32_e32 v114, 16, v155
	v_and_b32_e32 v115, 0xffff0000, v155
	v_pk_mul_f32 v[82:83], v[82:83], v[100:101] op_sel_hi:[1,0]
	v_pk_fma_f32 v[94:95], v[104:105], v[80:81], v[112:113]
	v_mul_f32_e32 v80, v85, v85
	v_mul_f32_e32 v81, v87, v87
	v_pk_fma_f32 v[92:93], v[106:107], v[82:83], v[114:115]
	v_fmac_f32_e32 v80, v84, v84
	v_fmac_f32_e32 v81, v86, v86
	v_add_f32_e32 v80, v80, v81
	v_mul_f32_e32 v81, v95, v95
	v_mul_f32_e32 v82, v93, v93
	v_fmac_f32_e32 v81, v94, v94
	v_fmac_f32_e32 v82, v92, v92
	v_add_f32_e32 v81, v81, v82
	v_add_f32_e32 v80, v80, v81
	v_add_f32_e32 v80, v97, v80
	ds_bpermute_b32 v81, v229, v80
	v_add_u32_e32 v96, 32, v207
	v_add_u32_e32 v98, s51, v96
	v_ashrrev_i32_e32 v99, 31, v98
	v_lshlrev_b64 v[98:99], 11, v[98:99]
	s_waitcnt lgkmcnt(0)
	v_add_f32_e32 v80, v80, v81
	ds_bpermute_b32 v81, v230, v80
	v_lshl_add_u64 v[98:99], v[204:205], 0, v[98:99]
	v_cvt_pk_bf16_f32 v90, v90, v91
	v_cvt_pk_bf16_f32 v91, v102, v103
	global_store_dwordx4 v[98:99], v[88:91], off
	v_cvt_pk_bf16_f32 v82, v84, v85
	v_cvt_pk_bf16_f32 v83, v86, v87
	v_cvt_pk_bf16_f32 v84, v94, v95
	v_cvt_pk_bf16_f32 v85, v92, v93
	global_store_dwordx4 v[98:99], v[82:85], off offset:256
	s_and_saveexec_b64 s[10:11], vcc
	s_cbranch_execz .LBB0_548
	s_waitcnt lgkmcnt(0)
	v_add_f32_e32 v80, v80, v81
	v_lshl_add_u32 v81, v96, 4, s39
	ds_write_b32 v81, v80
.LBB0_548:
	s_or_b64 exec, exec, s[10:11]
	ds_read_b32 v84, v206 offset:192
	v_lshlrev_b32_e32 v86, 16, v148
	v_and_b32_e32 v87, 0xffff0000, v148
	v_lshlrev_b32_e32 v88, 16, v149
	v_and_b32_e32 v89, 0xffff0000, v149
	s_waitcnt lgkmcnt(0)
	v_pk_mul_f32 v[78:79], v[78:79], v[84:85] op_sel_hi:[1,0]
	v_pk_mul_f32 v[76:77], v[76:77], v[84:85] op_sel_hi:[1,0]
	v_lshlrev_b32_e32 v90, 16, v150
	v_and_b32_e32 v91, 0xffff0000, v150
	v_lshlrev_b32_e32 v92, 16, v151
	v_and_b32_e32 v93, 0xffff0000, v151
	v_pk_fma_f32 v[78:79], v[126:127], v[78:79], v[88:89]
	v_pk_fma_f32 v[76:77], v[124:125], v[76:77], v[86:87]
	v_pk_mul_f32 v[74:75], v[74:75], v[84:85] op_sel_hi:[1,0]
	v_pk_mul_f32 v[72:73], v[72:73], v[84:85] op_sel_hi:[1,0]
	v_pk_fma_f32 v[86:87], v[122:123], v[74:75], v[92:93]
	v_pk_fma_f32 v[74:75], v[120:121], v[72:73], v[90:91]
	v_mul_f32_e32 v72, v77, v77
	v_mul_f32_e32 v73, v79, v79
	v_fmac_f32_e32 v72, v76, v76
	v_fmac_f32_e32 v73, v78, v78
	v_add_f32_e32 v72, v72, v73
	v_mul_f32_e32 v73, v75, v75
	v_mul_f32_e32 v81, v87, v87
	v_fmac_f32_e32 v73, v74, v74
	v_fmac_f32_e32 v81, v86, v86
	v_add_f32_e32 v73, v73, v81
	v_add_f32_e32 v81, v72, v73
	v_cvt_pk_bf16_f32 v72, v76, v77
	v_cvt_pk_bf16_f32 v73, v78, v79
	v_lshlrev_b32_e32 v76, 16, v144
	v_and_b32_e32 v77, 0xffff0000, v144
	v_lshlrev_b32_e32 v78, 16, v145
	v_and_b32_e32 v79, 0xffff0000, v145
	v_pk_mul_f32 v[70:71], v[70:71], v[84:85] op_sel_hi:[1,0]
	v_pk_mul_f32 v[68:69], v[68:69], v[84:85] op_sel_hi:[1,0]
	v_lshlrev_b32_e32 v88, 16, v146
	v_and_b32_e32 v89, 0xffff0000, v146
	v_pk_fma_f32 v[70:71], v[110:111], v[70:71], v[78:79]
	v_pk_fma_f32 v[68:69], v[108:109], v[68:69], v[76:77]
	v_pk_mul_f32 v[64:65], v[64:65], v[84:85] op_sel_hi:[1,0]
	v_lshlrev_b32_e32 v90, 16, v147
	v_and_b32_e32 v91, 0xffff0000, v147
	v_pk_mul_f32 v[66:67], v[66:67], v[84:85] op_sel_hi:[1,0]
	v_pk_fma_f32 v[78:79], v[104:105], v[64:65], v[88:89]
	v_mul_f32_e32 v64, v69, v69
	v_mul_f32_e32 v65, v71, v71
	v_pk_fma_f32 v[76:77], v[106:107], v[66:67], v[90:91]
	v_fmac_f32_e32 v64, v68, v68
	v_fmac_f32_e32 v65, v70, v70
	v_add_f32_e32 v64, v64, v65
	v_mul_f32_e32 v65, v79, v79
	v_mul_f32_e32 v66, v77, v77
	v_fmac_f32_e32 v65, v78, v78
	v_fmac_f32_e32 v66, v76, v76
	v_add_f32_e32 v65, v65, v66
	v_add_f32_e32 v64, v64, v65
	v_add_f32_e32 v64, v81, v64
	ds_bpermute_b32 v65, v229, v64
	v_add_u32_e32 v80, 48, v207
	v_add_u32_e32 v82, s51, v80
	v_ashrrev_i32_e32 v83, 31, v82
	v_lshlrev_b64 v[82:83], 11, v[82:83]
	s_waitcnt lgkmcnt(0)
	v_add_f32_e32 v64, v64, v65
	ds_bpermute_b32 v65, v230, v64
	v_lshl_add_u64 v[82:83], v[204:205], 0, v[82:83]
	v_cvt_pk_bf16_f32 v74, v74, v75
	v_cvt_pk_bf16_f32 v75, v86, v87
	global_store_dwordx4 v[82:83], v[72:75], off
	v_cvt_pk_bf16_f32 v66, v68, v69
	v_cvt_pk_bf16_f32 v67, v70, v71
	v_cvt_pk_bf16_f32 v68, v78, v79
	v_cvt_pk_bf16_f32 v69, v76, v77
	global_store_dwordx4 v[82:83], v[66:69], off offset:256
	s_and_saveexec_b64 s[10:11], vcc
	s_cbranch_execz .LBB0_550
	s_waitcnt lgkmcnt(0)
	v_add_f32_e32 v64, v64, v65
	v_lshl_add_u32 v65, v80, 4, s39
	ds_write_b32 v65, v64
.LBB0_550:
	s_or_b64 exec, exec, s[10:11]
	v_add_u32_e32 v64, 0x80, v207
	v_add_u32_e32 v66, s51, v64
	v_ashrrev_i32_e32 v67, 31, v66
	v_lshlrev_b64 v[66:67], 11, v[66:67]
	v_lshl_add_u64 v[70:71], v[204:205], 0, v[66:67]
	ds_read_b32 v72, v206 offset:512
	s_waitcnt lgkmcnt(0)
	v_pk_mul_f32 v[62:63], v[62:63], v[72:73] op_sel_hi:[1,0]
	v_pk_mul_f32 v[60:61], v[60:61], v[72:73] op_sel_hi:[1,0]
	v_pk_mul_f32 v[58:59], v[58:59], v[72:73] op_sel_hi:[1,0]
	v_pk_mul_f32 v[56:57], v[56:57], v[72:73] op_sel_hi:[1,0]
	v_pk_mul_f32 v[54:55], v[54:55], v[72:73] op_sel_hi:[1,0]
	v_pk_mul_f32 v[52:53], v[52:53], v[72:73] op_sel_hi:[1,0]
	v_pk_mul_f32 v[50:51], v[50:51], v[72:73] op_sel_hi:[1,0]
	v_pk_mul_f32 v[48:49], v[48:49], v[72:73] op_sel_hi:[1,0]
	v_lshlrev_b32_e32 v74, 16, v236
	v_and_b32_e32 v75, 0xffff0000, v236
	v_lshlrev_b32_e32 v66, 16, v237
	v_and_b32_e32 v67, 0xffff0000, v237
	v_lshlrev_b32_e32 v76, 16, v238
	v_and_b32_e32 v77, 0xffff0000, v238
	v_lshlrev_b32_e32 v68, 16, v239
	v_and_b32_e32 v69, 0xffff0000, v239
	v_pk_fma_f32 v[66:67], v[126:127], v[62:63], v[66:67]
	v_pk_fma_f32 v[74:75], v[124:125], v[60:61], v[74:75]
	v_pk_fma_f32 v[68:69], v[122:123], v[58:59], v[68:69]
	v_pk_fma_f32 v[76:77], v[120:121], v[56:57], v[76:77]
	v_cvt_pk_bf16_f32 v56, v74, v75
	v_cvt_pk_bf16_f32 v57, v66, v67
	v_mul_f32_e32 v65, v75, v75
	v_cvt_pk_bf16_f32 v58, v76, v77
	v_cvt_pk_bf16_f32 v59, v68, v69
	v_mul_f32_e32 v67, v67, v67
	v_mul_f32_e32 v72, v77, v77
	v_mul_f32_e32 v69, v69, v69
	v_fmac_f32_e32 v65, v74, v74
	v_fmac_f32_e32 v67, v66, v66
	v_fmac_f32_e32 v72, v76, v76
	v_fmac_f32_e32 v69, v68, v68
	v_add_f32_e32 v65, v65, v67
	v_add_f32_e32 v66, v72, v69
	v_add_f32_e32 v65, v65, v66
	global_store_dwordx4 v[70:71], v[56:59], off
	v_lshlrev_b32_e32 v66, 16, v240
	v_and_b32_e32 v67, 0xffff0000, v240
	v_lshlrev_b32_e32 v60, 16, v241
	v_and_b32_e32 v61, 0xffff0000, v241
	v_lshlrev_b32_e32 v68, 16, v242
	v_and_b32_e32 v69, 0xffff0000, v242
	v_lshlrev_b32_e32 v62, 16, v243
	v_and_b32_e32 v63, 0xffff0000, v243
	v_pk_fma_f32 v[54:55], v[110:111], v[54:55], v[60:61]
	v_pk_fma_f32 v[52:53], v[108:109], v[52:53], v[66:67]
	v_pk_fma_f32 v[60:61], v[106:107], v[50:51], v[62:63]
	v_pk_fma_f32 v[62:63], v[104:105], v[48:49], v[68:69]
	v_mul_f32_e32 v48, v53, v53
	v_mul_f32_e32 v49, v55, v55
	v_mul_f32_e32 v50, v63, v63
	v_mul_f32_e32 v51, v61, v61
	v_fmac_f32_e32 v48, v52, v52
	v_fmac_f32_e32 v49, v54, v54
	v_fmac_f32_e32 v50, v62, v62
	v_fmac_f32_e32 v51, v60, v60
	v_add_f32_e32 v48, v48, v49
	v_add_f32_e32 v49, v50, v51
	v_add_f32_e32 v48, v48, v49
	v_add_f32_e32 v48, v65, v48
	ds_bpermute_b32 v49, v229, v48
	v_cvt_pk_bf16_f32 v50, v52, v53
	v_cvt_pk_bf16_f32 v51, v54, v55
	v_cvt_pk_bf16_f32 v52, v62, v63
	v_cvt_pk_bf16_f32 v53, v60, v61
	s_waitcnt lgkmcnt(0)
	v_add_f32_e32 v48, v48, v49
	ds_bpermute_b32 v49, v230, v48
	global_store_dwordx4 v[70:71], v[50:53], off offset:256
	s_and_saveexec_b64 s[10:11], vcc
	s_cbranch_execz .LBB0_552
	s_waitcnt lgkmcnt(0)
	v_add_f32_e32 v48, v48, v49
	v_lshl_add_u32 v49, v64, 4, s39
	ds_write_b32 v49, v48
.LBB0_552:
	s_or_b64 exec, exec, s[10:11]
	v_add_u32_e32 v48, 0x90, v207
	v_add_u32_e32 v50, s51, v48
	v_ashrrev_i32_e32 v51, 31, v50
	v_lshlrev_b64 v[50:51], 11, v[50:51]
	v_lshl_add_u64 v[54:55], v[204:205], 0, v[50:51]
	ds_read_b32 v56, v206 offset:576
	s_waitcnt lgkmcnt(0)
	v_pk_mul_f32 v[46:47], v[46:47], v[56:57] op_sel_hi:[1,0]
	v_pk_mul_f32 v[44:45], v[44:45], v[56:57] op_sel_hi:[1,0]
	v_pk_mul_f32 v[42:43], v[42:43], v[56:57] op_sel_hi:[1,0]
	v_pk_mul_f32 v[40:41], v[40:41], v[56:57] op_sel_hi:[1,0]
	v_pk_mul_f32 v[38:39], v[38:39], v[56:57] op_sel_hi:[1,0]
	v_pk_mul_f32 v[36:37], v[36:37], v[56:57] op_sel_hi:[1,0]
	v_pk_mul_f32 v[34:35], v[34:35], v[56:57] op_sel_hi:[1,0]
	v_pk_mul_f32 v[32:33], v[32:33], v[56:57] op_sel_hi:[1,0]
	v_lshlrev_b32_e32 v58, 16, v244
	v_and_b32_e32 v59, 0xffff0000, v244
	v_lshlrev_b32_e32 v50, 16, v245
	v_and_b32_e32 v51, 0xffff0000, v245
	v_lshlrev_b32_e32 v60, 16, v246
	v_and_b32_e32 v61, 0xffff0000, v246
	v_lshlrev_b32_e32 v52, 16, v247
	v_and_b32_e32 v53, 0xffff0000, v247
	v_pk_fma_f32 v[50:51], v[126:127], v[46:47], v[50:51]
	v_pk_fma_f32 v[58:59], v[124:125], v[44:45], v[58:59]
	v_pk_fma_f32 v[52:53], v[122:123], v[42:43], v[52:53]
	v_pk_fma_f32 v[60:61], v[120:121], v[40:41], v[60:61]
	v_cvt_pk_bf16_f32 v40, v58, v59
	v_cvt_pk_bf16_f32 v41, v50, v51
	v_mul_f32_e32 v49, v59, v59
	v_cvt_pk_bf16_f32 v42, v60, v61
	v_cvt_pk_bf16_f32 v43, v52, v53
	v_mul_f32_e32 v51, v51, v51
	v_mul_f32_e32 v56, v61, v61
	v_mul_f32_e32 v53, v53, v53
	v_fmac_f32_e32 v49, v58, v58
	v_fmac_f32_e32 v51, v50, v50
	v_fmac_f32_e32 v56, v60, v60
	v_fmac_f32_e32 v53, v52, v52
	v_add_f32_e32 v49, v49, v51
	v_add_f32_e32 v50, v56, v53
	v_add_f32_e32 v49, v49, v50
	global_store_dwordx4 v[54:55], v[40:43], off
	v_lshlrev_b32_e32 v50, 16, v248
	v_and_b32_e32 v51, 0xffff0000, v248
	v_lshlrev_b32_e32 v44, 16, v249
	v_and_b32_e32 v45, 0xffff0000, v249
	v_lshlrev_b32_e32 v52, 16, v250
	v_and_b32_e32 v53, 0xffff0000, v250
	v_lshlrev_b32_e32 v46, 16, v251
	v_and_b32_e32 v47, 0xffff0000, v251
	v_pk_fma_f32 v[38:39], v[110:111], v[38:39], v[44:45]
	v_pk_fma_f32 v[36:37], v[108:109], v[36:37], v[50:51]
	v_pk_fma_f32 v[44:45], v[106:107], v[34:35], v[46:47]
	v_pk_fma_f32 v[46:47], v[104:105], v[32:33], v[52:53]
	v_mul_f32_e32 v32, v37, v37
	v_mul_f32_e32 v33, v39, v39
	v_mul_f32_e32 v34, v47, v47
	v_mul_f32_e32 v35, v45, v45
	v_fmac_f32_e32 v32, v36, v36
	v_fmac_f32_e32 v33, v38, v38
	v_fmac_f32_e32 v34, v46, v46
	v_fmac_f32_e32 v35, v44, v44
	v_add_f32_e32 v32, v32, v33
	v_add_f32_e32 v33, v34, v35
	v_add_f32_e32 v32, v32, v33
	v_add_f32_e32 v32, v49, v32
	ds_bpermute_b32 v33, v229, v32
	v_cvt_pk_bf16_f32 v34, v36, v37
	v_cvt_pk_bf16_f32 v35, v38, v39
	v_cvt_pk_bf16_f32 v36, v46, v47
	v_cvt_pk_bf16_f32 v37, v44, v45
	s_waitcnt lgkmcnt(0)
	v_add_f32_e32 v32, v32, v33
	ds_bpermute_b32 v33, v230, v32
	global_store_dwordx4 v[54:55], v[34:37], off offset:256
	s_and_saveexec_b64 s[10:11], vcc
	s_cbranch_execz .LBB0_554
	s_waitcnt lgkmcnt(0)
	v_add_f32_e32 v32, v32, v33
	v_lshl_add_u32 v33, v48, 4, s39
	ds_write_b32 v33, v32
.LBB0_554:
	s_or_b64 exec, exec, s[10:11]
	v_add_u32_e32 v32, 0xa0, v207
	v_add_u32_e32 v34, s51, v32
	v_ashrrev_i32_e32 v35, 31, v34
	v_lshlrev_b64 v[34:35], 11, v[34:35]
	v_lshl_add_u64 v[38:39], v[204:205], 0, v[34:35]
	ds_read_b32 v40, v206 offset:640
	s_waitcnt lgkmcnt(0)
	v_pk_mul_f32 v[30:31], v[30:31], v[40:41] op_sel_hi:[1,0]
	v_pk_mul_f32 v[28:29], v[28:29], v[40:41] op_sel_hi:[1,0]
	v_pk_mul_f32 v[26:27], v[26:27], v[40:41] op_sel_hi:[1,0]
	v_pk_mul_f32 v[24:25], v[24:25], v[40:41] op_sel_hi:[1,0]
	v_pk_mul_f32 v[22:23], v[22:23], v[40:41] op_sel_hi:[1,0]
	v_pk_mul_f32 v[20:21], v[20:21], v[40:41] op_sel_hi:[1,0]
	v_pk_mul_f32 v[18:19], v[18:19], v[40:41] op_sel_hi:[1,0]
	v_pk_mul_f32 v[16:17], v[16:17], v[40:41] op_sel_hi:[1,0]
	s_waitcnt vmcnt(13)
	v_lshlrev_b32_e32 v42, 16, v168
	v_and_b32_e32 v43, 0xffff0000, v168
	v_lshlrev_b32_e32 v34, 16, v169
	v_and_b32_e32 v35, 0xffff0000, v169
	v_lshlrev_b32_e32 v44, 16, v170
	v_and_b32_e32 v45, 0xffff0000, v170
	v_lshlrev_b32_e32 v36, 16, v171
	v_and_b32_e32 v37, 0xffff0000, v171
	v_pk_fma_f32 v[34:35], v[126:127], v[30:31], v[34:35]
	v_pk_fma_f32 v[42:43], v[124:125], v[28:29], v[42:43]
	v_pk_fma_f32 v[36:37], v[122:123], v[26:27], v[36:37]
	v_pk_fma_f32 v[44:45], v[120:121], v[24:25], v[44:45]
	v_cvt_pk_bf16_f32 v24, v42, v43
	v_cvt_pk_bf16_f32 v25, v34, v35
	v_mul_f32_e32 v33, v43, v43
	v_cvt_pk_bf16_f32 v26, v44, v45
	v_cvt_pk_bf16_f32 v27, v36, v37
	v_mul_f32_e32 v35, v35, v35
	v_mul_f32_e32 v40, v45, v45
	v_mul_f32_e32 v37, v37, v37
	v_fmac_f32_e32 v33, v42, v42
	v_fmac_f32_e32 v35, v34, v34
	v_fmac_f32_e32 v40, v44, v44
	v_fmac_f32_e32 v37, v36, v36
	v_add_f32_e32 v33, v33, v35
	v_add_f32_e32 v34, v40, v37
	v_add_f32_e32 v33, v33, v34
	global_store_dwordx4 v[38:39], v[24:27], off
	s_waitcnt vmcnt(13)
	v_lshlrev_b32_e32 v34, 16, v172
	v_and_b32_e32 v35, 0xffff0000, v172
	v_lshlrev_b32_e32 v28, 16, v173
	v_and_b32_e32 v29, 0xffff0000, v173
	v_lshlrev_b32_e32 v36, 16, v174
	v_and_b32_e32 v37, 0xffff0000, v174
	v_lshlrev_b32_e32 v30, 16, v175
	v_and_b32_e32 v31, 0xffff0000, v175
	v_pk_fma_f32 v[22:23], v[110:111], v[22:23], v[28:29]
	v_pk_fma_f32 v[20:21], v[108:109], v[20:21], v[34:35]
	v_pk_fma_f32 v[28:29], v[106:107], v[18:19], v[30:31]
	v_pk_fma_f32 v[30:31], v[104:105], v[16:17], v[36:37]
	v_mul_f32_e32 v16, v21, v21
	v_mul_f32_e32 v17, v23, v23
	v_mul_f32_e32 v18, v31, v31
	v_mul_f32_e32 v19, v29, v29
	v_fmac_f32_e32 v16, v20, v20
	v_fmac_f32_e32 v17, v22, v22
	v_fmac_f32_e32 v18, v30, v30
	v_fmac_f32_e32 v19, v28, v28
	v_add_f32_e32 v16, v16, v17
	v_add_f32_e32 v17, v18, v19
	v_add_f32_e32 v16, v16, v17
	v_add_f32_e32 v16, v33, v16
	ds_bpermute_b32 v17, v229, v16
	v_cvt_pk_bf16_f32 v18, v20, v21
	v_cvt_pk_bf16_f32 v19, v22, v23
	v_cvt_pk_bf16_f32 v20, v30, v31
	v_cvt_pk_bf16_f32 v21, v28, v29
	s_waitcnt lgkmcnt(0)
	v_add_f32_e32 v16, v16, v17
	ds_bpermute_b32 v17, v230, v16
	global_store_dwordx4 v[38:39], v[18:21], off offset:256
	s_and_saveexec_b64 s[10:11], vcc
	s_cbranch_execz .LBB0_556
	s_waitcnt lgkmcnt(0)
	v_add_f32_e32 v16, v16, v17
	v_lshl_add_u32 v17, v32, 4, s39
	ds_write_b32 v17, v16
.LBB0_556:
	s_or_b64 exec, exec, s[10:11]
	v_add_u32_e32 v16, 0xb0, v207
	v_add_u32_e32 v18, s51, v16
	v_ashrrev_i32_e32 v19, 31, v18
	v_lshlrev_b64 v[18:19], 11, v[18:19]
	v_lshl_add_u64 v[22:23], v[204:205], 0, v[18:19]
	ds_read_b32 v24, v206 offset:704
	s_waitcnt lgkmcnt(0)
	v_pk_mul_f32 v[14:15], v[14:15], v[24:25] op_sel_hi:[1,0]
	v_pk_mul_f32 v[12:13], v[12:13], v[24:25] op_sel_hi:[1,0]
	v_pk_mul_f32 v[10:11], v[10:11], v[24:25] op_sel_hi:[1,0]
	v_pk_mul_f32 v[8:9], v[8:9], v[24:25] op_sel_hi:[1,0]
	v_pk_mul_f32 v[6:7], v[6:7], v[24:25] op_sel_hi:[1,0]
	v_pk_mul_f32 v[4:5], v[4:5], v[24:25] op_sel_hi:[1,0]
	v_pk_mul_f32 v[2:3], v[2:3], v[24:25] op_sel_hi:[1,0]
	v_pk_mul_f32 v[0:1], v[0:1], v[24:25] op_sel_hi:[1,0]
	s_waitcnt vmcnt(13)
	v_lshlrev_b32_e32 v26, 16, v208
	v_and_b32_e32 v27, 0xffff0000, v208
	v_lshlrev_b32_e32 v18, 16, v209
	v_and_b32_e32 v19, 0xffff0000, v209
	v_lshlrev_b32_e32 v28, 16, v210
	v_and_b32_e32 v29, 0xffff0000, v210
	v_lshlrev_b32_e32 v20, 16, v211
	v_and_b32_e32 v21, 0xffff0000, v211
	v_pk_fma_f32 v[18:19], v[126:127], v[14:15], v[18:19]
	v_pk_fma_f32 v[26:27], v[124:125], v[12:13], v[26:27]
	v_pk_fma_f32 v[20:21], v[122:123], v[10:11], v[20:21]
	v_pk_fma_f32 v[28:29], v[120:121], v[8:9], v[28:29]
	v_cvt_pk_bf16_f32 v8, v26, v27
	v_cvt_pk_bf16_f32 v9, v18, v19
	v_mul_f32_e32 v17, v27, v27
	v_cvt_pk_bf16_f32 v10, v28, v29
	v_cvt_pk_bf16_f32 v11, v20, v21
	v_mul_f32_e32 v19, v19, v19
	v_mul_f32_e32 v24, v29, v29
	v_mul_f32_e32 v21, v21, v21
	v_fmac_f32_e32 v17, v26, v26
	v_fmac_f32_e32 v19, v18, v18
	v_fmac_f32_e32 v24, v28, v28
	v_fmac_f32_e32 v21, v20, v20
	v_add_f32_e32 v17, v17, v19
	v_add_f32_e32 v18, v24, v21
	v_add_f32_e32 v17, v17, v18
	global_store_dwordx4 v[22:23], v[8:11], off
	s_waitcnt vmcnt(13)
	v_lshlrev_b32_e32 v18, 16, v212
	v_and_b32_e32 v19, 0xffff0000, v212
	v_lshlrev_b32_e32 v12, 16, v213
	v_and_b32_e32 v13, 0xffff0000, v213
	v_lshlrev_b32_e32 v20, 16, v214
	v_and_b32_e32 v21, 0xffff0000, v214
	v_lshlrev_b32_e32 v14, 16, v215
	v_and_b32_e32 v15, 0xffff0000, v215
	v_pk_fma_f32 v[6:7], v[110:111], v[6:7], v[12:13]
	v_pk_fma_f32 v[4:5], v[108:109], v[4:5], v[18:19]
	v_pk_fma_f32 v[12:13], v[106:107], v[2:3], v[14:15]
	v_pk_fma_f32 v[14:15], v[104:105], v[0:1], v[20:21]
	v_mul_f32_e32 v0, v5, v5
	v_mul_f32_e32 v1, v7, v7
	v_mul_f32_e32 v2, v15, v15
	v_mul_f32_e32 v3, v13, v13
	v_fmac_f32_e32 v0, v4, v4
	v_fmac_f32_e32 v1, v6, v6
	v_fmac_f32_e32 v2, v14, v14
	v_fmac_f32_e32 v3, v12, v12
	v_add_f32_e32 v0, v0, v1
	v_add_f32_e32 v1, v2, v3
	v_add_f32_e32 v0, v0, v1
	v_add_f32_e32 v0, v17, v0
	ds_bpermute_b32 v1, v229, v0
	v_cvt_pk_bf16_f32 v2, v4, v5
	v_cvt_pk_bf16_f32 v3, v6, v7
	v_cvt_pk_bf16_f32 v4, v14, v15
	v_cvt_pk_bf16_f32 v5, v12, v13
	s_waitcnt lgkmcnt(0)
	v_add_f32_e32 v0, v0, v1
	ds_bpermute_b32 v1, v230, v0
	global_store_dwordx4 v[22:23], v[2:5], off offset:256
	s_and_saveexec_b64 s[10:11], vcc
	s_cbranch_execz .LBB0_558
	s_waitcnt lgkmcnt(0)
	v_add_f32_e32 v0, v0, v1
	v_lshl_add_u32 v1, v16, 4, s39
	ds_write_b32 v1, v0

.LBB0_715:
	s_or_b64 exec, exec, s[10:11]
	s_lshl_b32 s10, s14, 8
	s_lshl_b32 s11, s13, 5
	s_add_i32 s11, s11, s10
	s_lshl_b32 s80, s12, 8
	s_lshl_b32 s81, s15, 6
	v_lshl_add_u32 v144, v206, 3, s11
	s_add_i32 s10, s81, s80
	v_ashrrev_i32_e32 v145, 31, v144
	v_add_u32_e32 v146, s10, v233
	s_waitcnt vmcnt(0)
	v_lshl_add_u64 v[108:109], v[144:145], 2, v[104:105]
	v_lshl_add_u64 v[144:145], v[144:145], 1, v[202:203]
	v_ashrrev_i32_e32 v147, 31, v146
	v_lshl_add_u64 v[204:205], v[144:145], 0, s[34:35]
	v_lshlrev_b64 v[144:145], 11, v[146:147]
	s_waitcnt lgkmcnt(0)
	s_barrier
	v_lshl_add_u64 v[144:145], v[204:205], 0, v[144:145]
	global_load_dwordx4 v[120:123], v[108:109], off offset:16
	global_load_dwordx4 v[124:127], v[108:109], off
	s_waitcnt lgkmcnt(0)
	global_load_dwordx4 v[104:107], v[108:109], off offset:528
	s_nop 0
	global_load_dwordx4 v[108:111], v[108:109], off offset:512
	s_nop 0
	global_load_dwordx4 v[172:175], v[144:145], off
	global_load_dwordx4 v[168:171], v[144:145], off offset:256
	v_add_u32_e32 v144, 16, v146
	v_ashrrev_i32_e32 v145, 31, v144
	v_lshlrev_b64 v[144:145], 11, v[144:145]
	v_lshl_add_u64 v[144:145], v[204:205], 0, v[144:145]
	global_load_dwordx4 v[164:167], v[144:145], off
	global_load_dwordx4 v[160:163], v[144:145], off offset:256
	v_add_u32_e32 v144, 32, v146
	v_ashrrev_i32_e32 v145, 31, v144
	v_lshlrev_b64 v[144:145], 11, v[144:145]
	v_lshl_add_u64 v[144:145], v[204:205], 0, v[144:145]
	global_load_dwordx4 v[156:159], v[144:145], off
	global_load_dwordx4 v[152:155], v[144:145], off offset:256
	v_add_u32_e32 v144, 0x80, v146
	v_ashrrev_i32_e32 v145, 31, v144
	v_lshlrev_b64 v[144:145], 11, v[144:145]
	v_lshl_add_u64 v[144:145], v[204:205], 0, v[144:145]
	global_load_dwordx4 v[236:239], v[144:145], off
	global_load_dwordx4 v[240:243], v[144:145], off offset:256
	v_add_u32_e32 v144, 0x90, v146
	v_ashrrev_i32_e32 v145, 31, v144
	v_lshlrev_b64 v[144:145], 11, v[144:145]
	v_lshl_add_u64 v[144:145], v[204:205], 0, v[144:145]
	global_load_dwordx4 v[244:247], v[144:145], off
	global_load_dwordx4 v[248:251], v[144:145], off offset:256
	v_add_u32_e32 v144, 48, v146
	v_ashrrev_i32_e32 v145, 31, v144
	v_lshlrev_b64 v[144:145], 11, v[144:145]
	v_lshl_add_u64 v[144:145], v[204:205], 0, v[144:145]
	global_load_dwordx4 v[148:151], v[144:145], off
	s_nop 0
	global_load_dwordx4 v[144:147], v[144:145], off offset:256
	s_lshl_b32 s10, s15, 2
	v_lshl_add_u32 v206, v206, 4, v233
	s_add_i32 s12, s10, s13
	v_cmp_gt_i32_e64 s[10:11], 32, v206
	v_lshl_add_u32 v232, s12, 5, v206
	s_and_saveexec_b64 s[38:39], s[10:11]
	s_cbranch_execz .LBB0_730
	v_lshl_add_u32 v206, v232, 4, v228
	ds_read_b128 v[208:211], v206
	v_add_u32_e32 v206, s80, v232
	v_ashrrev_i32_e32 v207, 31, v206
	v_lshlrev_b64 v[206:207], 5, v[206:207]
	v_lshl_add_u64 v[206:207], v[202:203], 0, v[206:207]
	s_waitcnt lgkmcnt(0)
	v_mov_b32_e32 v214, v209
	v_mov_b32_e32 v215, v210
	v_mov_b32_e32 v209, v211
	v_pk_add_f32 v[208:209], v[214:215], v[208:209]
	v_lshl_add_u64 v[206:207], v[206:207], 0, s[36:37]
	s_ashr_i32 s15, s14, 31
	v_pk_add_f32 v[208:209], v[208:209], v[208:209] op_sel:[0,1] op_sel_hi:[1,0]
	v_lshl_add_u64 v[212:213], s[14:15], 3, v[206:207]
	v_mov_b32_e32 v209, v217
	s_mov_b32 s15, 0x100000
	s_mov_b64 s[40:41], 0
	global_store_dwordx2 v[212:213], v[208:209], off sc1
	s_branch .LBB0_722

.LBB0_730:
	s_or_b64 exec, exec, s[38:39]
	v_add_u32_e32 v207, s81, v233
	s_waitcnt vmcnt(0) lgkmcnt(0)
	s_barrier
	v_lshl_add_u32 v206, v207, 2, v229
	ds_read_b32 v210, v206
	v_lshlrev_b32_e32 v212, 16, v172
	v_and_b32_e32 v213, 0xffff0000, v172
	v_lshlrev_b32_e32 v172, 16, v173
	v_and_b32_e32 v173, 0xffff0000, v173
	s_waitcnt lgkmcnt(0)
	v_pk_mul_f32 v[142:143], v[142:143], v[210:211] op_sel_hi:[1,0]
	v_pk_mul_f32 v[140:141], v[140:141], v[210:211] op_sel_hi:[1,0]
	v_lshlrev_b32_e32 v214, 16, v174
	v_and_b32_e32 v215, 0xffff0000, v174
	v_lshlrev_b32_e32 v174, 16, v175
	v_and_b32_e32 v175, 0xffff0000, v175
	v_pk_fma_f32 v[142:143], v[126:127], v[142:143], v[172:173]
	v_pk_fma_f32 v[140:141], v[124:125], v[140:141], v[212:213]
	v_pk_mul_f32 v[138:139], v[138:139], v[210:211] op_sel_hi:[1,0]
	v_pk_mul_f32 v[136:137], v[136:137], v[210:211] op_sel_hi:[1,0]
	v_pk_fma_f32 v[172:173], v[122:123], v[138:139], v[174:175]
	v_pk_fma_f32 v[138:139], v[120:121], v[136:137], v[214:215]
	v_mul_f32_e32 v136, v141, v141
	v_mul_f32_e32 v137, v143, v143
	v_fmac_f32_e32 v136, v140, v140
	v_fmac_f32_e32 v137, v142, v142
	v_add_f32_e32 v136, v136, v137
	v_mul_f32_e32 v137, v139, v139
	v_mul_f32_e32 v174, v173, v173
	v_fmac_f32_e32 v137, v138, v138
	v_fmac_f32_e32 v174, v172, v172
	v_add_f32_e32 v137, v137, v174
	v_add_f32_e32 v174, v136, v137
	v_cvt_pk_bf16_f32 v136, v140, v141
	v_cvt_pk_bf16_f32 v137, v142, v143
	v_lshlrev_b32_e32 v140, 16, v168
	v_and_b32_e32 v141, 0xffff0000, v168
	v_lshlrev_b32_e32 v142, 16, v169
	v_and_b32_e32 v143, 0xffff0000, v169
	v_pk_mul_f32 v[134:135], v[134:135], v[210:211] op_sel_hi:[1,0]
	v_pk_mul_f32 v[132:133], v[132:133], v[210:211] op_sel_hi:[1,0]
	v_lshlrev_b32_e32 v168, 16, v170
	v_and_b32_e32 v169, 0xffff0000, v170
	v_pk_fma_f32 v[134:135], v[110:111], v[134:135], v[142:143]
	v_pk_fma_f32 v[132:133], v[108:109], v[132:133], v[140:141]
	v_pk_mul_f32 v[128:129], v[128:129], v[210:211] op_sel_hi:[1,0]
	v_lshlrev_b32_e32 v170, 16, v171
	v_and_b32_e32 v171, 0xffff0000, v171
	v_pk_mul_f32 v[130:131], v[130:131], v[210:211] op_sel_hi:[1,0]
	v_pk_fma_f32 v[142:143], v[104:105], v[128:129], v[168:169]
	v_mul_f32_e32 v128, v133, v133
	v_mul_f32_e32 v129, v135, v135
	v_pk_fma_f32 v[140:141], v[106:107], v[130:131], v[170:171]
	v_fmac_f32_e32 v128, v132, v132
	v_fmac_f32_e32 v129, v134, v134
	v_add_f32_e32 v128, v128, v129
	v_mul_f32_e32 v129, v143, v143
	v_mul_f32_e32 v130, v141, v141
	v_fmac_f32_e32 v129, v142, v142
	v_fmac_f32_e32 v130, v140, v140
	v_add_f32_e32 v129, v129, v130
	v_add_f32_e32 v128, v128, v129
	v_add_f32_e32 v128, v174, v128
	ds_bpermute_b32 v129, v230, v128
	v_add_u32_e32 v208, s80, v207
	v_ashrrev_i32_e32 v209, 31, v208
	v_lshlrev_b64 v[208:209], 11, v[208:209]
	v_lshl_add_u64 v[208:209], v[204:205], 0, v[208:209]
	s_waitcnt lgkmcnt(0)
	v_add_f32_e32 v128, v128, v129
	ds_bpermute_b32 v129, v231, v128
	v_cvt_pk_bf16_f32 v138, v138, v139
	v_cvt_pk_bf16_f32 v139, v172, v173
	global_store_dwordx4 v[208:209], v[136:139], off
	v_cvt_pk_bf16_f32 v130, v132, v133
	v_cvt_pk_bf16_f32 v131, v134, v135
	v_cvt_pk_bf16_f32 v132, v142, v143
	v_cvt_pk_bf16_f32 v133, v140, v141
	global_store_dwordx4 v[208:209], v[130:133], off offset:256
	s_and_saveexec_b64 s[12:13], vcc
	s_cbranch_execz .LBB0_732
	s_waitcnt lgkmcnt(0)
	v_add_f32_e32 v128, v128, v129
	v_lshl_add_u32 v129, v207, 4, s79
	ds_write_b32 v129, v128
.LBB0_732:
	s_or_b64 exec, exec, s[12:13]
	v_add_u32_e32 v252, 0xa0, v207
	v_add_u32_e32 v252, s80, v252
	v_ashrrev_i32_e32 v253, 31, v252
	v_lshlrev_b64 v[252:253], 11, v[252:253]
	v_lshl_add_u64 v[252:253], v[204:205], 0, v[252:253]
	global_load_dwordx4 v[168:171], v[252:253], off
	global_load_dwordx4 v[172:175], v[252:253], off offset:256
	v_add_u32_e32 v252, 0xb0, v207
	v_add_u32_e32 v252, s80, v252
	v_ashrrev_i32_e32 v253, 31, v252
	v_lshlrev_b64 v[252:253], 11, v[252:253]
	v_lshl_add_u64 v[252:253], v[204:205], 0, v[252:253]
	global_load_dwordx4 v[208:211], v[252:253], off
	global_load_dwordx4 v[212:215], v[252:253], off offset:256
	ds_read_b32 v132, v206 offset:64
	v_lshlrev_b32_e32 v134, 16, v164
	v_and_b32_e32 v135, 0xffff0000, v164
	v_lshlrev_b32_e32 v136, 16, v165
	v_and_b32_e32 v137, 0xffff0000, v165
	s_waitcnt lgkmcnt(0)
	v_pk_mul_f32 v[118:119], v[118:119], v[132:133] op_sel_hi:[1,0]
	v_pk_mul_f32 v[116:117], v[116:117], v[132:133] op_sel_hi:[1,0]
	v_lshlrev_b32_e32 v138, 16, v166
	v_and_b32_e32 v139, 0xffff0000, v166
	v_lshlrev_b32_e32 v140, 16, v167
	v_and_b32_e32 v141, 0xffff0000, v167
	v_pk_fma_f32 v[118:119], v[126:127], v[118:119], v[136:137]
	v_pk_fma_f32 v[116:117], v[124:125], v[116:117], v[134:135]
	v_pk_mul_f32 v[114:115], v[114:115], v[132:133] op_sel_hi:[1,0]
	v_pk_mul_f32 v[112:113], v[112:113], v[132:133] op_sel_hi:[1,0]
	v_pk_fma_f32 v[134:135], v[122:123], v[114:115], v[140:141]
	v_pk_fma_f32 v[114:115], v[120:121], v[112:113], v[138:139]
	v_mul_f32_e32 v112, v117, v117
	v_mul_f32_e32 v113, v119, v119
	v_fmac_f32_e32 v112, v116, v116
	v_fmac_f32_e32 v113, v118, v118
	v_add_f32_e32 v112, v112, v113
	v_mul_f32_e32 v113, v115, v115
	v_mul_f32_e32 v129, v135, v135
	v_fmac_f32_e32 v113, v114, v114
	v_fmac_f32_e32 v129, v134, v134
	v_add_f32_e32 v113, v113, v129
	v_add_f32_e32 v129, v112, v113
	v_cvt_pk_bf16_f32 v112, v116, v117
	v_cvt_pk_bf16_f32 v113, v118, v119
	v_lshlrev_b32_e32 v116, 16, v160
	v_and_b32_e32 v117, 0xffff0000, v160
	v_lshlrev_b32_e32 v118, 16, v161
	v_and_b32_e32 v119, 0xffff0000, v161
	v_pk_mul_f32 v[102:103], v[102:103], v[132:133] op_sel_hi:[1,0]
	v_pk_mul_f32 v[100:101], v[100:101], v[132:133] op_sel_hi:[1,0]
	v_lshlrev_b32_e32 v136, 16, v162
	v_and_b32_e32 v137, 0xffff0000, v162
	v_pk_fma_f32 v[102:103], v[110:111], v[102:103], v[118:119]
	v_pk_fma_f32 v[100:101], v[108:109], v[100:101], v[116:117]
	v_pk_mul_f32 v[96:97], v[96:97], v[132:133] op_sel_hi:[1,0]
	v_lshlrev_b32_e32 v138, 16, v163
	v_and_b32_e32 v139, 0xffff0000, v163
	v_pk_mul_f32 v[98:99], v[98:99], v[132:133] op_sel_hi:[1,0]
	v_pk_fma_f32 v[118:119], v[104:105], v[96:97], v[136:137]
	v_mul_f32_e32 v96, v101, v101
	v_mul_f32_e32 v97, v103, v103
	v_pk_fma_f32 v[116:117], v[106:107], v[98:99], v[138:139]
	v_fmac_f32_e32 v96, v100, v100
	v_fmac_f32_e32 v97, v102, v102
	v_add_f32_e32 v96, v96, v97
	v_mul_f32_e32 v97, v119, v119
	v_mul_f32_e32 v98, v117, v117
	v_fmac_f32_e32 v97, v118, v118
	v_fmac_f32_e32 v98, v116, v116
	v_add_f32_e32 v97, v97, v98
	v_add_f32_e32 v96, v96, v97
	v_add_f32_e32 v96, v129, v96
	ds_bpermute_b32 v97, v230, v96
	v_add_u32_e32 v128, 16, v207
	v_add_u32_e32 v130, s80, v128
	v_ashrrev_i32_e32 v131, 31, v130
	v_lshlrev_b64 v[130:131], 11, v[130:131]
	s_waitcnt lgkmcnt(0)
	v_add_f32_e32 v96, v96, v97
	ds_bpermute_b32 v97, v231, v96
	v_lshl_add_u64 v[130:131], v[204:205], 0, v[130:131]
	v_cvt_pk_bf16_f32 v114, v114, v115
	v_cvt_pk_bf16_f32 v115, v134, v135
	global_store_dwordx4 v[130:131], v[112:115], off
	v_cvt_pk_bf16_f32 v98, v100, v101
	v_cvt_pk_bf16_f32 v99, v102, v103
	v_cvt_pk_bf16_f32 v100, v118, v119
	v_cvt_pk_bf16_f32 v101, v116, v117
	global_store_dwordx4 v[130:131], v[98:101], off offset:256
	s_and_saveexec_b64 s[12:13], vcc
	s_cbranch_execz .LBB0_734
	s_waitcnt lgkmcnt(0)
	v_add_f32_e32 v96, v96, v97
	v_lshl_add_u32 v97, v128, 4, s79
	ds_write_b32 v97, v96
.LBB0_734:
	s_or_b64 exec, exec, s[12:13]
	ds_read_b32 v100, v206 offset:128
	v_lshlrev_b32_e32 v102, 16, v156
	v_and_b32_e32 v103, 0xffff0000, v156
	v_lshlrev_b32_e32 v112, 16, v157
	v_and_b32_e32 v113, 0xffff0000, v157
	s_waitcnt lgkmcnt(0)
	v_pk_mul_f32 v[94:95], v[94:95], v[100:101] op_sel_hi:[1,0]
	v_pk_mul_f32 v[92:93], v[92:93], v[100:101] op_sel_hi:[1,0]
	v_lshlrev_b32_e32 v114, 16, v158
	v_and_b32_e32 v115, 0xffff0000, v158
	v_lshlrev_b32_e32 v116, 16, v159
	v_and_b32_e32 v117, 0xffff0000, v159
	v_pk_fma_f32 v[94:95], v[126:127], v[94:95], v[112:113]
	v_pk_fma_f32 v[92:93], v[124:125], v[92:93], v[102:103]
	v_pk_mul_f32 v[90:91], v[90:91], v[100:101] op_sel_hi:[1,0]
	v_pk_mul_f32 v[88:89], v[88:89], v[100:101] op_sel_hi:[1,0]
	v_pk_fma_f32 v[102:103], v[122:123], v[90:91], v[116:117]
	v_pk_fma_f32 v[90:91], v[120:121], v[88:89], v[114:115]
	v_mul_f32_e32 v88, v93, v93
	v_mul_f32_e32 v89, v95, v95
	v_fmac_f32_e32 v88, v92, v92
	v_fmac_f32_e32 v89, v94, v94
	v_add_f32_e32 v88, v88, v89
	v_mul_f32_e32 v89, v91, v91
	v_mul_f32_e32 v97, v103, v103
	v_fmac_f32_e32 v89, v90, v90
	v_fmac_f32_e32 v97, v102, v102
	v_add_f32_e32 v89, v89, v97
	v_add_f32_e32 v97, v88, v89
	v_cvt_pk_bf16_f32 v88, v92, v93
	v_cvt_pk_bf16_f32 v89, v94, v95
	v_lshlrev_b32_e32 v92, 16, v152
	v_and_b32_e32 v93, 0xffff0000, v152
	v_lshlrev_b32_e32 v94, 16, v153
	v_and_b32_e32 v95, 0xffff0000, v153
	v_pk_mul_f32 v[86:87], v[86:87], v[100:101] op_sel_hi:[1,0]
	v_pk_mul_f32 v[84:85], v[84:85], v[100:101] op_sel_hi:[1,0]
	v_lshlrev_b32_e32 v112, 16, v154
	v_and_b32_e32 v113, 0xffff0000, v154
	v_pk_fma_f32 v[86:87], v[110:111], v[86:87], v[94:95]
	v_pk_fma_f32 v[84:85], v[108:109], v[84:85], v[92:93]
	v_pk_mul_f32 v[80:81], v[80:81], v[100:101] op_sel_hi:[1,0]
	v_lshlrev_b32_e32 v114, 16, v155
	v_and_b32_e32 v115, 0xffff0000, v155
	v_pk_mul_f32 v[82:83], v[82:83], v[100:101] op_sel_hi:[1,0]
	v_pk_fma_f32 v[94:95], v[104:105], v[80:81], v[112:113]
	v_mul_f32_e32 v80, v85, v85
	v_mul_f32_e32 v81, v87, v87
	v_pk_fma_f32 v[92:93], v[106:107], v[82:83], v[114:115]
	v_fmac_f32_e32 v80, v84, v84
	v_fmac_f32_e32 v81, v86, v86
	v_add_f32_e32 v80, v80, v81
	v_mul_f32_e32 v81, v95, v95
	v_mul_f32_e32 v82, v93, v93
	v_fmac_f32_e32 v81, v94, v94
	v_fmac_f32_e32 v82, v92, v92
	v_add_f32_e32 v81, v81, v82
	v_add_f32_e32 v80, v80, v81
	v_add_f32_e32 v80, v97, v80
	ds_bpermute_b32 v81, v230, v80
	v_add_u32_e32 v96, 32, v207
	v_add_u32_e32 v98, s80, v96
	v_ashrrev_i32_e32 v99, 31, v98
	v_lshlrev_b64 v[98:99], 11, v[98:99]
	s_waitcnt lgkmcnt(0)
	v_add_f32_e32 v80, v80, v81
	ds_bpermute_b32 v81, v231, v80
	v_lshl_add_u64 v[98:99], v[204:205], 0, v[98:99]
	v_cvt_pk_bf16_f32 v90, v90, v91
	v_cvt_pk_bf16_f32 v91, v102, v103
	global_store_dwordx4 v[98:99], v[88:91], off
	v_cvt_pk_bf16_f32 v82, v84, v85
	v_cvt_pk_bf16_f32 v83, v86, v87
	v_cvt_pk_bf16_f32 v84, v94, v95
	v_cvt_pk_bf16_f32 v85, v92, v93
	global_store_dwordx4 v[98:99], v[82:85], off offset:256
	s_and_saveexec_b64 s[12:13], vcc
	s_cbranch_execz .LBB0_736
	s_waitcnt lgkmcnt(0)
	v_add_f32_e32 v80, v80, v81
	v_lshl_add_u32 v81, v96, 4, s79
	ds_write_b32 v81, v80
.LBB0_736:
	s_or_b64 exec, exec, s[12:13]
	ds_read_b32 v84, v206 offset:192
	v_lshlrev_b32_e32 v86, 16, v148
	v_and_b32_e32 v87, 0xffff0000, v148
	v_lshlrev_b32_e32 v88, 16, v149
	v_and_b32_e32 v89, 0xffff0000, v149
	s_waitcnt lgkmcnt(0)
	v_pk_mul_f32 v[78:79], v[78:79], v[84:85] op_sel_hi:[1,0]
	v_pk_mul_f32 v[76:77], v[76:77], v[84:85] op_sel_hi:[1,0]
	v_lshlrev_b32_e32 v90, 16, v150
	v_and_b32_e32 v91, 0xffff0000, v150
	v_lshlrev_b32_e32 v92, 16, v151
	v_and_b32_e32 v93, 0xffff0000, v151
	v_pk_fma_f32 v[78:79], v[126:127], v[78:79], v[88:89]
	v_pk_fma_f32 v[76:77], v[124:125], v[76:77], v[86:87]
	v_pk_mul_f32 v[74:75], v[74:75], v[84:85] op_sel_hi:[1,0]
	v_pk_mul_f32 v[72:73], v[72:73], v[84:85] op_sel_hi:[1,0]
	v_pk_fma_f32 v[86:87], v[122:123], v[74:75], v[92:93]
	v_pk_fma_f32 v[74:75], v[120:121], v[72:73], v[90:91]
	v_mul_f32_e32 v72, v77, v77
	v_mul_f32_e32 v73, v79, v79
	v_fmac_f32_e32 v72, v76, v76
	v_fmac_f32_e32 v73, v78, v78
	v_add_f32_e32 v72, v72, v73
	v_mul_f32_e32 v73, v75, v75
	v_mul_f32_e32 v81, v87, v87
	v_fmac_f32_e32 v73, v74, v74
	v_fmac_f32_e32 v81, v86, v86
	v_add_f32_e32 v73, v73, v81
	v_add_f32_e32 v81, v72, v73
	v_cvt_pk_bf16_f32 v72, v76, v77
	v_cvt_pk_bf16_f32 v73, v78, v79
	v_lshlrev_b32_e32 v76, 16, v144
	v_and_b32_e32 v77, 0xffff0000, v144
	v_lshlrev_b32_e32 v78, 16, v145
	v_and_b32_e32 v79, 0xffff0000, v145
	v_pk_mul_f32 v[70:71], v[70:71], v[84:85] op_sel_hi:[1,0]
	v_pk_mul_f32 v[68:69], v[68:69], v[84:85] op_sel_hi:[1,0]
	v_lshlrev_b32_e32 v88, 16, v146
	v_and_b32_e32 v89, 0xffff0000, v146
	v_pk_fma_f32 v[70:71], v[110:111], v[70:71], v[78:79]
	v_pk_fma_f32 v[68:69], v[108:109], v[68:69], v[76:77]
	v_pk_mul_f32 v[64:65], v[64:65], v[84:85] op_sel_hi:[1,0]
	v_lshlrev_b32_e32 v90, 16, v147
	v_and_b32_e32 v91, 0xffff0000, v147
	v_pk_mul_f32 v[66:67], v[66:67], v[84:85] op_sel_hi:[1,0]
	v_pk_fma_f32 v[78:79], v[104:105], v[64:65], v[88:89]
	v_mul_f32_e32 v64, v69, v69
	v_mul_f32_e32 v65, v71, v71
	v_pk_fma_f32 v[76:77], v[106:107], v[66:67], v[90:91]
	v_fmac_f32_e32 v64, v68, v68
	v_fmac_f32_e32 v65, v70, v70
	v_add_f32_e32 v64, v64, v65
	v_mul_f32_e32 v65, v79, v79
	v_mul_f32_e32 v66, v77, v77
	v_fmac_f32_e32 v65, v78, v78
	v_fmac_f32_e32 v66, v76, v76
	v_add_f32_e32 v65, v65, v66
	v_add_f32_e32 v64, v64, v65
	v_add_f32_e32 v64, v81, v64
	ds_bpermute_b32 v65, v230, v64
	v_add_u32_e32 v80, 48, v207
	v_add_u32_e32 v82, s80, v80
	v_ashrrev_i32_e32 v83, 31, v82
	v_lshlrev_b64 v[82:83], 11, v[82:83]
	s_waitcnt lgkmcnt(0)
	v_add_f32_e32 v64, v64, v65
	ds_bpermute_b32 v65, v231, v64
	v_lshl_add_u64 v[82:83], v[204:205], 0, v[82:83]
	v_cvt_pk_bf16_f32 v74, v74, v75
	v_cvt_pk_bf16_f32 v75, v86, v87
	global_store_dwordx4 v[82:83], v[72:75], off
	v_cvt_pk_bf16_f32 v66, v68, v69
	v_cvt_pk_bf16_f32 v67, v70, v71
	v_cvt_pk_bf16_f32 v68, v78, v79
	v_cvt_pk_bf16_f32 v69, v76, v77
	global_store_dwordx4 v[82:83], v[66:69], off offset:256
	s_and_saveexec_b64 s[12:13], vcc
	s_cbranch_execz .LBB0_738
	s_waitcnt lgkmcnt(0)
	v_add_f32_e32 v64, v64, v65
	v_lshl_add_u32 v65, v80, 4, s79
	ds_write_b32 v65, v64
.LBB0_738:
	s_or_b64 exec, exec, s[12:13]
	v_add_u32_e32 v64, 0x80, v207
	v_add_u32_e32 v66, s80, v64
	v_ashrrev_i32_e32 v67, 31, v66
	v_lshlrev_b64 v[66:67], 11, v[66:67]
	v_lshl_add_u64 v[70:71], v[204:205], 0, v[66:67]
	ds_read_b32 v72, v206 offset:512
	s_waitcnt lgkmcnt(0)
	v_pk_mul_f32 v[62:63], v[62:63], v[72:73] op_sel_hi:[1,0]
	v_pk_mul_f32 v[60:61], v[60:61], v[72:73] op_sel_hi:[1,0]
	v_pk_mul_f32 v[58:59], v[58:59], v[72:73] op_sel_hi:[1,0]
	v_pk_mul_f32 v[56:57], v[56:57], v[72:73] op_sel_hi:[1,0]
	v_pk_mul_f32 v[54:55], v[54:55], v[72:73] op_sel_hi:[1,0]
	v_pk_mul_f32 v[52:53], v[52:53], v[72:73] op_sel_hi:[1,0]
	v_pk_mul_f32 v[50:51], v[50:51], v[72:73] op_sel_hi:[1,0]
	v_pk_mul_f32 v[48:49], v[48:49], v[72:73] op_sel_hi:[1,0]
	v_lshlrev_b32_e32 v74, 16, v236
	v_and_b32_e32 v75, 0xffff0000, v236
	v_lshlrev_b32_e32 v66, 16, v237
	v_and_b32_e32 v67, 0xffff0000, v237
	v_lshlrev_b32_e32 v76, 16, v238
	v_and_b32_e32 v77, 0xffff0000, v238
	v_lshlrev_b32_e32 v68, 16, v239
	v_and_b32_e32 v69, 0xffff0000, v239
	v_pk_fma_f32 v[66:67], v[126:127], v[62:63], v[66:67]
	v_pk_fma_f32 v[74:75], v[124:125], v[60:61], v[74:75]
	v_pk_fma_f32 v[68:69], v[122:123], v[58:59], v[68:69]
	v_pk_fma_f32 v[76:77], v[120:121], v[56:57], v[76:77]
	v_cvt_pk_bf16_f32 v56, v74, v75
	v_cvt_pk_bf16_f32 v57, v66, v67
	v_mul_f32_e32 v65, v75, v75
	v_cvt_pk_bf16_f32 v58, v76, v77
	v_cvt_pk_bf16_f32 v59, v68, v69
	v_mul_f32_e32 v67, v67, v67
	v_mul_f32_e32 v72, v77, v77
	v_mul_f32_e32 v69, v69, v69
	v_fmac_f32_e32 v65, v74, v74
	v_fmac_f32_e32 v67, v66, v66
	v_fmac_f32_e32 v72, v76, v76
	v_fmac_f32_e32 v69, v68, v68
	v_add_f32_e32 v65, v65, v67
	v_add_f32_e32 v66, v72, v69
	v_add_f32_e32 v65, v65, v66
	global_store_dwordx4 v[70:71], v[56:59], off
	v_lshlrev_b32_e32 v66, 16, v240
	v_and_b32_e32 v67, 0xffff0000, v240
	v_lshlrev_b32_e32 v60, 16, v241
	v_and_b32_e32 v61, 0xffff0000, v241
	v_lshlrev_b32_e32 v68, 16, v242
	v_and_b32_e32 v69, 0xffff0000, v242
	v_lshlrev_b32_e32 v62, 16, v243
	v_and_b32_e32 v63, 0xffff0000, v243
	v_pk_fma_f32 v[54:55], v[110:111], v[54:55], v[60:61]
	v_pk_fma_f32 v[52:53], v[108:109], v[52:53], v[66:67]
	v_pk_fma_f32 v[60:61], v[106:107], v[50:51], v[62:63]
	v_pk_fma_f32 v[62:63], v[104:105], v[48:49], v[68:69]
	v_mul_f32_e32 v48, v53, v53
	v_mul_f32_e32 v49, v55, v55
	v_mul_f32_e32 v50, v63, v63
	v_mul_f32_e32 v51, v61, v61
	v_fmac_f32_e32 v48, v52, v52
	v_fmac_f32_e32 v49, v54, v54
	v_fmac_f32_e32 v50, v62, v62
	v_fmac_f32_e32 v51, v60, v60
	v_add_f32_e32 v48, v48, v49
	v_add_f32_e32 v49, v50, v51
	v_add_f32_e32 v48, v48, v49
	v_add_f32_e32 v48, v65, v48
	ds_bpermute_b32 v49, v230, v48
	v_cvt_pk_bf16_f32 v50, v52, v53
	v_cvt_pk_bf16_f32 v51, v54, v55
	v_cvt_pk_bf16_f32 v52, v62, v63
	v_cvt_pk_bf16_f32 v53, v60, v61
	s_waitcnt lgkmcnt(0)
	v_add_f32_e32 v48, v48, v49
	ds_bpermute_b32 v49, v231, v48
	global_store_dwordx4 v[70:71], v[50:53], off offset:256
	s_and_saveexec_b64 s[12:13], vcc
	s_cbranch_execz .LBB0_740
	s_waitcnt lgkmcnt(0)
	v_add_f32_e32 v48, v48, v49
	v_lshl_add_u32 v49, v64, 4, s79
	ds_write_b32 v49, v48
.LBB0_740:
	s_or_b64 exec, exec, s[12:13]
	v_add_u32_e32 v48, 0x90, v207
	v_add_u32_e32 v50, s80, v48
	v_ashrrev_i32_e32 v51, 31, v50
	v_lshlrev_b64 v[50:51], 11, v[50:51]
	v_lshl_add_u64 v[54:55], v[204:205], 0, v[50:51]
	ds_read_b32 v56, v206 offset:576
	s_waitcnt lgkmcnt(0)
	v_pk_mul_f32 v[46:47], v[46:47], v[56:57] op_sel_hi:[1,0]
	v_pk_mul_f32 v[44:45], v[44:45], v[56:57] op_sel_hi:[1,0]
	v_pk_mul_f32 v[42:43], v[42:43], v[56:57] op_sel_hi:[1,0]
	v_pk_mul_f32 v[40:41], v[40:41], v[56:57] op_sel_hi:[1,0]
	v_pk_mul_f32 v[38:39], v[38:39], v[56:57] op_sel_hi:[1,0]
	v_pk_mul_f32 v[36:37], v[36:37], v[56:57] op_sel_hi:[1,0]
	v_pk_mul_f32 v[34:35], v[34:35], v[56:57] op_sel_hi:[1,0]
	v_pk_mul_f32 v[32:33], v[32:33], v[56:57] op_sel_hi:[1,0]
	v_lshlrev_b32_e32 v58, 16, v244
	v_and_b32_e32 v59, 0xffff0000, v244
	v_lshlrev_b32_e32 v50, 16, v245
	v_and_b32_e32 v51, 0xffff0000, v245
	v_lshlrev_b32_e32 v60, 16, v246
	v_and_b32_e32 v61, 0xffff0000, v246
	v_lshlrev_b32_e32 v52, 16, v247
	v_and_b32_e32 v53, 0xffff0000, v247
	v_pk_fma_f32 v[50:51], v[126:127], v[46:47], v[50:51]
	v_pk_fma_f32 v[58:59], v[124:125], v[44:45], v[58:59]
	v_pk_fma_f32 v[52:53], v[122:123], v[42:43], v[52:53]
	v_pk_fma_f32 v[60:61], v[120:121], v[40:41], v[60:61]
	v_cvt_pk_bf16_f32 v40, v58, v59
	v_cvt_pk_bf16_f32 v41, v50, v51
	v_mul_f32_e32 v49, v59, v59
	v_cvt_pk_bf16_f32 v42, v60, v61
	v_cvt_pk_bf16_f32 v43, v52, v53
	v_mul_f32_e32 v51, v51, v51
	v_mul_f32_e32 v56, v61, v61
	v_mul_f32_e32 v53, v53, v53
	v_fmac_f32_e32 v49, v58, v58
	v_fmac_f32_e32 v51, v50, v50
	v_fmac_f32_e32 v56, v60, v60
	v_fmac_f32_e32 v53, v52, v52
	v_add_f32_e32 v49, v49, v51
	v_add_f32_e32 v50, v56, v53
	v_add_f32_e32 v49, v49, v50
	global_store_dwordx4 v[54:55], v[40:43], off
	v_lshlrev_b32_e32 v50, 16, v248
	v_and_b32_e32 v51, 0xffff0000, v248
	v_lshlrev_b32_e32 v44, 16, v249
	v_and_b32_e32 v45, 0xffff0000, v249
	v_lshlrev_b32_e32 v52, 16, v250
	v_and_b32_e32 v53, 0xffff0000, v250
	v_lshlrev_b32_e32 v46, 16, v251
	v_and_b32_e32 v47, 0xffff0000, v251
	v_pk_fma_f32 v[38:39], v[110:111], v[38:39], v[44:45]
	v_pk_fma_f32 v[36:37], v[108:109], v[36:37], v[50:51]
	v_pk_fma_f32 v[44:45], v[106:107], v[34:35], v[46:47]
	v_pk_fma_f32 v[46:47], v[104:105], v[32:33], v[52:53]
	v_mul_f32_e32 v32, v37, v37
	v_mul_f32_e32 v33, v39, v39
	v_mul_f32_e32 v34, v47, v47
	v_mul_f32_e32 v35, v45, v45
	v_fmac_f32_e32 v32, v36, v36
	v_fmac_f32_e32 v33, v38, v38
	v_fmac_f32_e32 v34, v46, v46
	v_fmac_f32_e32 v35, v44, v44
	v_add_f32_e32 v32, v32, v33
	v_add_f32_e32 v33, v34, v35
	v_add_f32_e32 v32, v32, v33
	v_add_f32_e32 v32, v49, v32
	ds_bpermute_b32 v33, v230, v32
	v_cvt_pk_bf16_f32 v34, v36, v37
	v_cvt_pk_bf16_f32 v35, v38, v39
	v_cvt_pk_bf16_f32 v36, v46, v47
	v_cvt_pk_bf16_f32 v37, v44, v45
	s_waitcnt lgkmcnt(0)
	v_add_f32_e32 v32, v32, v33
	ds_bpermute_b32 v33, v231, v32
	global_store_dwordx4 v[54:55], v[34:37], off offset:256
	s_and_saveexec_b64 s[12:13], vcc
	s_cbranch_execz .LBB0_742
	s_waitcnt lgkmcnt(0)
	v_add_f32_e32 v32, v32, v33
	v_lshl_add_u32 v33, v48, 4, s79
	ds_write_b32 v33, v32
.LBB0_742:
	s_or_b64 exec, exec, s[12:13]
	v_add_u32_e32 v32, 0xa0, v207
	v_add_u32_e32 v34, s80, v32
	v_ashrrev_i32_e32 v35, 31, v34
	v_lshlrev_b64 v[34:35], 11, v[34:35]
	v_lshl_add_u64 v[38:39], v[204:205], 0, v[34:35]
	ds_read_b32 v40, v206 offset:640
	s_waitcnt lgkmcnt(0)
	v_pk_mul_f32 v[30:31], v[30:31], v[40:41] op_sel_hi:[1,0]
	v_pk_mul_f32 v[28:29], v[28:29], v[40:41] op_sel_hi:[1,0]
	v_pk_mul_f32 v[26:27], v[26:27], v[40:41] op_sel_hi:[1,0]
	v_pk_mul_f32 v[24:25], v[24:25], v[40:41] op_sel_hi:[1,0]
	v_pk_mul_f32 v[22:23], v[22:23], v[40:41] op_sel_hi:[1,0]
	v_pk_mul_f32 v[20:21], v[20:21], v[40:41] op_sel_hi:[1,0]
	v_pk_mul_f32 v[18:19], v[18:19], v[40:41] op_sel_hi:[1,0]
	v_pk_mul_f32 v[16:17], v[16:17], v[40:41] op_sel_hi:[1,0]
	s_waitcnt vmcnt(13)
	v_lshlrev_b32_e32 v42, 16, v168
	v_and_b32_e32 v43, 0xffff0000, v168
	v_lshlrev_b32_e32 v34, 16, v169
	v_and_b32_e32 v35, 0xffff0000, v169
	v_lshlrev_b32_e32 v44, 16, v170
	v_and_b32_e32 v45, 0xffff0000, v170
	v_lshlrev_b32_e32 v36, 16, v171
	v_and_b32_e32 v37, 0xffff0000, v171
	v_pk_fma_f32 v[34:35], v[126:127], v[30:31], v[34:35]
	v_pk_fma_f32 v[42:43], v[124:125], v[28:29], v[42:43]
	v_pk_fma_f32 v[36:37], v[122:123], v[26:27], v[36:37]
	v_pk_fma_f32 v[44:45], v[120:121], v[24:25], v[44:45]
	v_cvt_pk_bf16_f32 v24, v42, v43
	v_cvt_pk_bf16_f32 v25, v34, v35
	v_mul_f32_e32 v33, v43, v43
	v_cvt_pk_bf16_f32 v26, v44, v45
	v_cvt_pk_bf16_f32 v27, v36, v37
	v_mul_f32_e32 v35, v35, v35
	v_mul_f32_e32 v40, v45, v45
	v_mul_f32_e32 v37, v37, v37
	v_fmac_f32_e32 v33, v42, v42
	v_fmac_f32_e32 v35, v34, v34
	v_fmac_f32_e32 v40, v44, v44
	v_fmac_f32_e32 v37, v36, v36
	v_add_f32_e32 v33, v33, v35
	v_add_f32_e32 v34, v40, v37
	v_add_f32_e32 v33, v33, v34
	global_store_dwordx4 v[38:39], v[24:27], off
	s_waitcnt vmcnt(13)
	v_lshlrev_b32_e32 v34, 16, v172
	v_and_b32_e32 v35, 0xffff0000, v172
	v_lshlrev_b32_e32 v28, 16, v173
	v_and_b32_e32 v29, 0xffff0000, v173
	v_lshlrev_b32_e32 v36, 16, v174
	v_and_b32_e32 v37, 0xffff0000, v174
	v_lshlrev_b32_e32 v30, 16, v175
	v_and_b32_e32 v31, 0xffff0000, v175
	v_pk_fma_f32 v[22:23], v[110:111], v[22:23], v[28:29]
	v_pk_fma_f32 v[20:21], v[108:109], v[20:21], v[34:35]
	v_pk_fma_f32 v[28:29], v[106:107], v[18:19], v[30:31]
	v_pk_fma_f32 v[30:31], v[104:105], v[16:17], v[36:37]
	v_mul_f32_e32 v16, v21, v21
	v_mul_f32_e32 v17, v23, v23
	v_mul_f32_e32 v18, v31, v31
	v_mul_f32_e32 v19, v29, v29
	v_fmac_f32_e32 v16, v20, v20
	v_fmac_f32_e32 v17, v22, v22
	v_fmac_f32_e32 v18, v30, v30
	v_fmac_f32_e32 v19, v28, v28
	v_add_f32_e32 v16, v16, v17
	v_add_f32_e32 v17, v18, v19
	v_add_f32_e32 v16, v16, v17
	v_add_f32_e32 v16, v33, v16
	ds_bpermute_b32 v17, v230, v16
	v_cvt_pk_bf16_f32 v18, v20, v21
	v_cvt_pk_bf16_f32 v19, v22, v23
	v_cvt_pk_bf16_f32 v20, v30, v31
	v_cvt_pk_bf16_f32 v21, v28, v29
	s_waitcnt lgkmcnt(0)
	v_add_f32_e32 v16, v16, v17
	ds_bpermute_b32 v17, v231, v16
	global_store_dwordx4 v[38:39], v[18:21], off offset:256
	s_and_saveexec_b64 s[12:13], vcc
	s_cbranch_execz .LBB0_744
	s_waitcnt lgkmcnt(0)
	v_add_f32_e32 v16, v16, v17
	v_lshl_add_u32 v17, v32, 4, s79
	ds_write_b32 v17, v16
.LBB0_744:
	s_or_b64 exec, exec, s[12:13]
	v_add_u32_e32 v16, 0xb0, v207
	v_add_u32_e32 v18, s80, v16
	v_ashrrev_i32_e32 v19, 31, v18
	v_lshlrev_b64 v[18:19], 11, v[18:19]
	v_lshl_add_u64 v[22:23], v[204:205], 0, v[18:19]
	ds_read_b32 v24, v206 offset:704
	s_waitcnt lgkmcnt(0)
	v_pk_mul_f32 v[14:15], v[14:15], v[24:25] op_sel_hi:[1,0]
	v_pk_mul_f32 v[12:13], v[12:13], v[24:25] op_sel_hi:[1,0]
	v_pk_mul_f32 v[10:11], v[10:11], v[24:25] op_sel_hi:[1,0]
	v_pk_mul_f32 v[8:9], v[8:9], v[24:25] op_sel_hi:[1,0]
	v_pk_mul_f32 v[6:7], v[6:7], v[24:25] op_sel_hi:[1,0]
	v_pk_mul_f32 v[4:5], v[4:5], v[24:25] op_sel_hi:[1,0]
	v_pk_mul_f32 v[2:3], v[2:3], v[24:25] op_sel_hi:[1,0]
	v_pk_mul_f32 v[0:1], v[0:1], v[24:25] op_sel_hi:[1,0]
	s_waitcnt vmcnt(13)
	v_lshlrev_b32_e32 v26, 16, v208
	v_and_b32_e32 v27, 0xffff0000, v208
	v_lshlrev_b32_e32 v18, 16, v209
	v_and_b32_e32 v19, 0xffff0000, v209
	v_lshlrev_b32_e32 v28, 16, v210
	v_and_b32_e32 v29, 0xffff0000, v210
	v_lshlrev_b32_e32 v20, 16, v211
	v_and_b32_e32 v21, 0xffff0000, v211
	v_pk_fma_f32 v[18:19], v[126:127], v[14:15], v[18:19]
	v_pk_fma_f32 v[26:27], v[124:125], v[12:13], v[26:27]
	v_pk_fma_f32 v[20:21], v[122:123], v[10:11], v[20:21]
	v_pk_fma_f32 v[28:29], v[120:121], v[8:9], v[28:29]
	v_cvt_pk_bf16_f32 v8, v26, v27
	v_cvt_pk_bf16_f32 v9, v18, v19
	v_mul_f32_e32 v17, v27, v27
	v_cvt_pk_bf16_f32 v10, v28, v29
	v_cvt_pk_bf16_f32 v11, v20, v21
	v_mul_f32_e32 v19, v19, v19
	v_mul_f32_e32 v24, v29, v29
	v_mul_f32_e32 v21, v21, v21
	v_fmac_f32_e32 v17, v26, v26
	v_fmac_f32_e32 v19, v18, v18
	v_fmac_f32_e32 v24, v28, v28
	v_fmac_f32_e32 v21, v20, v20
	v_add_f32_e32 v17, v17, v19
	v_add_f32_e32 v18, v24, v21
	v_add_f32_e32 v17, v17, v18
	global_store_dwordx4 v[22:23], v[8:11], off
	s_waitcnt vmcnt(13)
	v_lshlrev_b32_e32 v18, 16, v212
	v_and_b32_e32 v19, 0xffff0000, v212
	v_lshlrev_b32_e32 v12, 16, v213
	v_and_b32_e32 v13, 0xffff0000, v213
	v_lshlrev_b32_e32 v20, 16, v214
	v_and_b32_e32 v21, 0xffff0000, v214
	v_lshlrev_b32_e32 v14, 16, v215
	v_and_b32_e32 v15, 0xffff0000, v215
	v_pk_fma_f32 v[6:7], v[110:111], v[6:7], v[12:13]
	v_pk_fma_f32 v[4:5], v[108:109], v[4:5], v[18:19]
	v_pk_fma_f32 v[12:13], v[106:107], v[2:3], v[14:15]
	v_pk_fma_f32 v[14:15], v[104:105], v[0:1], v[20:21]
	v_mul_f32_e32 v0, v5, v5
	v_mul_f32_e32 v1, v7, v7
	v_mul_f32_e32 v2, v15, v15
	v_mul_f32_e32 v3, v13, v13
	v_fmac_f32_e32 v0, v4, v4
	v_fmac_f32_e32 v1, v6, v6
	v_fmac_f32_e32 v2, v14, v14
	v_fmac_f32_e32 v3, v12, v12
	v_add_f32_e32 v0, v0, v1
	v_add_f32_e32 v1, v2, v3
	v_add_f32_e32 v0, v0, v1
	v_add_f32_e32 v0, v17, v0
	ds_bpermute_b32 v1, v230, v0
	v_cvt_pk_bf16_f32 v2, v4, v5
	v_cvt_pk_bf16_f32 v3, v6, v7
	v_cvt_pk_bf16_f32 v4, v14, v15
	v_cvt_pk_bf16_f32 v5, v12, v13
	s_waitcnt lgkmcnt(0)
	v_add_f32_e32 v0, v0, v1
	ds_bpermute_b32 v1, v231, v0
	global_store_dwordx4 v[22:23], v[2:5], off offset:256
	s_and_saveexec_b64 s[12:13], vcc
	s_cbranch_execz .LBB0_746
	s_waitcnt lgkmcnt(0)
	v_add_f32_e32 v0, v0, v1
	v_lshl_add_u32 v1, v16, 4, s79
	ds_write_b32 v1, v0

.LBB0_903:
	s_or_b64 exec, exec, s[12:13]
	s_lshl_b32 s12, s14, 8
	s_lshl_b32 s13, s40, 5
	s_add_i32 s13, s13, s12
	s_lshl_b32 s82, s15, 8
	s_lshl_b32 s83, s41, 6
	v_lshl_add_u32 v144, v206, 3, s13
	s_add_i32 s12, s83, s82
	v_ashrrev_i32_e32 v145, 31, v144
	v_add_u32_e32 v146, s12, v233
	s_waitcnt vmcnt(0)
	v_lshl_add_u64 v[104:105], v[144:145], 2, v[104:105]
	v_lshl_add_u64 v[144:145], v[144:145], 1, v[202:203]
	v_ashrrev_i32_e32 v147, 31, v146
	v_lshl_add_u64 v[108:109], v[104:105], 0, s[34:35]
	v_add_co_u32_e32 v104, vcc, 0x1000, v104
	v_lshl_add_u64 v[204:205], v[144:145], 0, s[36:37]
	v_lshlrev_b64 v[144:145], 11, v[146:147]
	s_waitcnt lgkmcnt(0)
	s_barrier
	v_addc_co_u32_e32 v105, vcc, 0, v105, vcc
	v_lshl_add_u64 v[144:145], v[204:205], 0, v[144:145]
	global_load_dwordx4 v[124:127], v[104:105], off
	s_waitcnt lgkmcnt(0)
	global_load_dwordx4 v[104:107], v[108:109], off offset:528
	global_load_dwordx4 v[120:123], v[108:109], off offset:16
	s_nop 0
	global_load_dwordx4 v[108:111], v[108:109], off offset:512
	s_nop 0
	global_load_dwordx4 v[172:175], v[144:145], off
	global_load_dwordx4 v[168:171], v[144:145], off offset:256
	v_add_u32_e32 v144, 16, v146
	v_ashrrev_i32_e32 v145, 31, v144
	v_lshlrev_b64 v[144:145], 11, v[144:145]
	v_lshl_add_u64 v[144:145], v[204:205], 0, v[144:145]
	global_load_dwordx4 v[164:167], v[144:145], off
	global_load_dwordx4 v[160:163], v[144:145], off offset:256
	v_add_u32_e32 v144, 32, v146
	v_ashrrev_i32_e32 v145, 31, v144
	v_lshlrev_b64 v[144:145], 11, v[144:145]
	v_lshl_add_u64 v[144:145], v[204:205], 0, v[144:145]
	global_load_dwordx4 v[156:159], v[144:145], off
	global_load_dwordx4 v[152:155], v[144:145], off offset:256
	v_add_u32_e32 v144, 0x80, v146
	v_ashrrev_i32_e32 v145, 31, v144
	v_lshlrev_b64 v[144:145], 11, v[144:145]
	v_lshl_add_u64 v[144:145], v[204:205], 0, v[144:145]
	global_load_dwordx4 v[236:239], v[144:145], off
	global_load_dwordx4 v[240:243], v[144:145], off offset:256
	v_add_u32_e32 v144, 0x90, v146
	v_ashrrev_i32_e32 v145, 31, v144
	v_lshlrev_b64 v[144:145], 11, v[144:145]
	v_lshl_add_u64 v[144:145], v[204:205], 0, v[144:145]
	global_load_dwordx4 v[244:247], v[144:145], off
	global_load_dwordx4 v[248:251], v[144:145], off offset:256
	v_add_u32_e32 v144, 48, v146
	v_ashrrev_i32_e32 v145, 31, v144
	v_lshlrev_b64 v[144:145], 11, v[144:145]
	v_lshl_add_u64 v[144:145], v[204:205], 0, v[144:145]
	global_load_dwordx4 v[148:151], v[144:145], off
	s_nop 0
	global_load_dwordx4 v[144:147], v[144:145], off offset:256
	s_lshl_b32 s12, s41, 2
	v_lshl_add_u32 v206, v206, 4, v233
	s_add_i32 s12, s12, s40
	v_cmp_gt_i32_e32 vcc, 32, v206
	v_lshl_add_u32 v232, s12, 5, v206
	s_and_saveexec_b64 s[40:41], vcc
	s_cbranch_execz .LBB0_918
	v_lshl_add_u32 v206, v232, 4, v228
	ds_read_b128 v[208:211], v206
	v_add_u32_e32 v206, s82, v232
	v_ashrrev_i32_e32 v207, 31, v206
	v_lshlrev_b64 v[206:207], 5, v[206:207]
	v_lshl_add_u64 v[206:207], v[202:203], 0, v[206:207]
	s_waitcnt lgkmcnt(0)
	v_mov_b32_e32 v214, v209
	v_mov_b32_e32 v215, v210
	v_mov_b32_e32 v209, v211
	v_pk_add_f32 v[208:209], v[214:215], v[208:209]
	v_lshl_add_u64 v[206:207], v[206:207], 0, s[38:39]
	s_ashr_i32 s15, s14, 31
	v_pk_add_f32 v[208:209], v[208:209], v[208:209] op_sel:[0,1] op_sel_hi:[1,0]
	v_lshl_add_u64 v[212:213], s[14:15], 3, v[206:207]
	v_mov_b32_e32 v209, v217
	s_mov_b32 s15, 0x100000
	s_mov_b64 s[50:51], 0
	global_store_dwordx2 v[212:213], v[208:209], off sc1
	s_branch .LBB0_910

.LBB0_918:
	s_or_b64 exec, exec, s[40:41]
	v_add_u32_e32 v207, s83, v233
	s_waitcnt vmcnt(0) lgkmcnt(0)
	s_barrier
	v_lshl_add_u32 v206, v207, 2, v229
	ds_read_b32 v210, v206
	v_lshlrev_b32_e32 v212, 16, v172
	v_and_b32_e32 v213, 0xffff0000, v172
	v_lshlrev_b32_e32 v172, 16, v173
	v_and_b32_e32 v173, 0xffff0000, v173
	s_waitcnt lgkmcnt(0)
	v_pk_mul_f32 v[142:143], v[142:143], v[210:211] op_sel_hi:[1,0]
	v_pk_mul_f32 v[140:141], v[140:141], v[210:211] op_sel_hi:[1,0]
	v_lshlrev_b32_e32 v214, 16, v174
	v_and_b32_e32 v215, 0xffff0000, v174
	v_lshlrev_b32_e32 v174, 16, v175
	v_and_b32_e32 v175, 0xffff0000, v175
	v_pk_fma_f32 v[142:143], v[126:127], v[142:143], v[172:173]
	v_pk_fma_f32 v[140:141], v[124:125], v[140:141], v[212:213]
	v_pk_mul_f32 v[138:139], v[138:139], v[210:211] op_sel_hi:[1,0]
	v_pk_mul_f32 v[136:137], v[136:137], v[210:211] op_sel_hi:[1,0]
	v_pk_fma_f32 v[172:173], v[122:123], v[138:139], v[174:175]
	v_pk_fma_f32 v[138:139], v[120:121], v[136:137], v[214:215]
	v_mul_f32_e32 v136, v141, v141
	v_mul_f32_e32 v137, v143, v143
	v_fmac_f32_e32 v136, v140, v140
	v_fmac_f32_e32 v137, v142, v142
	v_add_f32_e32 v136, v136, v137
	v_mul_f32_e32 v137, v139, v139
	v_mul_f32_e32 v174, v173, v173
	v_fmac_f32_e32 v137, v138, v138
	v_fmac_f32_e32 v174, v172, v172
	v_add_f32_e32 v137, v137, v174
	v_add_f32_e32 v174, v136, v137
	v_cvt_pk_bf16_f32 v136, v140, v141
	v_cvt_pk_bf16_f32 v137, v142, v143
	v_lshlrev_b32_e32 v140, 16, v168
	v_and_b32_e32 v141, 0xffff0000, v168
	v_lshlrev_b32_e32 v142, 16, v169
	v_and_b32_e32 v143, 0xffff0000, v169
	v_pk_mul_f32 v[134:135], v[134:135], v[210:211] op_sel_hi:[1,0]
	v_pk_mul_f32 v[132:133], v[132:133], v[210:211] op_sel_hi:[1,0]
	v_lshlrev_b32_e32 v168, 16, v170
	v_and_b32_e32 v169, 0xffff0000, v170
	v_pk_fma_f32 v[134:135], v[110:111], v[134:135], v[142:143]
	v_pk_fma_f32 v[132:133], v[108:109], v[132:133], v[140:141]
	v_pk_mul_f32 v[128:129], v[128:129], v[210:211] op_sel_hi:[1,0]
	v_lshlrev_b32_e32 v170, 16, v171
	v_and_b32_e32 v171, 0xffff0000, v171
	v_pk_mul_f32 v[130:131], v[130:131], v[210:211] op_sel_hi:[1,0]
	v_pk_fma_f32 v[142:143], v[104:105], v[128:129], v[168:169]
	v_mul_f32_e32 v128, v133, v133
	v_mul_f32_e32 v129, v135, v135
	v_pk_fma_f32 v[140:141], v[106:107], v[130:131], v[170:171]
	v_fmac_f32_e32 v128, v132, v132
	v_fmac_f32_e32 v129, v134, v134
	v_add_f32_e32 v128, v128, v129
	v_mul_f32_e32 v129, v143, v143
	v_mul_f32_e32 v130, v141, v141
	v_fmac_f32_e32 v129, v142, v142
	v_fmac_f32_e32 v130, v140, v140
	v_add_f32_e32 v129, v129, v130
	v_add_f32_e32 v128, v128, v129
	v_add_f32_e32 v128, v174, v128
	ds_bpermute_b32 v129, v230, v128
	v_add_u32_e32 v208, s82, v207
	v_ashrrev_i32_e32 v209, 31, v208
	v_lshlrev_b64 v[208:209], 11, v[208:209]
	v_lshl_add_u64 v[208:209], v[204:205], 0, v[208:209]
	s_waitcnt lgkmcnt(0)
	v_add_f32_e32 v128, v128, v129
	ds_bpermute_b32 v129, v231, v128
	v_cvt_pk_bf16_f32 v138, v138, v139
	v_cvt_pk_bf16_f32 v139, v172, v173
	global_store_dwordx4 v[208:209], v[136:139], off
	v_cvt_pk_bf16_f32 v130, v132, v133
	v_cvt_pk_bf16_f32 v131, v134, v135
	v_cvt_pk_bf16_f32 v132, v142, v143
	v_cvt_pk_bf16_f32 v133, v140, v141
	global_store_dwordx4 v[208:209], v[130:133], off offset:256
	s_and_saveexec_b64 s[12:13], s[10:11]
	s_cbranch_execz .LBB0_920
	s_waitcnt lgkmcnt(0)
	v_add_f32_e32 v128, v128, v129
	v_lshl_add_u32 v129, v207, 4, s81
	ds_write_b32 v129, v128
.LBB0_920:
	s_or_b64 exec, exec, s[12:13]
	v_add_u32_e32 v252, 0xa0, v207
	v_add_u32_e32 v252, s82, v252
	v_ashrrev_i32_e32 v253, 31, v252
	v_lshlrev_b64 v[252:253], 11, v[252:253]
	v_lshl_add_u64 v[252:253], v[204:205], 0, v[252:253]
	global_load_dwordx4 v[168:171], v[252:253], off
	global_load_dwordx4 v[172:175], v[252:253], off offset:256
	v_add_u32_e32 v252, 0xb0, v207
	v_add_u32_e32 v252, s82, v252
	v_ashrrev_i32_e32 v253, 31, v252
	v_lshlrev_b64 v[252:253], 11, v[252:253]
	v_lshl_add_u64 v[252:253], v[204:205], 0, v[252:253]
	global_load_dwordx4 v[208:211], v[252:253], off
	global_load_dwordx4 v[212:215], v[252:253], off offset:256
	ds_read_b32 v132, v206 offset:64
	v_lshlrev_b32_e32 v134, 16, v164
	v_and_b32_e32 v135, 0xffff0000, v164
	v_lshlrev_b32_e32 v136, 16, v165
	v_and_b32_e32 v137, 0xffff0000, v165
	s_waitcnt lgkmcnt(0)
	v_pk_mul_f32 v[118:119], v[118:119], v[132:133] op_sel_hi:[1,0]
	v_pk_mul_f32 v[116:117], v[116:117], v[132:133] op_sel_hi:[1,0]
	v_lshlrev_b32_e32 v138, 16, v166
	v_and_b32_e32 v139, 0xffff0000, v166
	v_lshlrev_b32_e32 v140, 16, v167
	v_and_b32_e32 v141, 0xffff0000, v167
	v_pk_fma_f32 v[118:119], v[126:127], v[118:119], v[136:137]
	v_pk_fma_f32 v[116:117], v[124:125], v[116:117], v[134:135]
	v_pk_mul_f32 v[114:115], v[114:115], v[132:133] op_sel_hi:[1,0]
	v_pk_mul_f32 v[112:113], v[112:113], v[132:133] op_sel_hi:[1,0]
	v_pk_fma_f32 v[134:135], v[122:123], v[114:115], v[140:141]
	v_pk_fma_f32 v[114:115], v[120:121], v[112:113], v[138:139]
	v_mul_f32_e32 v112, v117, v117
	v_mul_f32_e32 v113, v119, v119
	v_fmac_f32_e32 v112, v116, v116
	v_fmac_f32_e32 v113, v118, v118
	v_add_f32_e32 v112, v112, v113
	v_mul_f32_e32 v113, v115, v115
	v_mul_f32_e32 v129, v135, v135
	v_fmac_f32_e32 v113, v114, v114
	v_fmac_f32_e32 v129, v134, v134
	v_add_f32_e32 v113, v113, v129
	v_add_f32_e32 v129, v112, v113
	v_cvt_pk_bf16_f32 v112, v116, v117
	v_cvt_pk_bf16_f32 v113, v118, v119
	v_lshlrev_b32_e32 v116, 16, v160
	v_and_b32_e32 v117, 0xffff0000, v160
	v_lshlrev_b32_e32 v118, 16, v161
	v_and_b32_e32 v119, 0xffff0000, v161
	v_pk_mul_f32 v[102:103], v[102:103], v[132:133] op_sel_hi:[1,0]
	v_pk_mul_f32 v[100:101], v[100:101], v[132:133] op_sel_hi:[1,0]
	v_lshlrev_b32_e32 v136, 16, v162
	v_and_b32_e32 v137, 0xffff0000, v162
	v_pk_fma_f32 v[102:103], v[110:111], v[102:103], v[118:119]
	v_pk_fma_f32 v[100:101], v[108:109], v[100:101], v[116:117]
	v_pk_mul_f32 v[96:97], v[96:97], v[132:133] op_sel_hi:[1,0]
	v_lshlrev_b32_e32 v138, 16, v163
	v_and_b32_e32 v139, 0xffff0000, v163
	v_pk_mul_f32 v[98:99], v[98:99], v[132:133] op_sel_hi:[1,0]
	v_pk_fma_f32 v[118:119], v[104:105], v[96:97], v[136:137]
	v_mul_f32_e32 v96, v101, v101
	v_mul_f32_e32 v97, v103, v103
	v_pk_fma_f32 v[116:117], v[106:107], v[98:99], v[138:139]
	v_fmac_f32_e32 v96, v100, v100
	v_fmac_f32_e32 v97, v102, v102
	v_add_f32_e32 v96, v96, v97
	v_mul_f32_e32 v97, v119, v119
	v_mul_f32_e32 v98, v117, v117
	v_fmac_f32_e32 v97, v118, v118
	v_fmac_f32_e32 v98, v116, v116
	v_add_f32_e32 v97, v97, v98
	v_add_f32_e32 v96, v96, v97
	v_add_f32_e32 v96, v129, v96
	ds_bpermute_b32 v97, v230, v96
	v_add_u32_e32 v128, 16, v207
	v_add_u32_e32 v130, s82, v128
	v_ashrrev_i32_e32 v131, 31, v130
	v_lshlrev_b64 v[130:131], 11, v[130:131]
	s_waitcnt lgkmcnt(0)
	v_add_f32_e32 v96, v96, v97
	ds_bpermute_b32 v97, v231, v96
	v_lshl_add_u64 v[130:131], v[204:205], 0, v[130:131]
	v_cvt_pk_bf16_f32 v114, v114, v115
	v_cvt_pk_bf16_f32 v115, v134, v135
	global_store_dwordx4 v[130:131], v[112:115], off
	v_cvt_pk_bf16_f32 v98, v100, v101
	v_cvt_pk_bf16_f32 v99, v102, v103
	v_cvt_pk_bf16_f32 v100, v118, v119
	v_cvt_pk_bf16_f32 v101, v116, v117
	global_store_dwordx4 v[130:131], v[98:101], off offset:256
	s_and_saveexec_b64 s[12:13], s[10:11]
	s_cbranch_execz .LBB0_922
	s_waitcnt lgkmcnt(0)
	v_add_f32_e32 v96, v96, v97
	v_lshl_add_u32 v97, v128, 4, s81
	ds_write_b32 v97, v96
.LBB0_922:
	s_or_b64 exec, exec, s[12:13]
	ds_read_b32 v100, v206 offset:128
	v_lshlrev_b32_e32 v102, 16, v156
	v_and_b32_e32 v103, 0xffff0000, v156
	v_lshlrev_b32_e32 v112, 16, v157
	v_and_b32_e32 v113, 0xffff0000, v157
	s_waitcnt lgkmcnt(0)
	v_pk_mul_f32 v[94:95], v[94:95], v[100:101] op_sel_hi:[1,0]
	v_pk_mul_f32 v[92:93], v[92:93], v[100:101] op_sel_hi:[1,0]
	v_lshlrev_b32_e32 v114, 16, v158
	v_and_b32_e32 v115, 0xffff0000, v158
	v_lshlrev_b32_e32 v116, 16, v159
	v_and_b32_e32 v117, 0xffff0000, v159
	v_pk_fma_f32 v[94:95], v[126:127], v[94:95], v[112:113]
	v_pk_fma_f32 v[92:93], v[124:125], v[92:93], v[102:103]
	v_pk_mul_f32 v[90:91], v[90:91], v[100:101] op_sel_hi:[1,0]
	v_pk_mul_f32 v[88:89], v[88:89], v[100:101] op_sel_hi:[1,0]
	v_pk_fma_f32 v[102:103], v[122:123], v[90:91], v[116:117]
	v_pk_fma_f32 v[90:91], v[120:121], v[88:89], v[114:115]
	v_mul_f32_e32 v88, v93, v93
	v_mul_f32_e32 v89, v95, v95
	v_fmac_f32_e32 v88, v92, v92
	v_fmac_f32_e32 v89, v94, v94
	v_add_f32_e32 v88, v88, v89
	v_mul_f32_e32 v89, v91, v91
	v_mul_f32_e32 v97, v103, v103
	v_fmac_f32_e32 v89, v90, v90
	v_fmac_f32_e32 v97, v102, v102
	v_add_f32_e32 v89, v89, v97
	v_add_f32_e32 v97, v88, v89
	v_cvt_pk_bf16_f32 v88, v92, v93
	v_cvt_pk_bf16_f32 v89, v94, v95
	v_lshlrev_b32_e32 v92, 16, v152
	v_and_b32_e32 v93, 0xffff0000, v152
	v_lshlrev_b32_e32 v94, 16, v153
	v_and_b32_e32 v95, 0xffff0000, v153
	v_pk_mul_f32 v[86:87], v[86:87], v[100:101] op_sel_hi:[1,0]
	v_pk_mul_f32 v[84:85], v[84:85], v[100:101] op_sel_hi:[1,0]
	v_lshlrev_b32_e32 v112, 16, v154
	v_and_b32_e32 v113, 0xffff0000, v154
	v_pk_fma_f32 v[86:87], v[110:111], v[86:87], v[94:95]
	v_pk_fma_f32 v[84:85], v[108:109], v[84:85], v[92:93]
	v_pk_mul_f32 v[80:81], v[80:81], v[100:101] op_sel_hi:[1,0]
	v_lshlrev_b32_e32 v114, 16, v155
	v_and_b32_e32 v115, 0xffff0000, v155
	v_pk_mul_f32 v[82:83], v[82:83], v[100:101] op_sel_hi:[1,0]
	v_pk_fma_f32 v[94:95], v[104:105], v[80:81], v[112:113]
	v_mul_f32_e32 v80, v85, v85
	v_mul_f32_e32 v81, v87, v87
	v_pk_fma_f32 v[92:93], v[106:107], v[82:83], v[114:115]
	v_fmac_f32_e32 v80, v84, v84
	v_fmac_f32_e32 v81, v86, v86
	v_add_f32_e32 v80, v80, v81
	v_mul_f32_e32 v81, v95, v95
	v_mul_f32_e32 v82, v93, v93
	v_fmac_f32_e32 v81, v94, v94
	v_fmac_f32_e32 v82, v92, v92
	v_add_f32_e32 v81, v81, v82
	v_add_f32_e32 v80, v80, v81
	v_add_f32_e32 v80, v97, v80
	ds_bpermute_b32 v81, v230, v80
	v_add_u32_e32 v96, 32, v207
	v_add_u32_e32 v98, s82, v96
	v_ashrrev_i32_e32 v99, 31, v98
	v_lshlrev_b64 v[98:99], 11, v[98:99]
	s_waitcnt lgkmcnt(0)
	v_add_f32_e32 v80, v80, v81
	ds_bpermute_b32 v81, v231, v80
	v_lshl_add_u64 v[98:99], v[204:205], 0, v[98:99]
	v_cvt_pk_bf16_f32 v90, v90, v91
	v_cvt_pk_bf16_f32 v91, v102, v103
	global_store_dwordx4 v[98:99], v[88:91], off
	v_cvt_pk_bf16_f32 v82, v84, v85
	v_cvt_pk_bf16_f32 v83, v86, v87
	v_cvt_pk_bf16_f32 v84, v94, v95
	v_cvt_pk_bf16_f32 v85, v92, v93
	global_store_dwordx4 v[98:99], v[82:85], off offset:256
	s_and_saveexec_b64 s[12:13], s[10:11]
	s_cbranch_execz .LBB0_924
	s_waitcnt lgkmcnt(0)
	v_add_f32_e32 v80, v80, v81
	v_lshl_add_u32 v81, v96, 4, s81
	ds_write_b32 v81, v80
.LBB0_924:
	s_or_b64 exec, exec, s[12:13]
	ds_read_b32 v84, v206 offset:192
	v_lshlrev_b32_e32 v86, 16, v148
	v_and_b32_e32 v87, 0xffff0000, v148
	v_lshlrev_b32_e32 v88, 16, v149
	v_and_b32_e32 v89, 0xffff0000, v149
	s_waitcnt lgkmcnt(0)
	v_pk_mul_f32 v[78:79], v[78:79], v[84:85] op_sel_hi:[1,0]
	v_pk_mul_f32 v[76:77], v[76:77], v[84:85] op_sel_hi:[1,0]
	v_lshlrev_b32_e32 v90, 16, v150
	v_and_b32_e32 v91, 0xffff0000, v150
	v_lshlrev_b32_e32 v92, 16, v151
	v_and_b32_e32 v93, 0xffff0000, v151
	v_pk_fma_f32 v[78:79], v[126:127], v[78:79], v[88:89]
	v_pk_fma_f32 v[76:77], v[124:125], v[76:77], v[86:87]
	v_pk_mul_f32 v[74:75], v[74:75], v[84:85] op_sel_hi:[1,0]
	v_pk_mul_f32 v[72:73], v[72:73], v[84:85] op_sel_hi:[1,0]
	v_pk_fma_f32 v[86:87], v[122:123], v[74:75], v[92:93]
	v_pk_fma_f32 v[74:75], v[120:121], v[72:73], v[90:91]
	v_mul_f32_e32 v72, v77, v77
	v_mul_f32_e32 v73, v79, v79
	v_fmac_f32_e32 v72, v76, v76
	v_fmac_f32_e32 v73, v78, v78
	v_add_f32_e32 v72, v72, v73
	v_mul_f32_e32 v73, v75, v75
	v_mul_f32_e32 v81, v87, v87
	v_fmac_f32_e32 v73, v74, v74
	v_fmac_f32_e32 v81, v86, v86
	v_add_f32_e32 v73, v73, v81
	v_add_f32_e32 v81, v72, v73
	v_cvt_pk_bf16_f32 v72, v76, v77
	v_cvt_pk_bf16_f32 v73, v78, v79
	v_lshlrev_b32_e32 v76, 16, v144
	v_and_b32_e32 v77, 0xffff0000, v144
	v_lshlrev_b32_e32 v78, 16, v145
	v_and_b32_e32 v79, 0xffff0000, v145
	v_pk_mul_f32 v[70:71], v[70:71], v[84:85] op_sel_hi:[1,0]
	v_pk_mul_f32 v[68:69], v[68:69], v[84:85] op_sel_hi:[1,0]
	v_lshlrev_b32_e32 v88, 16, v146
	v_and_b32_e32 v89, 0xffff0000, v146
	v_pk_fma_f32 v[70:71], v[110:111], v[70:71], v[78:79]
	v_pk_fma_f32 v[68:69], v[108:109], v[68:69], v[76:77]
	v_pk_mul_f32 v[64:65], v[64:65], v[84:85] op_sel_hi:[1,0]
	v_lshlrev_b32_e32 v90, 16, v147
	v_and_b32_e32 v91, 0xffff0000, v147
	v_pk_mul_f32 v[66:67], v[66:67], v[84:85] op_sel_hi:[1,0]
	v_pk_fma_f32 v[78:79], v[104:105], v[64:65], v[88:89]
	v_mul_f32_e32 v64, v69, v69
	v_mul_f32_e32 v65, v71, v71
	v_pk_fma_f32 v[76:77], v[106:107], v[66:67], v[90:91]
	v_fmac_f32_e32 v64, v68, v68
	v_fmac_f32_e32 v65, v70, v70
	v_add_f32_e32 v64, v64, v65
	v_mul_f32_e32 v65, v79, v79
	v_mul_f32_e32 v66, v77, v77
	v_fmac_f32_e32 v65, v78, v78
	v_fmac_f32_e32 v66, v76, v76
	v_add_f32_e32 v65, v65, v66
	v_add_f32_e32 v64, v64, v65
	v_add_f32_e32 v64, v81, v64
	ds_bpermute_b32 v65, v230, v64
	v_add_u32_e32 v80, 48, v207
	v_add_u32_e32 v82, s82, v80
	v_ashrrev_i32_e32 v83, 31, v82
	v_lshlrev_b64 v[82:83], 11, v[82:83]
	s_waitcnt lgkmcnt(0)
	v_add_f32_e32 v64, v64, v65
	ds_bpermute_b32 v65, v231, v64
	v_lshl_add_u64 v[82:83], v[204:205], 0, v[82:83]
	v_cvt_pk_bf16_f32 v74, v74, v75
	v_cvt_pk_bf16_f32 v75, v86, v87
	global_store_dwordx4 v[82:83], v[72:75], off
	v_cvt_pk_bf16_f32 v66, v68, v69
	v_cvt_pk_bf16_f32 v67, v70, v71
	v_cvt_pk_bf16_f32 v68, v78, v79
	v_cvt_pk_bf16_f32 v69, v76, v77
	global_store_dwordx4 v[82:83], v[66:69], off offset:256
	s_and_saveexec_b64 s[12:13], s[10:11]
	s_cbranch_execz .LBB0_926
	s_waitcnt lgkmcnt(0)
	v_add_f32_e32 v64, v64, v65
	v_lshl_add_u32 v65, v80, 4, s81
	ds_write_b32 v65, v64
.LBB0_926:
	s_or_b64 exec, exec, s[12:13]
	v_add_u32_e32 v64, 0x80, v207
	v_add_u32_e32 v66, s82, v64
	v_ashrrev_i32_e32 v67, 31, v66
	v_lshlrev_b64 v[66:67], 11, v[66:67]
	v_lshl_add_u64 v[70:71], v[204:205], 0, v[66:67]
	ds_read_b32 v72, v206 offset:512
	s_waitcnt lgkmcnt(0)
	v_pk_mul_f32 v[62:63], v[62:63], v[72:73] op_sel_hi:[1,0]
	v_pk_mul_f32 v[60:61], v[60:61], v[72:73] op_sel_hi:[1,0]
	v_pk_mul_f32 v[58:59], v[58:59], v[72:73] op_sel_hi:[1,0]
	v_pk_mul_f32 v[56:57], v[56:57], v[72:73] op_sel_hi:[1,0]
	v_pk_mul_f32 v[54:55], v[54:55], v[72:73] op_sel_hi:[1,0]
	v_pk_mul_f32 v[52:53], v[52:53], v[72:73] op_sel_hi:[1,0]
	v_pk_mul_f32 v[50:51], v[50:51], v[72:73] op_sel_hi:[1,0]
	v_pk_mul_f32 v[48:49], v[48:49], v[72:73] op_sel_hi:[1,0]
	v_lshlrev_b32_e32 v74, 16, v236
	v_and_b32_e32 v75, 0xffff0000, v236
	v_lshlrev_b32_e32 v66, 16, v237
	v_and_b32_e32 v67, 0xffff0000, v237
	v_lshlrev_b32_e32 v76, 16, v238
	v_and_b32_e32 v77, 0xffff0000, v238
	v_lshlrev_b32_e32 v68, 16, v239
	v_and_b32_e32 v69, 0xffff0000, v239
	v_pk_fma_f32 v[66:67], v[126:127], v[62:63], v[66:67]
	v_pk_fma_f32 v[74:75], v[124:125], v[60:61], v[74:75]
	v_pk_fma_f32 v[68:69], v[122:123], v[58:59], v[68:69]
	v_pk_fma_f32 v[76:77], v[120:121], v[56:57], v[76:77]
	v_cvt_pk_bf16_f32 v56, v74, v75
	v_cvt_pk_bf16_f32 v57, v66, v67
	v_mul_f32_e32 v65, v75, v75
	v_cvt_pk_bf16_f32 v58, v76, v77
	v_cvt_pk_bf16_f32 v59, v68, v69
	v_mul_f32_e32 v67, v67, v67
	v_mul_f32_e32 v72, v77, v77
	v_mul_f32_e32 v69, v69, v69
	v_fmac_f32_e32 v65, v74, v74
	v_fmac_f32_e32 v67, v66, v66
	v_fmac_f32_e32 v72, v76, v76
	v_fmac_f32_e32 v69, v68, v68
	v_add_f32_e32 v65, v65, v67
	v_add_f32_e32 v66, v72, v69
	v_add_f32_e32 v65, v65, v66
	global_store_dwordx4 v[70:71], v[56:59], off
	v_lshlrev_b32_e32 v66, 16, v240
	v_and_b32_e32 v67, 0xffff0000, v240
	v_lshlrev_b32_e32 v60, 16, v241
	v_and_b32_e32 v61, 0xffff0000, v241
	v_lshlrev_b32_e32 v68, 16, v242
	v_and_b32_e32 v69, 0xffff0000, v242
	v_lshlrev_b32_e32 v62, 16, v243
	v_and_b32_e32 v63, 0xffff0000, v243
	v_pk_fma_f32 v[54:55], v[110:111], v[54:55], v[60:61]
	v_pk_fma_f32 v[52:53], v[108:109], v[52:53], v[66:67]
	v_pk_fma_f32 v[60:61], v[106:107], v[50:51], v[62:63]
	v_pk_fma_f32 v[62:63], v[104:105], v[48:49], v[68:69]
	v_mul_f32_e32 v48, v53, v53
	v_mul_f32_e32 v49, v55, v55
	v_mul_f32_e32 v50, v63, v63
	v_mul_f32_e32 v51, v61, v61
	v_fmac_f32_e32 v48, v52, v52
	v_fmac_f32_e32 v49, v54, v54
	v_fmac_f32_e32 v50, v62, v62
	v_fmac_f32_e32 v51, v60, v60
	v_add_f32_e32 v48, v48, v49
	v_add_f32_e32 v49, v50, v51
	v_add_f32_e32 v48, v48, v49
	v_add_f32_e32 v48, v65, v48
	ds_bpermute_b32 v49, v230, v48
	v_cvt_pk_bf16_f32 v50, v52, v53
	v_cvt_pk_bf16_f32 v51, v54, v55
	v_cvt_pk_bf16_f32 v52, v62, v63
	v_cvt_pk_bf16_f32 v53, v60, v61
	s_waitcnt lgkmcnt(0)
	v_add_f32_e32 v48, v48, v49
	ds_bpermute_b32 v49, v231, v48
	global_store_dwordx4 v[70:71], v[50:53], off offset:256
	s_and_saveexec_b64 s[12:13], s[10:11]
	s_cbranch_execz .LBB0_928
	s_waitcnt lgkmcnt(0)
	v_add_f32_e32 v48, v48, v49
	v_lshl_add_u32 v49, v64, 4, s81
	ds_write_b32 v49, v48
.LBB0_928:
	s_or_b64 exec, exec, s[12:13]
	v_add_u32_e32 v48, 0x90, v207
	v_add_u32_e32 v50, s82, v48
	v_ashrrev_i32_e32 v51, 31, v50
	v_lshlrev_b64 v[50:51], 11, v[50:51]
	v_lshl_add_u64 v[54:55], v[204:205], 0, v[50:51]
	ds_read_b32 v56, v206 offset:576
	s_waitcnt lgkmcnt(0)
	v_pk_mul_f32 v[46:47], v[46:47], v[56:57] op_sel_hi:[1,0]
	v_pk_mul_f32 v[44:45], v[44:45], v[56:57] op_sel_hi:[1,0]
	v_pk_mul_f32 v[42:43], v[42:43], v[56:57] op_sel_hi:[1,0]
	v_pk_mul_f32 v[40:41], v[40:41], v[56:57] op_sel_hi:[1,0]
	v_pk_mul_f32 v[38:39], v[38:39], v[56:57] op_sel_hi:[1,0]
	v_pk_mul_f32 v[36:37], v[36:37], v[56:57] op_sel_hi:[1,0]
	v_pk_mul_f32 v[34:35], v[34:35], v[56:57] op_sel_hi:[1,0]
	v_pk_mul_f32 v[32:33], v[32:33], v[56:57] op_sel_hi:[1,0]
	v_lshlrev_b32_e32 v58, 16, v244
	v_and_b32_e32 v59, 0xffff0000, v244
	v_lshlrev_b32_e32 v50, 16, v245
	v_and_b32_e32 v51, 0xffff0000, v245
	v_lshlrev_b32_e32 v60, 16, v246
	v_and_b32_e32 v61, 0xffff0000, v246
	v_lshlrev_b32_e32 v52, 16, v247
	v_and_b32_e32 v53, 0xffff0000, v247
	v_pk_fma_f32 v[50:51], v[126:127], v[46:47], v[50:51]
	v_pk_fma_f32 v[58:59], v[124:125], v[44:45], v[58:59]
	v_pk_fma_f32 v[52:53], v[122:123], v[42:43], v[52:53]
	v_pk_fma_f32 v[60:61], v[120:121], v[40:41], v[60:61]
	v_cvt_pk_bf16_f32 v40, v58, v59
	v_cvt_pk_bf16_f32 v41, v50, v51
	v_mul_f32_e32 v49, v59, v59
	v_cvt_pk_bf16_f32 v42, v60, v61
	v_cvt_pk_bf16_f32 v43, v52, v53
	v_mul_f32_e32 v51, v51, v51
	v_mul_f32_e32 v56, v61, v61
	v_mul_f32_e32 v53, v53, v53
	v_fmac_f32_e32 v49, v58, v58
	v_fmac_f32_e32 v51, v50, v50
	v_fmac_f32_e32 v56, v60, v60
	v_fmac_f32_e32 v53, v52, v52
	v_add_f32_e32 v49, v49, v51
	v_add_f32_e32 v50, v56, v53
	v_add_f32_e32 v49, v49, v50
	global_store_dwordx4 v[54:55], v[40:43], off
	v_lshlrev_b32_e32 v50, 16, v248
	v_and_b32_e32 v51, 0xffff0000, v248
	v_lshlrev_b32_e32 v44, 16, v249
	v_and_b32_e32 v45, 0xffff0000, v249
	v_lshlrev_b32_e32 v52, 16, v250
	v_and_b32_e32 v53, 0xffff0000, v250
	v_lshlrev_b32_e32 v46, 16, v251
	v_and_b32_e32 v47, 0xffff0000, v251
	v_pk_fma_f32 v[38:39], v[110:111], v[38:39], v[44:45]
	v_pk_fma_f32 v[36:37], v[108:109], v[36:37], v[50:51]
	v_pk_fma_f32 v[44:45], v[106:107], v[34:35], v[46:47]
	v_pk_fma_f32 v[46:47], v[104:105], v[32:33], v[52:53]
	v_mul_f32_e32 v32, v37, v37
	v_mul_f32_e32 v33, v39, v39
	v_mul_f32_e32 v34, v47, v47
	v_mul_f32_e32 v35, v45, v45
	v_fmac_f32_e32 v32, v36, v36
	v_fmac_f32_e32 v33, v38, v38
	v_fmac_f32_e32 v34, v46, v46
	v_fmac_f32_e32 v35, v44, v44
	v_add_f32_e32 v32, v32, v33
	v_add_f32_e32 v33, v34, v35
	v_add_f32_e32 v32, v32, v33
	v_add_f32_e32 v32, v49, v32
	ds_bpermute_b32 v33, v230, v32
	v_cvt_pk_bf16_f32 v34, v36, v37
	v_cvt_pk_bf16_f32 v35, v38, v39
	v_cvt_pk_bf16_f32 v36, v46, v47
	v_cvt_pk_bf16_f32 v37, v44, v45
	s_waitcnt lgkmcnt(0)
	v_add_f32_e32 v32, v32, v33
	ds_bpermute_b32 v33, v231, v32
	global_store_dwordx4 v[54:55], v[34:37], off offset:256
	s_and_saveexec_b64 s[12:13], s[10:11]
	s_cbranch_execz .LBB0_930
	s_waitcnt lgkmcnt(0)
	v_add_f32_e32 v32, v32, v33
	v_lshl_add_u32 v33, v48, 4, s81
	ds_write_b32 v33, v32
.LBB0_930:
	s_or_b64 exec, exec, s[12:13]
	v_add_u32_e32 v32, 0xa0, v207
	v_add_u32_e32 v34, s82, v32
	v_ashrrev_i32_e32 v35, 31, v34
	v_lshlrev_b64 v[34:35], 11, v[34:35]
	v_lshl_add_u64 v[38:39], v[204:205], 0, v[34:35]
	ds_read_b32 v40, v206 offset:640
	s_waitcnt lgkmcnt(0)
	v_pk_mul_f32 v[30:31], v[30:31], v[40:41] op_sel_hi:[1,0]
	v_pk_mul_f32 v[28:29], v[28:29], v[40:41] op_sel_hi:[1,0]
	v_pk_mul_f32 v[26:27], v[26:27], v[40:41] op_sel_hi:[1,0]
	v_pk_mul_f32 v[24:25], v[24:25], v[40:41] op_sel_hi:[1,0]
	v_pk_mul_f32 v[22:23], v[22:23], v[40:41] op_sel_hi:[1,0]
	v_pk_mul_f32 v[20:21], v[20:21], v[40:41] op_sel_hi:[1,0]
	v_pk_mul_f32 v[18:19], v[18:19], v[40:41] op_sel_hi:[1,0]
	v_pk_mul_f32 v[16:17], v[16:17], v[40:41] op_sel_hi:[1,0]
	s_waitcnt vmcnt(13)
	v_lshlrev_b32_e32 v42, 16, v168
	v_and_b32_e32 v43, 0xffff0000, v168
	v_lshlrev_b32_e32 v34, 16, v169
	v_and_b32_e32 v35, 0xffff0000, v169
	v_lshlrev_b32_e32 v44, 16, v170
	v_and_b32_e32 v45, 0xffff0000, v170
	v_lshlrev_b32_e32 v36, 16, v171
	v_and_b32_e32 v37, 0xffff0000, v171
	v_pk_fma_f32 v[34:35], v[126:127], v[30:31], v[34:35]
	v_pk_fma_f32 v[42:43], v[124:125], v[28:29], v[42:43]
	v_pk_fma_f32 v[36:37], v[122:123], v[26:27], v[36:37]
	v_pk_fma_f32 v[44:45], v[120:121], v[24:25], v[44:45]
	v_cvt_pk_bf16_f32 v24, v42, v43
	v_cvt_pk_bf16_f32 v25, v34, v35
	v_mul_f32_e32 v33, v43, v43
	v_cvt_pk_bf16_f32 v26, v44, v45
	v_cvt_pk_bf16_f32 v27, v36, v37
	v_mul_f32_e32 v35, v35, v35
	v_mul_f32_e32 v40, v45, v45
	v_mul_f32_e32 v37, v37, v37
	v_fmac_f32_e32 v33, v42, v42
	v_fmac_f32_e32 v35, v34, v34
	v_fmac_f32_e32 v40, v44, v44
	v_fmac_f32_e32 v37, v36, v36
	v_add_f32_e32 v33, v33, v35
	v_add_f32_e32 v34, v40, v37
	v_add_f32_e32 v33, v33, v34
	global_store_dwordx4 v[38:39], v[24:27], off
	s_waitcnt vmcnt(13)
	v_lshlrev_b32_e32 v34, 16, v172
	v_and_b32_e32 v35, 0xffff0000, v172
	v_lshlrev_b32_e32 v28, 16, v173
	v_and_b32_e32 v29, 0xffff0000, v173
	v_lshlrev_b32_e32 v36, 16, v174
	v_and_b32_e32 v37, 0xffff0000, v174
	v_lshlrev_b32_e32 v30, 16, v175
	v_and_b32_e32 v31, 0xffff0000, v175
	v_pk_fma_f32 v[22:23], v[110:111], v[22:23], v[28:29]
	v_pk_fma_f32 v[20:21], v[108:109], v[20:21], v[34:35]
	v_pk_fma_f32 v[28:29], v[106:107], v[18:19], v[30:31]
	v_pk_fma_f32 v[30:31], v[104:105], v[16:17], v[36:37]
	v_mul_f32_e32 v16, v21, v21
	v_mul_f32_e32 v17, v23, v23
	v_mul_f32_e32 v18, v31, v31
	v_mul_f32_e32 v19, v29, v29
	v_fmac_f32_e32 v16, v20, v20
	v_fmac_f32_e32 v17, v22, v22
	v_fmac_f32_e32 v18, v30, v30
	v_fmac_f32_e32 v19, v28, v28
	v_add_f32_e32 v16, v16, v17
	v_add_f32_e32 v17, v18, v19
	v_add_f32_e32 v16, v16, v17
	v_add_f32_e32 v16, v33, v16
	ds_bpermute_b32 v17, v230, v16
	v_cvt_pk_bf16_f32 v18, v20, v21
	v_cvt_pk_bf16_f32 v19, v22, v23
	v_cvt_pk_bf16_f32 v20, v30, v31
	v_cvt_pk_bf16_f32 v21, v28, v29
	s_waitcnt lgkmcnt(0)
	v_add_f32_e32 v16, v16, v17
	ds_bpermute_b32 v17, v231, v16
	global_store_dwordx4 v[38:39], v[18:21], off offset:256
	s_and_saveexec_b64 s[12:13], s[10:11]
	s_cbranch_execz .LBB0_932
	s_waitcnt lgkmcnt(0)
	v_add_f32_e32 v16, v16, v17
	v_lshl_add_u32 v17, v32, 4, s81
	ds_write_b32 v17, v16
.LBB0_932:
	s_or_b64 exec, exec, s[12:13]
	v_add_u32_e32 v16, 0xb0, v207
	v_add_u32_e32 v18, s82, v16
	v_ashrrev_i32_e32 v19, 31, v18
	v_lshlrev_b64 v[18:19], 11, v[18:19]
	v_lshl_add_u64 v[22:23], v[204:205], 0, v[18:19]
	ds_read_b32 v24, v206 offset:704
	s_waitcnt lgkmcnt(0)
	v_pk_mul_f32 v[14:15], v[14:15], v[24:25] op_sel_hi:[1,0]
	v_pk_mul_f32 v[12:13], v[12:13], v[24:25] op_sel_hi:[1,0]
	v_pk_mul_f32 v[10:11], v[10:11], v[24:25] op_sel_hi:[1,0]
	v_pk_mul_f32 v[8:9], v[8:9], v[24:25] op_sel_hi:[1,0]
	v_pk_mul_f32 v[6:7], v[6:7], v[24:25] op_sel_hi:[1,0]
	v_pk_mul_f32 v[4:5], v[4:5], v[24:25] op_sel_hi:[1,0]
	v_pk_mul_f32 v[2:3], v[2:3], v[24:25] op_sel_hi:[1,0]
	v_pk_mul_f32 v[0:1], v[0:1], v[24:25] op_sel_hi:[1,0]
	s_waitcnt vmcnt(13)
	v_lshlrev_b32_e32 v26, 16, v208
	v_and_b32_e32 v27, 0xffff0000, v208
	v_lshlrev_b32_e32 v18, 16, v209
	v_and_b32_e32 v19, 0xffff0000, v209
	v_lshlrev_b32_e32 v28, 16, v210
	v_and_b32_e32 v29, 0xffff0000, v210
	v_lshlrev_b32_e32 v20, 16, v211
	v_and_b32_e32 v21, 0xffff0000, v211
	v_pk_fma_f32 v[18:19], v[126:127], v[14:15], v[18:19]
	v_pk_fma_f32 v[26:27], v[124:125], v[12:13], v[26:27]
	v_pk_fma_f32 v[20:21], v[122:123], v[10:11], v[20:21]
	v_pk_fma_f32 v[28:29], v[120:121], v[8:9], v[28:29]
	v_cvt_pk_bf16_f32 v8, v26, v27
	v_cvt_pk_bf16_f32 v9, v18, v19
	v_mul_f32_e32 v17, v27, v27
	v_cvt_pk_bf16_f32 v10, v28, v29
	v_cvt_pk_bf16_f32 v11, v20, v21
	v_mul_f32_e32 v19, v19, v19
	v_mul_f32_e32 v24, v29, v29
	v_mul_f32_e32 v21, v21, v21
	v_fmac_f32_e32 v17, v26, v26
	v_fmac_f32_e32 v19, v18, v18
	v_fmac_f32_e32 v24, v28, v28
	v_fmac_f32_e32 v21, v20, v20
	v_add_f32_e32 v17, v17, v19
	v_add_f32_e32 v18, v24, v21
	v_add_f32_e32 v17, v17, v18
	global_store_dwordx4 v[22:23], v[8:11], off
	s_waitcnt vmcnt(13)
	v_lshlrev_b32_e32 v18, 16, v212
	v_and_b32_e32 v19, 0xffff0000, v212
	v_lshlrev_b32_e32 v12, 16, v213
	v_and_b32_e32 v13, 0xffff0000, v213
	v_lshlrev_b32_e32 v20, 16, v214
	v_and_b32_e32 v21, 0xffff0000, v214
	v_lshlrev_b32_e32 v14, 16, v215
	v_and_b32_e32 v15, 0xffff0000, v215
	v_pk_fma_f32 v[6:7], v[110:111], v[6:7], v[12:13]
	v_pk_fma_f32 v[4:5], v[108:109], v[4:5], v[18:19]
	v_pk_fma_f32 v[12:13], v[106:107], v[2:3], v[14:15]
	v_pk_fma_f32 v[14:15], v[104:105], v[0:1], v[20:21]
	v_mul_f32_e32 v0, v5, v5
	v_mul_f32_e32 v1, v7, v7
	v_mul_f32_e32 v2, v15, v15
	v_mul_f32_e32 v3, v13, v13
	v_fmac_f32_e32 v0, v4, v4
	v_fmac_f32_e32 v1, v6, v6
	v_fmac_f32_e32 v2, v14, v14
	v_fmac_f32_e32 v3, v12, v12
	v_add_f32_e32 v0, v0, v1
	v_add_f32_e32 v1, v2, v3
	v_add_f32_e32 v0, v0, v1
	v_add_f32_e32 v0, v17, v0
	ds_bpermute_b32 v1, v230, v0
	v_cvt_pk_bf16_f32 v2, v4, v5
	v_cvt_pk_bf16_f32 v3, v6, v7
	v_cvt_pk_bf16_f32 v4, v14, v15
	v_cvt_pk_bf16_f32 v5, v12, v13
	s_waitcnt lgkmcnt(0)
	v_add_f32_e32 v0, v0, v1
	ds_bpermute_b32 v1, v231, v0
	global_store_dwordx4 v[22:23], v[2:5], off offset:256
	s_and_saveexec_b64 s[12:13], s[10:11]
	s_cbranch_execz .LBB0_934
	s_waitcnt lgkmcnt(0)
	v_add_f32_e32 v0, v0, v1
	v_lshl_add_u32 v1, v16, 4, s81
	ds_write_b32 v1, v0

.LBB0_1264:
	s_or_b64 exec, exec, s[52:53]
	s_lshl_b32 s51, s14, 8
	s_lshl_b32 s52, s15, 5
	s_add_i32 s52, s52, s51
	s_lshl_b32 s51, s12, 8
	s_lshl_b32 s85, s13, 6
	v_lshl_add_u32 v144, v206, 3, s52
	s_add_i32 s12, s85, s51
	v_ashrrev_i32_e32 v145, 31, v144
	v_add_u32_e32 v146, s12, v232
	s_waitcnt vmcnt(0)
	v_lshl_add_u64 v[104:105], v[144:145], 2, v[104:105]
	v_lshl_add_u64 v[144:145], v[144:145], 1, v[202:203]
	v_ashrrev_i32_e32 v147, 31, v146
	v_lshl_add_u64 v[108:109], v[104:105], 0, s[36:37]
	v_add_co_u32_e32 v104, vcc, 0x1000, v104
	v_lshl_add_u64 v[204:205], v[144:145], 0, s[38:39]
	v_lshlrev_b64 v[144:145], 11, v[146:147]
	s_waitcnt lgkmcnt(0)
	s_barrier
	v_addc_co_u32_e32 v105, vcc, 0, v105, vcc
	v_lshl_add_u64 v[144:145], v[204:205], 0, v[144:145]
	global_load_dwordx4 v[124:127], v[104:105], off
	s_waitcnt lgkmcnt(0)
	global_load_dwordx4 v[104:107], v[108:109], off offset:528
	global_load_dwordx4 v[120:123], v[108:109], off offset:16
	s_nop 0
	global_load_dwordx4 v[108:111], v[108:109], off offset:512
	s_nop 0
	global_load_dwordx4 v[172:175], v[144:145], off
	global_load_dwordx4 v[168:171], v[144:145], off offset:256
	v_add_u32_e32 v144, 16, v146
	v_ashrrev_i32_e32 v145, 31, v144
	v_lshlrev_b64 v[144:145], 11, v[144:145]
	v_lshl_add_u64 v[144:145], v[204:205], 0, v[144:145]
	global_load_dwordx4 v[164:167], v[144:145], off
	global_load_dwordx4 v[160:163], v[144:145], off offset:256
	v_add_u32_e32 v144, 32, v146
	v_ashrrev_i32_e32 v145, 31, v144
	v_lshlrev_b64 v[144:145], 11, v[144:145]
	v_lshl_add_u64 v[144:145], v[204:205], 0, v[144:145]
	global_load_dwordx4 v[156:159], v[144:145], off
	global_load_dwordx4 v[152:155], v[144:145], off offset:256
	v_add_u32_e32 v144, 0x80, v146
	v_ashrrev_i32_e32 v145, 31, v144
	v_lshlrev_b64 v[144:145], 11, v[144:145]
	v_lshl_add_u64 v[144:145], v[204:205], 0, v[144:145]
	global_load_dwordx4 v[236:239], v[144:145], off
	global_load_dwordx4 v[240:243], v[144:145], off offset:256
	v_add_u32_e32 v144, 0x90, v146
	v_ashrrev_i32_e32 v145, 31, v144
	v_lshlrev_b64 v[144:145], 11, v[144:145]
	v_lshl_add_u64 v[144:145], v[204:205], 0, v[144:145]
	global_load_dwordx4 v[244:247], v[144:145], off
	global_load_dwordx4 v[248:251], v[144:145], off offset:256
	v_add_u32_e32 v144, 48, v146
	v_ashrrev_i32_e32 v145, 31, v144
	v_lshlrev_b64 v[144:145], 11, v[144:145]
	v_lshl_add_u64 v[144:145], v[204:205], 0, v[144:145]
	global_load_dwordx4 v[148:151], v[144:145], off
	s_nop 0
	global_load_dwordx4 v[144:147], v[144:145], off offset:256
	s_lshl_b32 s12, s13, 2
	v_lshl_add_u32 v206, v206, 4, v232
	s_add_i32 s12, s12, s15
	v_cmp_gt_i32_e32 vcc, 32, v206
	v_lshl_add_u32 v231, s12, 5, v206
	s_and_saveexec_b64 s[52:53], vcc
	s_cbranch_execz .LBB0_1279
	v_lshl_add_u32 v206, v231, 4, v227
	ds_read_b128 v[208:211], v206
	v_add_u32_e32 v206, s51, v231
	v_ashrrev_i32_e32 v207, 31, v206
	v_lshlrev_b64 v[206:207], 5, v[206:207]
	v_lshl_add_u64 v[206:207], v[202:203], 0, v[206:207]
	s_waitcnt lgkmcnt(0)
	v_mov_b32_e32 v214, v209
	v_mov_b32_e32 v215, v210
	v_mov_b32_e32 v209, v211
	v_pk_add_f32 v[208:209], v[214:215], v[208:209]
	v_lshl_add_u64 v[206:207], v[206:207], 0, s[40:41]
	s_ashr_i32 s15, s14, 31
	v_pk_add_f32 v[208:209], v[208:209], v[208:209] op_sel:[0,1] op_sel_hi:[1,0]
	v_lshl_add_u64 v[212:213], s[14:15], 3, v[206:207]
	v_mov_b32_e32 v209, v217
	s_mov_b32 s15, 0x100000
	s_mov_b64 s[54:55], 0
	global_store_dwordx2 v[212:213], v[208:209], off sc1
	s_branch .LBB0_1271

.LBB0_1279:
	s_or_b64 exec, exec, s[52:53]
	v_add_u32_e32 v207, s85, v232
	s_waitcnt vmcnt(0) lgkmcnt(0)
	s_barrier
	v_lshl_add_u32 v206, v207, 2, v228
	ds_read_b32 v210, v206
	v_lshlrev_b32_e32 v212, 16, v172
	v_and_b32_e32 v213, 0xffff0000, v172
	v_lshlrev_b32_e32 v172, 16, v173
	v_and_b32_e32 v173, 0xffff0000, v173
	s_waitcnt lgkmcnt(0)
	v_pk_mul_f32 v[142:143], v[142:143], v[210:211] op_sel_hi:[1,0]
	v_pk_mul_f32 v[140:141], v[140:141], v[210:211] op_sel_hi:[1,0]
	v_lshlrev_b32_e32 v214, 16, v174
	v_and_b32_e32 v215, 0xffff0000, v174
	v_lshlrev_b32_e32 v174, 16, v175
	v_and_b32_e32 v175, 0xffff0000, v175
	v_pk_fma_f32 v[142:143], v[126:127], v[142:143], v[172:173]
	v_pk_fma_f32 v[140:141], v[124:125], v[140:141], v[212:213]
	v_pk_mul_f32 v[138:139], v[138:139], v[210:211] op_sel_hi:[1,0]
	v_pk_mul_f32 v[136:137], v[136:137], v[210:211] op_sel_hi:[1,0]
	v_pk_fma_f32 v[172:173], v[122:123], v[138:139], v[174:175]
	v_pk_fma_f32 v[138:139], v[120:121], v[136:137], v[214:215]
	v_mul_f32_e32 v136, v141, v141
	v_mul_f32_e32 v137, v143, v143
	v_fmac_f32_e32 v136, v140, v140
	v_fmac_f32_e32 v137, v142, v142
	v_add_f32_e32 v136, v136, v137
	v_mul_f32_e32 v137, v139, v139
	v_mul_f32_e32 v174, v173, v173
	v_fmac_f32_e32 v137, v138, v138
	v_fmac_f32_e32 v174, v172, v172
	v_add_f32_e32 v137, v137, v174
	v_add_f32_e32 v174, v136, v137
	v_cvt_pk_bf16_f32 v136, v140, v141
	v_cvt_pk_bf16_f32 v137, v142, v143
	v_lshlrev_b32_e32 v140, 16, v168
	v_and_b32_e32 v141, 0xffff0000, v168
	v_lshlrev_b32_e32 v142, 16, v169
	v_and_b32_e32 v143, 0xffff0000, v169
	v_pk_mul_f32 v[134:135], v[134:135], v[210:211] op_sel_hi:[1,0]
	v_pk_mul_f32 v[132:133], v[132:133], v[210:211] op_sel_hi:[1,0]
	v_lshlrev_b32_e32 v168, 16, v170
	v_and_b32_e32 v169, 0xffff0000, v170
	v_pk_fma_f32 v[134:135], v[110:111], v[134:135], v[142:143]
	v_pk_fma_f32 v[132:133], v[108:109], v[132:133], v[140:141]
	v_pk_mul_f32 v[128:129], v[128:129], v[210:211] op_sel_hi:[1,0]
	v_lshlrev_b32_e32 v170, 16, v171
	v_and_b32_e32 v171, 0xffff0000, v171
	v_pk_mul_f32 v[130:131], v[130:131], v[210:211] op_sel_hi:[1,0]
	v_pk_fma_f32 v[142:143], v[104:105], v[128:129], v[168:169]
	v_mul_f32_e32 v128, v133, v133
	v_mul_f32_e32 v129, v135, v135
	v_pk_fma_f32 v[140:141], v[106:107], v[130:131], v[170:171]
	v_fmac_f32_e32 v128, v132, v132
	v_fmac_f32_e32 v129, v134, v134
	v_add_f32_e32 v128, v128, v129
	v_mul_f32_e32 v129, v143, v143
	v_mul_f32_e32 v130, v141, v141
	v_fmac_f32_e32 v129, v142, v142
	v_fmac_f32_e32 v130, v140, v140
	v_add_f32_e32 v129, v129, v130
	v_add_f32_e32 v128, v128, v129
	v_add_f32_e32 v128, v174, v128
	ds_bpermute_b32 v129, v229, v128
	v_add_u32_e32 v208, s51, v207
	v_ashrrev_i32_e32 v209, 31, v208
	v_lshlrev_b64 v[208:209], 11, v[208:209]
	v_lshl_add_u64 v[208:209], v[204:205], 0, v[208:209]
	s_waitcnt lgkmcnt(0)
	v_add_f32_e32 v128, v128, v129
	ds_bpermute_b32 v129, v230, v128
	v_cvt_pk_bf16_f32 v138, v138, v139
	v_cvt_pk_bf16_f32 v139, v172, v173
	global_store_dwordx4 v[208:209], v[136:139], off
	v_cvt_pk_bf16_f32 v130, v132, v133
	v_cvt_pk_bf16_f32 v131, v134, v135
	v_cvt_pk_bf16_f32 v132, v142, v143
	v_cvt_pk_bf16_f32 v133, v140, v141
	global_store_dwordx4 v[208:209], v[130:133], off offset:256
	s_and_saveexec_b64 s[12:13], s[10:11]
	s_cbranch_execz .LBB0_1281
	s_waitcnt lgkmcnt(0)
	v_add_f32_e32 v128, v128, v129
	v_lshl_add_u32 v129, v207, 4, s49
	ds_write_b32 v129, v128
.LBB0_1281:
	s_or_b64 exec, exec, s[12:13]
	v_add_u32_e32 v252, 0xa0, v207
	v_add_u32_e32 v252, s51, v252
	v_ashrrev_i32_e32 v253, 31, v252
	v_lshlrev_b64 v[252:253], 11, v[252:253]
	v_lshl_add_u64 v[252:253], v[204:205], 0, v[252:253]
	global_load_dwordx4 v[168:171], v[252:253], off
	global_load_dwordx4 v[172:175], v[252:253], off offset:256
	v_add_u32_e32 v252, 0xb0, v207
	v_add_u32_e32 v252, s51, v252
	v_ashrrev_i32_e32 v253, 31, v252
	v_lshlrev_b64 v[252:253], 11, v[252:253]
	v_lshl_add_u64 v[252:253], v[204:205], 0, v[252:253]
	global_load_dwordx4 v[208:211], v[252:253], off
	global_load_dwordx4 v[212:215], v[252:253], off offset:256
	ds_read_b32 v132, v206 offset:64
	v_lshlrev_b32_e32 v134, 16, v164
	v_and_b32_e32 v135, 0xffff0000, v164
	v_lshlrev_b32_e32 v136, 16, v165
	v_and_b32_e32 v137, 0xffff0000, v165
	s_waitcnt lgkmcnt(0)
	v_pk_mul_f32 v[118:119], v[118:119], v[132:133] op_sel_hi:[1,0]
	v_pk_mul_f32 v[116:117], v[116:117], v[132:133] op_sel_hi:[1,0]
	v_lshlrev_b32_e32 v138, 16, v166
	v_and_b32_e32 v139, 0xffff0000, v166
	v_lshlrev_b32_e32 v140, 16, v167
	v_and_b32_e32 v141, 0xffff0000, v167
	v_pk_fma_f32 v[118:119], v[126:127], v[118:119], v[136:137]
	v_pk_fma_f32 v[116:117], v[124:125], v[116:117], v[134:135]
	v_pk_mul_f32 v[114:115], v[114:115], v[132:133] op_sel_hi:[1,0]
	v_pk_mul_f32 v[112:113], v[112:113], v[132:133] op_sel_hi:[1,0]
	v_pk_fma_f32 v[134:135], v[122:123], v[114:115], v[140:141]
	v_pk_fma_f32 v[114:115], v[120:121], v[112:113], v[138:139]
	v_mul_f32_e32 v112, v117, v117
	v_mul_f32_e32 v113, v119, v119
	v_fmac_f32_e32 v112, v116, v116
	v_fmac_f32_e32 v113, v118, v118
	v_add_f32_e32 v112, v112, v113
	v_mul_f32_e32 v113, v115, v115
	v_mul_f32_e32 v129, v135, v135
	v_fmac_f32_e32 v113, v114, v114
	v_fmac_f32_e32 v129, v134, v134
	v_add_f32_e32 v113, v113, v129
	v_add_f32_e32 v129, v112, v113
	v_cvt_pk_bf16_f32 v112, v116, v117
	v_cvt_pk_bf16_f32 v113, v118, v119
	v_lshlrev_b32_e32 v116, 16, v160
	v_and_b32_e32 v117, 0xffff0000, v160
	v_lshlrev_b32_e32 v118, 16, v161
	v_and_b32_e32 v119, 0xffff0000, v161
	v_pk_mul_f32 v[102:103], v[102:103], v[132:133] op_sel_hi:[1,0]
	v_pk_mul_f32 v[100:101], v[100:101], v[132:133] op_sel_hi:[1,0]
	v_lshlrev_b32_e32 v136, 16, v162
	v_and_b32_e32 v137, 0xffff0000, v162
	v_pk_fma_f32 v[102:103], v[110:111], v[102:103], v[118:119]
	v_pk_fma_f32 v[100:101], v[108:109], v[100:101], v[116:117]
	v_pk_mul_f32 v[96:97], v[96:97], v[132:133] op_sel_hi:[1,0]
	v_lshlrev_b32_e32 v138, 16, v163
	v_and_b32_e32 v139, 0xffff0000, v163
	v_pk_mul_f32 v[98:99], v[98:99], v[132:133] op_sel_hi:[1,0]
	v_pk_fma_f32 v[118:119], v[104:105], v[96:97], v[136:137]
	v_mul_f32_e32 v96, v101, v101
	v_mul_f32_e32 v97, v103, v103
	v_pk_fma_f32 v[116:117], v[106:107], v[98:99], v[138:139]
	v_fmac_f32_e32 v96, v100, v100
	v_fmac_f32_e32 v97, v102, v102
	v_add_f32_e32 v96, v96, v97
	v_mul_f32_e32 v97, v119, v119
	v_mul_f32_e32 v98, v117, v117
	v_fmac_f32_e32 v97, v118, v118
	v_fmac_f32_e32 v98, v116, v116
	v_add_f32_e32 v97, v97, v98
	v_add_f32_e32 v96, v96, v97
	v_add_f32_e32 v96, v129, v96
	ds_bpermute_b32 v97, v229, v96
	v_add_u32_e32 v128, 16, v207
	v_add_u32_e32 v130, s51, v128
	v_ashrrev_i32_e32 v131, 31, v130
	v_lshlrev_b64 v[130:131], 11, v[130:131]
	s_waitcnt lgkmcnt(0)
	v_add_f32_e32 v96, v96, v97
	ds_bpermute_b32 v97, v230, v96
	v_lshl_add_u64 v[130:131], v[204:205], 0, v[130:131]
	v_cvt_pk_bf16_f32 v114, v114, v115
	v_cvt_pk_bf16_f32 v115, v134, v135
	global_store_dwordx4 v[130:131], v[112:115], off
	v_cvt_pk_bf16_f32 v98, v100, v101
	v_cvt_pk_bf16_f32 v99, v102, v103
	v_cvt_pk_bf16_f32 v100, v118, v119
	v_cvt_pk_bf16_f32 v101, v116, v117
	global_store_dwordx4 v[130:131], v[98:101], off offset:256
	s_and_saveexec_b64 s[12:13], s[10:11]
	s_cbranch_execz .LBB0_1283
	s_waitcnt lgkmcnt(0)
	v_add_f32_e32 v96, v96, v97
	v_lshl_add_u32 v97, v128, 4, s49
	ds_write_b32 v97, v96
.LBB0_1283:
	s_or_b64 exec, exec, s[12:13]
	ds_read_b32 v100, v206 offset:128
	v_lshlrev_b32_e32 v102, 16, v156
	v_and_b32_e32 v103, 0xffff0000, v156
	v_lshlrev_b32_e32 v112, 16, v157
	v_and_b32_e32 v113, 0xffff0000, v157
	s_waitcnt lgkmcnt(0)
	v_pk_mul_f32 v[94:95], v[94:95], v[100:101] op_sel_hi:[1,0]
	v_pk_mul_f32 v[92:93], v[92:93], v[100:101] op_sel_hi:[1,0]
	v_lshlrev_b32_e32 v114, 16, v158
	v_and_b32_e32 v115, 0xffff0000, v158
	v_lshlrev_b32_e32 v116, 16, v159
	v_and_b32_e32 v117, 0xffff0000, v159
	v_pk_fma_f32 v[94:95], v[126:127], v[94:95], v[112:113]
	v_pk_fma_f32 v[92:93], v[124:125], v[92:93], v[102:103]
	v_pk_mul_f32 v[90:91], v[90:91], v[100:101] op_sel_hi:[1,0]
	v_pk_mul_f32 v[88:89], v[88:89], v[100:101] op_sel_hi:[1,0]
	v_pk_fma_f32 v[102:103], v[122:123], v[90:91], v[116:117]
	v_pk_fma_f32 v[90:91], v[120:121], v[88:89], v[114:115]
	v_mul_f32_e32 v88, v93, v93
	v_mul_f32_e32 v89, v95, v95
	v_fmac_f32_e32 v88, v92, v92
	v_fmac_f32_e32 v89, v94, v94
	v_add_f32_e32 v88, v88, v89
	v_mul_f32_e32 v89, v91, v91
	v_mul_f32_e32 v97, v103, v103
	v_fmac_f32_e32 v89, v90, v90
	v_fmac_f32_e32 v97, v102, v102
	v_add_f32_e32 v89, v89, v97
	v_add_f32_e32 v97, v88, v89
	v_cvt_pk_bf16_f32 v88, v92, v93
	v_cvt_pk_bf16_f32 v89, v94, v95
	v_lshlrev_b32_e32 v92, 16, v152
	v_and_b32_e32 v93, 0xffff0000, v152
	v_lshlrev_b32_e32 v94, 16, v153
	v_and_b32_e32 v95, 0xffff0000, v153
	v_pk_mul_f32 v[86:87], v[86:87], v[100:101] op_sel_hi:[1,0]
	v_pk_mul_f32 v[84:85], v[84:85], v[100:101] op_sel_hi:[1,0]
	v_lshlrev_b32_e32 v112, 16, v154
	v_and_b32_e32 v113, 0xffff0000, v154
	v_pk_fma_f32 v[86:87], v[110:111], v[86:87], v[94:95]
	v_pk_fma_f32 v[84:85], v[108:109], v[84:85], v[92:93]
	v_pk_mul_f32 v[80:81], v[80:81], v[100:101] op_sel_hi:[1,0]
	v_lshlrev_b32_e32 v114, 16, v155
	v_and_b32_e32 v115, 0xffff0000, v155
	v_pk_mul_f32 v[82:83], v[82:83], v[100:101] op_sel_hi:[1,0]
	v_pk_fma_f32 v[94:95], v[104:105], v[80:81], v[112:113]
	v_mul_f32_e32 v80, v85, v85
	v_mul_f32_e32 v81, v87, v87
	v_pk_fma_f32 v[92:93], v[106:107], v[82:83], v[114:115]
	v_fmac_f32_e32 v80, v84, v84
	v_fmac_f32_e32 v81, v86, v86
	v_add_f32_e32 v80, v80, v81
	v_mul_f32_e32 v81, v95, v95
	v_mul_f32_e32 v82, v93, v93
	v_fmac_f32_e32 v81, v94, v94
	v_fmac_f32_e32 v82, v92, v92
	v_add_f32_e32 v81, v81, v82
	v_add_f32_e32 v80, v80, v81
	v_add_f32_e32 v80, v97, v80
	ds_bpermute_b32 v81, v229, v80
	v_add_u32_e32 v96, 32, v207
	v_add_u32_e32 v98, s51, v96
	v_ashrrev_i32_e32 v99, 31, v98
	v_lshlrev_b64 v[98:99], 11, v[98:99]
	s_waitcnt lgkmcnt(0)
	v_add_f32_e32 v80, v80, v81
	ds_bpermute_b32 v81, v230, v80
	v_lshl_add_u64 v[98:99], v[204:205], 0, v[98:99]
	v_cvt_pk_bf16_f32 v90, v90, v91
	v_cvt_pk_bf16_f32 v91, v102, v103
	global_store_dwordx4 v[98:99], v[88:91], off
	v_cvt_pk_bf16_f32 v82, v84, v85
	v_cvt_pk_bf16_f32 v83, v86, v87
	v_cvt_pk_bf16_f32 v84, v94, v95
	v_cvt_pk_bf16_f32 v85, v92, v93
	global_store_dwordx4 v[98:99], v[82:85], off offset:256
	s_and_saveexec_b64 s[12:13], s[10:11]
	s_cbranch_execz .LBB0_1285
	s_waitcnt lgkmcnt(0)
	v_add_f32_e32 v80, v80, v81
	v_lshl_add_u32 v81, v96, 4, s49
	ds_write_b32 v81, v80
.LBB0_1285:
	s_or_b64 exec, exec, s[12:13]
	ds_read_b32 v84, v206 offset:192
	v_lshlrev_b32_e32 v86, 16, v148
	v_and_b32_e32 v87, 0xffff0000, v148
	v_lshlrev_b32_e32 v88, 16, v149
	v_and_b32_e32 v89, 0xffff0000, v149
	s_waitcnt lgkmcnt(0)
	v_pk_mul_f32 v[78:79], v[78:79], v[84:85] op_sel_hi:[1,0]
	v_pk_mul_f32 v[76:77], v[76:77], v[84:85] op_sel_hi:[1,0]
	v_lshlrev_b32_e32 v90, 16, v150
	v_and_b32_e32 v91, 0xffff0000, v150
	v_lshlrev_b32_e32 v92, 16, v151
	v_and_b32_e32 v93, 0xffff0000, v151
	v_pk_fma_f32 v[78:79], v[126:127], v[78:79], v[88:89]
	v_pk_fma_f32 v[76:77], v[124:125], v[76:77], v[86:87]
	v_pk_mul_f32 v[74:75], v[74:75], v[84:85] op_sel_hi:[1,0]
	v_pk_mul_f32 v[72:73], v[72:73], v[84:85] op_sel_hi:[1,0]
	v_pk_fma_f32 v[86:87], v[122:123], v[74:75], v[92:93]
	v_pk_fma_f32 v[74:75], v[120:121], v[72:73], v[90:91]
	v_mul_f32_e32 v72, v77, v77
	v_mul_f32_e32 v73, v79, v79
	v_fmac_f32_e32 v72, v76, v76
	v_fmac_f32_e32 v73, v78, v78
	v_add_f32_e32 v72, v72, v73
	v_mul_f32_e32 v73, v75, v75
	v_mul_f32_e32 v81, v87, v87
	v_fmac_f32_e32 v73, v74, v74
	v_fmac_f32_e32 v81, v86, v86
	v_add_f32_e32 v73, v73, v81
	v_add_f32_e32 v81, v72, v73
	v_cvt_pk_bf16_f32 v72, v76, v77
	v_cvt_pk_bf16_f32 v73, v78, v79
	v_lshlrev_b32_e32 v76, 16, v144
	v_and_b32_e32 v77, 0xffff0000, v144
	v_lshlrev_b32_e32 v78, 16, v145
	v_and_b32_e32 v79, 0xffff0000, v145
	v_pk_mul_f32 v[70:71], v[70:71], v[84:85] op_sel_hi:[1,0]
	v_pk_mul_f32 v[68:69], v[68:69], v[84:85] op_sel_hi:[1,0]
	v_lshlrev_b32_e32 v88, 16, v146
	v_and_b32_e32 v89, 0xffff0000, v146
	v_pk_fma_f32 v[70:71], v[110:111], v[70:71], v[78:79]
	v_pk_fma_f32 v[68:69], v[108:109], v[68:69], v[76:77]
	v_pk_mul_f32 v[64:65], v[64:65], v[84:85] op_sel_hi:[1,0]
	v_lshlrev_b32_e32 v90, 16, v147
	v_and_b32_e32 v91, 0xffff0000, v147
	v_pk_mul_f32 v[66:67], v[66:67], v[84:85] op_sel_hi:[1,0]
	v_pk_fma_f32 v[78:79], v[104:105], v[64:65], v[88:89]
	v_mul_f32_e32 v64, v69, v69
	v_mul_f32_e32 v65, v71, v71
	v_pk_fma_f32 v[76:77], v[106:107], v[66:67], v[90:91]
	v_fmac_f32_e32 v64, v68, v68
	v_fmac_f32_e32 v65, v70, v70
	v_add_f32_e32 v64, v64, v65
	v_mul_f32_e32 v65, v79, v79
	v_mul_f32_e32 v66, v77, v77
	v_fmac_f32_e32 v65, v78, v78
	v_fmac_f32_e32 v66, v76, v76
	v_add_f32_e32 v65, v65, v66
	v_add_f32_e32 v64, v64, v65
	v_add_f32_e32 v64, v81, v64
	ds_bpermute_b32 v65, v229, v64
	v_add_u32_e32 v80, 48, v207
	v_add_u32_e32 v82, s51, v80
	v_ashrrev_i32_e32 v83, 31, v82
	v_lshlrev_b64 v[82:83], 11, v[82:83]
	s_waitcnt lgkmcnt(0)
	v_add_f32_e32 v64, v64, v65
	ds_bpermute_b32 v65, v230, v64
	v_lshl_add_u64 v[82:83], v[204:205], 0, v[82:83]
	v_cvt_pk_bf16_f32 v74, v74, v75
	v_cvt_pk_bf16_f32 v75, v86, v87
	global_store_dwordx4 v[82:83], v[72:75], off
	v_cvt_pk_bf16_f32 v66, v68, v69
	v_cvt_pk_bf16_f32 v67, v70, v71
	v_cvt_pk_bf16_f32 v68, v78, v79
	v_cvt_pk_bf16_f32 v69, v76, v77
	global_store_dwordx4 v[82:83], v[66:69], off offset:256
	s_and_saveexec_b64 s[12:13], s[10:11]
	s_cbranch_execz .LBB0_1287
	s_waitcnt lgkmcnt(0)
	v_add_f32_e32 v64, v64, v65
	v_lshl_add_u32 v65, v80, 4, s49
	ds_write_b32 v65, v64
.LBB0_1287:
	s_or_b64 exec, exec, s[12:13]
	v_add_u32_e32 v64, 0x80, v207
	v_add_u32_e32 v66, s51, v64
	v_ashrrev_i32_e32 v67, 31, v66
	v_lshlrev_b64 v[66:67], 11, v[66:67]
	v_lshl_add_u64 v[70:71], v[204:205], 0, v[66:67]
	ds_read_b32 v72, v206 offset:512
	s_waitcnt lgkmcnt(0)
	v_pk_mul_f32 v[62:63], v[62:63], v[72:73] op_sel_hi:[1,0]
	v_pk_mul_f32 v[60:61], v[60:61], v[72:73] op_sel_hi:[1,0]
	v_pk_mul_f32 v[58:59], v[58:59], v[72:73] op_sel_hi:[1,0]
	v_pk_mul_f32 v[56:57], v[56:57], v[72:73] op_sel_hi:[1,0]
	v_pk_mul_f32 v[54:55], v[54:55], v[72:73] op_sel_hi:[1,0]
	v_pk_mul_f32 v[52:53], v[52:53], v[72:73] op_sel_hi:[1,0]
	v_pk_mul_f32 v[50:51], v[50:51], v[72:73] op_sel_hi:[1,0]
	v_pk_mul_f32 v[48:49], v[48:49], v[72:73] op_sel_hi:[1,0]
	v_lshlrev_b32_e32 v74, 16, v236
	v_and_b32_e32 v75, 0xffff0000, v236
	v_lshlrev_b32_e32 v66, 16, v237
	v_and_b32_e32 v67, 0xffff0000, v237
	v_lshlrev_b32_e32 v76, 16, v238
	v_and_b32_e32 v77, 0xffff0000, v238
	v_lshlrev_b32_e32 v68, 16, v239
	v_and_b32_e32 v69, 0xffff0000, v239
	v_pk_fma_f32 v[66:67], v[126:127], v[62:63], v[66:67]
	v_pk_fma_f32 v[74:75], v[124:125], v[60:61], v[74:75]
	v_pk_fma_f32 v[68:69], v[122:123], v[58:59], v[68:69]
	v_pk_fma_f32 v[76:77], v[120:121], v[56:57], v[76:77]
	v_cvt_pk_bf16_f32 v56, v74, v75
	v_cvt_pk_bf16_f32 v57, v66, v67
	v_mul_f32_e32 v65, v75, v75
	v_cvt_pk_bf16_f32 v58, v76, v77
	v_cvt_pk_bf16_f32 v59, v68, v69
	v_mul_f32_e32 v67, v67, v67
	v_mul_f32_e32 v72, v77, v77
	v_mul_f32_e32 v69, v69, v69
	v_fmac_f32_e32 v65, v74, v74
	v_fmac_f32_e32 v67, v66, v66
	v_fmac_f32_e32 v72, v76, v76
	v_fmac_f32_e32 v69, v68, v68
	v_add_f32_e32 v65, v65, v67
	v_add_f32_e32 v66, v72, v69
	v_add_f32_e32 v65, v65, v66
	global_store_dwordx4 v[70:71], v[56:59], off
	v_lshlrev_b32_e32 v66, 16, v240
	v_and_b32_e32 v67, 0xffff0000, v240
	v_lshlrev_b32_e32 v60, 16, v241
	v_and_b32_e32 v61, 0xffff0000, v241
	v_lshlrev_b32_e32 v68, 16, v242
	v_and_b32_e32 v69, 0xffff0000, v242
	v_lshlrev_b32_e32 v62, 16, v243
	v_and_b32_e32 v63, 0xffff0000, v243
	v_pk_fma_f32 v[54:55], v[110:111], v[54:55], v[60:61]
	v_pk_fma_f32 v[52:53], v[108:109], v[52:53], v[66:67]
	v_pk_fma_f32 v[60:61], v[106:107], v[50:51], v[62:63]
	v_pk_fma_f32 v[62:63], v[104:105], v[48:49], v[68:69]
	v_mul_f32_e32 v48, v53, v53
	v_mul_f32_e32 v49, v55, v55
	v_mul_f32_e32 v50, v63, v63
	v_mul_f32_e32 v51, v61, v61
	v_fmac_f32_e32 v48, v52, v52
	v_fmac_f32_e32 v49, v54, v54
	v_fmac_f32_e32 v50, v62, v62
	v_fmac_f32_e32 v51, v60, v60
	v_add_f32_e32 v48, v48, v49
	v_add_f32_e32 v49, v50, v51
	v_add_f32_e32 v48, v48, v49
	v_add_f32_e32 v48, v65, v48
	ds_bpermute_b32 v49, v229, v48
	v_cvt_pk_bf16_f32 v50, v52, v53
	v_cvt_pk_bf16_f32 v51, v54, v55
	v_cvt_pk_bf16_f32 v52, v62, v63
	v_cvt_pk_bf16_f32 v53, v60, v61
	s_waitcnt lgkmcnt(0)
	v_add_f32_e32 v48, v48, v49
	ds_bpermute_b32 v49, v230, v48
	global_store_dwordx4 v[70:71], v[50:53], off offset:256
	s_and_saveexec_b64 s[12:13], s[10:11]
	s_cbranch_execz .LBB0_1289
	s_waitcnt lgkmcnt(0)
	v_add_f32_e32 v48, v48, v49
	v_lshl_add_u32 v49, v64, 4, s49
	ds_write_b32 v49, v48
.LBB0_1289:
	s_or_b64 exec, exec, s[12:13]
	v_add_u32_e32 v48, 0x90, v207
	v_add_u32_e32 v50, s51, v48
	v_ashrrev_i32_e32 v51, 31, v50
	v_lshlrev_b64 v[50:51], 11, v[50:51]
	v_lshl_add_u64 v[54:55], v[204:205], 0, v[50:51]
	ds_read_b32 v56, v206 offset:576
	s_waitcnt lgkmcnt(0)
	v_pk_mul_f32 v[46:47], v[46:47], v[56:57] op_sel_hi:[1,0]
	v_pk_mul_f32 v[44:45], v[44:45], v[56:57] op_sel_hi:[1,0]
	v_pk_mul_f32 v[42:43], v[42:43], v[56:57] op_sel_hi:[1,0]
	v_pk_mul_f32 v[40:41], v[40:41], v[56:57] op_sel_hi:[1,0]
	v_pk_mul_f32 v[38:39], v[38:39], v[56:57] op_sel_hi:[1,0]
	v_pk_mul_f32 v[36:37], v[36:37], v[56:57] op_sel_hi:[1,0]
	v_pk_mul_f32 v[34:35], v[34:35], v[56:57] op_sel_hi:[1,0]
	v_pk_mul_f32 v[32:33], v[32:33], v[56:57] op_sel_hi:[1,0]
	v_lshlrev_b32_e32 v58, 16, v244
	v_and_b32_e32 v59, 0xffff0000, v244
	v_lshlrev_b32_e32 v50, 16, v245
	v_and_b32_e32 v51, 0xffff0000, v245
	v_lshlrev_b32_e32 v60, 16, v246
	v_and_b32_e32 v61, 0xffff0000, v246
	v_lshlrev_b32_e32 v52, 16, v247
	v_and_b32_e32 v53, 0xffff0000, v247
	v_pk_fma_f32 v[50:51], v[126:127], v[46:47], v[50:51]
	v_pk_fma_f32 v[58:59], v[124:125], v[44:45], v[58:59]
	v_pk_fma_f32 v[52:53], v[122:123], v[42:43], v[52:53]
	v_pk_fma_f32 v[60:61], v[120:121], v[40:41], v[60:61]
	v_cvt_pk_bf16_f32 v40, v58, v59
	v_cvt_pk_bf16_f32 v41, v50, v51
	v_mul_f32_e32 v49, v59, v59
	v_cvt_pk_bf16_f32 v42, v60, v61
	v_cvt_pk_bf16_f32 v43, v52, v53
	v_mul_f32_e32 v51, v51, v51
	v_mul_f32_e32 v56, v61, v61
	v_mul_f32_e32 v53, v53, v53
	v_fmac_f32_e32 v49, v58, v58
	v_fmac_f32_e32 v51, v50, v50
	v_fmac_f32_e32 v56, v60, v60
	v_fmac_f32_e32 v53, v52, v52
	v_add_f32_e32 v49, v49, v51
	v_add_f32_e32 v50, v56, v53
	v_add_f32_e32 v49, v49, v50
	global_store_dwordx4 v[54:55], v[40:43], off
	v_lshlrev_b32_e32 v50, 16, v248
	v_and_b32_e32 v51, 0xffff0000, v248
	v_lshlrev_b32_e32 v44, 16, v249
	v_and_b32_e32 v45, 0xffff0000, v249
	v_lshlrev_b32_e32 v52, 16, v250
	v_and_b32_e32 v53, 0xffff0000, v250
	v_lshlrev_b32_e32 v46, 16, v251
	v_and_b32_e32 v47, 0xffff0000, v251
	v_pk_fma_f32 v[38:39], v[110:111], v[38:39], v[44:45]
	v_pk_fma_f32 v[36:37], v[108:109], v[36:37], v[50:51]
	v_pk_fma_f32 v[44:45], v[106:107], v[34:35], v[46:47]
	v_pk_fma_f32 v[46:47], v[104:105], v[32:33], v[52:53]
	v_mul_f32_e32 v32, v37, v37
	v_mul_f32_e32 v33, v39, v39
	v_mul_f32_e32 v34, v47, v47
	v_mul_f32_e32 v35, v45, v45
	v_fmac_f32_e32 v32, v36, v36
	v_fmac_f32_e32 v33, v38, v38
	v_fmac_f32_e32 v34, v46, v46
	v_fmac_f32_e32 v35, v44, v44
	v_add_f32_e32 v32, v32, v33
	v_add_f32_e32 v33, v34, v35
	v_add_f32_e32 v32, v32, v33
	v_add_f32_e32 v32, v49, v32
	ds_bpermute_b32 v33, v229, v32
	v_cvt_pk_bf16_f32 v34, v36, v37
	v_cvt_pk_bf16_f32 v35, v38, v39
	v_cvt_pk_bf16_f32 v36, v46, v47
	v_cvt_pk_bf16_f32 v37, v44, v45
	s_waitcnt lgkmcnt(0)
	v_add_f32_e32 v32, v32, v33
	ds_bpermute_b32 v33, v230, v32
	global_store_dwordx4 v[54:55], v[34:37], off offset:256
	s_and_saveexec_b64 s[12:13], s[10:11]
	s_cbranch_execz .LBB0_1291
	s_waitcnt lgkmcnt(0)
	v_add_f32_e32 v32, v32, v33
	v_lshl_add_u32 v33, v48, 4, s49
	ds_write_b32 v33, v32
.LBB0_1291:
	s_or_b64 exec, exec, s[12:13]
	v_add_u32_e32 v32, 0xa0, v207
	v_add_u32_e32 v34, s51, v32
	v_ashrrev_i32_e32 v35, 31, v34
	v_lshlrev_b64 v[34:35], 11, v[34:35]
	v_lshl_add_u64 v[38:39], v[204:205], 0, v[34:35]
	ds_read_b32 v40, v206 offset:640
	s_waitcnt lgkmcnt(0)
	v_pk_mul_f32 v[30:31], v[30:31], v[40:41] op_sel_hi:[1,0]
	v_pk_mul_f32 v[28:29], v[28:29], v[40:41] op_sel_hi:[1,0]
	v_pk_mul_f32 v[26:27], v[26:27], v[40:41] op_sel_hi:[1,0]
	v_pk_mul_f32 v[24:25], v[24:25], v[40:41] op_sel_hi:[1,0]
	v_pk_mul_f32 v[22:23], v[22:23], v[40:41] op_sel_hi:[1,0]
	v_pk_mul_f32 v[20:21], v[20:21], v[40:41] op_sel_hi:[1,0]
	v_pk_mul_f32 v[18:19], v[18:19], v[40:41] op_sel_hi:[1,0]
	v_pk_mul_f32 v[16:17], v[16:17], v[40:41] op_sel_hi:[1,0]
	s_waitcnt vmcnt(13)
	v_lshlrev_b32_e32 v42, 16, v168
	v_and_b32_e32 v43, 0xffff0000, v168
	v_lshlrev_b32_e32 v34, 16, v169
	v_and_b32_e32 v35, 0xffff0000, v169
	v_lshlrev_b32_e32 v44, 16, v170
	v_and_b32_e32 v45, 0xffff0000, v170
	v_lshlrev_b32_e32 v36, 16, v171
	v_and_b32_e32 v37, 0xffff0000, v171
	v_pk_fma_f32 v[34:35], v[126:127], v[30:31], v[34:35]
	v_pk_fma_f32 v[42:43], v[124:125], v[28:29], v[42:43]
	v_pk_fma_f32 v[36:37], v[122:123], v[26:27], v[36:37]
	v_pk_fma_f32 v[44:45], v[120:121], v[24:25], v[44:45]
	v_cvt_pk_bf16_f32 v24, v42, v43
	v_cvt_pk_bf16_f32 v25, v34, v35
	v_mul_f32_e32 v33, v43, v43
	v_cvt_pk_bf16_f32 v26, v44, v45
	v_cvt_pk_bf16_f32 v27, v36, v37
	v_mul_f32_e32 v35, v35, v35
	v_mul_f32_e32 v40, v45, v45
	v_mul_f32_e32 v37, v37, v37
	v_fmac_f32_e32 v33, v42, v42
	v_fmac_f32_e32 v35, v34, v34
	v_fmac_f32_e32 v40, v44, v44
	v_fmac_f32_e32 v37, v36, v36
	v_add_f32_e32 v33, v33, v35
	v_add_f32_e32 v34, v40, v37
	v_add_f32_e32 v33, v33, v34
	global_store_dwordx4 v[38:39], v[24:27], off
	s_waitcnt vmcnt(13)
	v_lshlrev_b32_e32 v34, 16, v172
	v_and_b32_e32 v35, 0xffff0000, v172
	v_lshlrev_b32_e32 v28, 16, v173
	v_and_b32_e32 v29, 0xffff0000, v173
	v_lshlrev_b32_e32 v36, 16, v174
	v_and_b32_e32 v37, 0xffff0000, v174
	v_lshlrev_b32_e32 v30, 16, v175
	v_and_b32_e32 v31, 0xffff0000, v175
	v_pk_fma_f32 v[22:23], v[110:111], v[22:23], v[28:29]
	v_pk_fma_f32 v[20:21], v[108:109], v[20:21], v[34:35]
	v_pk_fma_f32 v[28:29], v[106:107], v[18:19], v[30:31]
	v_pk_fma_f32 v[30:31], v[104:105], v[16:17], v[36:37]
	v_mul_f32_e32 v16, v21, v21
	v_mul_f32_e32 v17, v23, v23
	v_mul_f32_e32 v18, v31, v31
	v_mul_f32_e32 v19, v29, v29
	v_fmac_f32_e32 v16, v20, v20
	v_fmac_f32_e32 v17, v22, v22
	v_fmac_f32_e32 v18, v30, v30
	v_fmac_f32_e32 v19, v28, v28
	v_add_f32_e32 v16, v16, v17
	v_add_f32_e32 v17, v18, v19
	v_add_f32_e32 v16, v16, v17
	v_add_f32_e32 v16, v33, v16
	ds_bpermute_b32 v17, v229, v16
	v_cvt_pk_bf16_f32 v18, v20, v21
	v_cvt_pk_bf16_f32 v19, v22, v23
	v_cvt_pk_bf16_f32 v20, v30, v31
	v_cvt_pk_bf16_f32 v21, v28, v29
	s_waitcnt lgkmcnt(0)
	v_add_f32_e32 v16, v16, v17
	ds_bpermute_b32 v17, v230, v16
	global_store_dwordx4 v[38:39], v[18:21], off offset:256
	s_and_saveexec_b64 s[12:13], s[10:11]
	s_cbranch_execz .LBB0_1293
	s_waitcnt lgkmcnt(0)
	v_add_f32_e32 v16, v16, v17
	v_lshl_add_u32 v17, v32, 4, s49
	ds_write_b32 v17, v16
.LBB0_1293:
	s_or_b64 exec, exec, s[12:13]
	v_add_u32_e32 v16, 0xb0, v207
	v_add_u32_e32 v18, s51, v16
	v_ashrrev_i32_e32 v19, 31, v18
	v_lshlrev_b64 v[18:19], 11, v[18:19]
	v_lshl_add_u64 v[22:23], v[204:205], 0, v[18:19]
	ds_read_b32 v24, v206 offset:704
	s_waitcnt lgkmcnt(0)
	v_pk_mul_f32 v[14:15], v[14:15], v[24:25] op_sel_hi:[1,0]
	v_pk_mul_f32 v[12:13], v[12:13], v[24:25] op_sel_hi:[1,0]
	v_pk_mul_f32 v[10:11], v[10:11], v[24:25] op_sel_hi:[1,0]
	v_pk_mul_f32 v[8:9], v[8:9], v[24:25] op_sel_hi:[1,0]
	v_pk_mul_f32 v[6:7], v[6:7], v[24:25] op_sel_hi:[1,0]
	v_pk_mul_f32 v[4:5], v[4:5], v[24:25] op_sel_hi:[1,0]
	v_pk_mul_f32 v[2:3], v[2:3], v[24:25] op_sel_hi:[1,0]
	v_pk_mul_f32 v[0:1], v[0:1], v[24:25] op_sel_hi:[1,0]
	s_waitcnt vmcnt(13)
	v_lshlrev_b32_e32 v26, 16, v208
	v_and_b32_e32 v27, 0xffff0000, v208
	v_lshlrev_b32_e32 v18, 16, v209
	v_and_b32_e32 v19, 0xffff0000, v209
	v_lshlrev_b32_e32 v28, 16, v210
	v_and_b32_e32 v29, 0xffff0000, v210
	v_lshlrev_b32_e32 v20, 16, v211
	v_and_b32_e32 v21, 0xffff0000, v211
	v_pk_fma_f32 v[18:19], v[126:127], v[14:15], v[18:19]
	v_pk_fma_f32 v[26:27], v[124:125], v[12:13], v[26:27]
	v_pk_fma_f32 v[20:21], v[122:123], v[10:11], v[20:21]
	v_pk_fma_f32 v[28:29], v[120:121], v[8:9], v[28:29]
	v_cvt_pk_bf16_f32 v8, v26, v27
	v_cvt_pk_bf16_f32 v9, v18, v19
	v_mul_f32_e32 v17, v27, v27
	v_cvt_pk_bf16_f32 v10, v28, v29
	v_cvt_pk_bf16_f32 v11, v20, v21
	v_mul_f32_e32 v19, v19, v19
	v_mul_f32_e32 v24, v29, v29
	v_mul_f32_e32 v21, v21, v21
	v_fmac_f32_e32 v17, v26, v26
	v_fmac_f32_e32 v19, v18, v18
	v_fmac_f32_e32 v24, v28, v28
	v_fmac_f32_e32 v21, v20, v20
	v_add_f32_e32 v17, v17, v19
	v_add_f32_e32 v18, v24, v21
	v_add_f32_e32 v17, v17, v18
	global_store_dwordx4 v[22:23], v[8:11], off
	s_waitcnt vmcnt(13)
	v_lshlrev_b32_e32 v18, 16, v212
	v_and_b32_e32 v19, 0xffff0000, v212
	v_lshlrev_b32_e32 v12, 16, v213
	v_and_b32_e32 v13, 0xffff0000, v213
	v_lshlrev_b32_e32 v20, 16, v214
	v_and_b32_e32 v21, 0xffff0000, v214
	v_lshlrev_b32_e32 v14, 16, v215
	v_and_b32_e32 v15, 0xffff0000, v215
	v_pk_fma_f32 v[6:7], v[110:111], v[6:7], v[12:13]
	v_pk_fma_f32 v[4:5], v[108:109], v[4:5], v[18:19]
	v_pk_fma_f32 v[12:13], v[106:107], v[2:3], v[14:15]
	v_pk_fma_f32 v[14:15], v[104:105], v[0:1], v[20:21]
	v_mul_f32_e32 v0, v5, v5
	v_mul_f32_e32 v1, v7, v7
	v_mul_f32_e32 v2, v15, v15
	v_mul_f32_e32 v3, v13, v13
	v_fmac_f32_e32 v0, v4, v4
	v_fmac_f32_e32 v1, v6, v6
	v_fmac_f32_e32 v2, v14, v14
	v_fmac_f32_e32 v3, v12, v12
	v_add_f32_e32 v0, v0, v1
	v_add_f32_e32 v1, v2, v3
	v_add_f32_e32 v0, v0, v1
	v_add_f32_e32 v0, v17, v0
	ds_bpermute_b32 v1, v229, v0
	v_cvt_pk_bf16_f32 v2, v4, v5
	v_cvt_pk_bf16_f32 v3, v6, v7
	v_cvt_pk_bf16_f32 v4, v14, v15
	v_cvt_pk_bf16_f32 v5, v12, v13
	s_waitcnt lgkmcnt(0)
	v_add_f32_e32 v0, v0, v1
	ds_bpermute_b32 v1, v230, v0
	global_store_dwordx4 v[22:23], v[2:5], off offset:256
	s_and_saveexec_b64 s[12:13], s[10:11]
	s_cbranch_execz .LBB0_1295
	s_waitcnt lgkmcnt(0)
	v_add_f32_e32 v0, v0, v1
	v_lshl_add_u32 v1, v16, 4, s49
	ds_write_b32 v1, v0
